# speedup vs baseline: 1.0277x; 1.0277x over previous
; __device__ __forceinline__ void transpose_tile(const float* __restrict__ src, int ldsrc, int k0, int n0, bool is_win, bf16_t* __restrict__ dst, int ldd, ...
;   const int c = (tid & 63) * 4, kb = tid >> 6;
;   int col = n0 + c; bool valid = true;
;   if (is_win) { if (col >= 1536) col -= 192; else if (col >= 1344) valid = false; }
; __global__ __launch_bounds__(512, 2) void mega(Params p) {
;   extern __shared__ __attribute__((aligned(16))) char shm[];
;   cg::grid_group grid = cg::this_grid();
;   char* ws = p.ws;
;   phase0(p, shm);
_Z4mega6Params:
	s_load_dwordx16 s[4:19], s[0:1], 0x0
	s_load_dwordx4 s[96:99], s[0:1], 0xa0
	s_load_dword s72, s[0:1], 0xb0
	s_mov_b32 s68, s2
	s_add_u32 s2, s0, 0xb0
	s_addc_u32 s3, s1, 0
	s_waitcnt lgkmcnt(0)
	v_writelane_b32 v250, s4, 0
	s_cmpk_gt_i32 s68, 0x43f
	v_and_b32_e32 v160, 0x3ff, v0
	v_writelane_b32 v250, s5, 1
	v_writelane_b32 v250, s6, 2
	v_writelane_b32 v250, s7, 3
	v_writelane_b32 v250, s8, 4
	v_writelane_b32 v250, s9, 5
	v_writelane_b32 v250, s10, 6
	v_writelane_b32 v250, s11, 7
	v_writelane_b32 v250, s12, 8
	v_writelane_b32 v250, s13, 9
	v_writelane_b32 v250, s14, 10
	v_writelane_b32 v250, s15, 11
	v_writelane_b32 v250, s16, 12
	v_writelane_b32 v250, s17, 13
	v_writelane_b32 v250, s18, 14
	v_writelane_b32 v250, s19, 15
	s_load_dwordx8 s[4:11], s[0:1], 0x80
	s_waitcnt lgkmcnt(0)
	v_writelane_b32 v250, s4, 16
	s_nop 1
	v_writelane_b32 v250, s5, 17
	v_writelane_b32 v250, s6, 18
	v_writelane_b32 v250, s7, 19
	v_writelane_b32 v250, s8, 20
	v_writelane_b32 v250, s9, 21
	v_writelane_b32 v250, s10, 22
	v_writelane_b32 v250, s11, 23
	s_cbranch_scc1 .LBB0_19
	v_lshlrev_b32_e32 v1, 2, v160
	v_lshlrev_b32_e32 v2, 5, v160
	v_and_b32_e32 v1, 0xfc, v1
	v_lshrrev_b32_e32 v3, 6, v160
	v_lshrrev_b32_e32 v40, 1, v160
	v_and_b32_e32 v2, 32, v2
	s_mul_i32 s4, s68, 0x85000
	v_lshl_add_u32 v4, v1, 2, 0
	v_mul_u32_u24_e32 v5, 0x404, v3
	v_lshl_add_u32 v6, v40, 2, 0
	v_mul_u32_u24_e32 v7, 0x404, v2
	s_movk_i32 s5, 0x2140
	v_mov_b32_e32 v8, s4
	v_mov_b32_e32 v35, 0
	s_lshl_b32 s8, s68, 6
	s_lshl_b32 s9, s72, 6
	v_mad_u32_u24 v41, v3, s5, v8
	s_mul_i32 s10, s72, 0x85000
	s_movk_i32 s11, 0x5ff
	s_movk_i32 s12, 0xff40
	v_add_u32_e32 v42, v4, v5
	v_lshlrev_b32_e32 v34, 1, v2
	v_add_u32_e32 v43, v6, v7
	s_mov_b32 s13, s68
	s_branch .LBB0_3

; #define SBAR() __builtin_amdgcn_sched_barrier(0)
; __device__ __forceinline__ void finishSM(f32x16& p0, f32x16& p1, float alpha, float& l_reg, bf16x8& pa0, bf16x8& pa1, bf16x8& pa2, bf16x8& pa3) {
; #pragma unroll
;   for (int r = 0; r < 16; ++r) p1[r] = __builtin_amdgcn_exp2f(p1[r]);
;   float ps = 0;
; #pragma unroll
;   for (int r = 0; r < 16; ++r) ps += p0[r];
; #pragma unroll
;   for (int r = 0; r < 16; ++r) ps += p1[r];
;   { auto rr = __builtin_amdgcn_permlane32_swap(__float_as_uint(ps), __float_as_uint(ps), false, false);
;     ps = __uint_as_float(rr[0]) + __uint_as_float(rr[1]); }
;   l_reg = l_reg * alpha + ps;
;     ...
;   PK4(p0, 0, pa0); PK4(p0, 8, pa1); PK4(p1, 0, pa2); PK4(p1, 8, pa3);
; template <int D0> __device__ __forceinline__ void pv_one_t(f32x16& od, int vb, bf16x8 pa0, bf16x8 pa1, bf16x8 pa2, bf16x8 pa3) {
;   const s16x4 l0 = tr_read<v_rd_off(D0, 0, 0)>(vb), h0 = tr_read<v_rd_off(D0, 0, 1)>(vb), l1 = tr_read<v_rd_off(D0, 1, 0)>(vb), h1 = tr_read<v_rd_off(D0, 1, 1)>(vb);
;   const s16x4 l2 = tr_read<v_rd_off(D0, 2, 0)>(vb), h2 = tr_read<v_rd_off(D0, 2, 1)>(vb), l3 = tr_read<v_rd_off(D0, 3, 0)>(vb), h3 = tr_read<v_rd_off(D0, 3, 1)>(vb);
;   asm volatile("s_waitcnt lgkmcnt(0)" ::: "memory"); SBAR();
;     ...
;   od = __builtin_amdgcn_mfma_f32_32x32x16_bf16(PK(l0, h0), pa0, od, 0, 0, 0);
;   od = __builtin_amdgcn_mfma_f32_32x32x16_bf16(PK(l1, h1), pa1, od, 0, 0, 0);
;   od = __builtin_amdgcn_mfma_f32_32x32x16_bf16(PK(l2, h2), pa2, od, 0, 0, 0);
;   od = __builtin_amdgcn_mfma_f32_32x32x16_bf16(PK(l3, h3), pa3, od, 0, 0, 0);
.LBB0_113:
	v_cndmask_b32_e64 v97, v97, v197, s[4:5]
	v_mul_f32_e32 v97, 0xbdd53b94, v97
	v_fmamk_f32 v80, v80, 0x3dd53b94, v97
	v_fmamk_f32 v81, v81, 0x3dd53b94, v97
	v_exp_f32_e32 v80, v80
	v_fmamk_f32 v82, v82, 0x3dd53b94, v97
	v_exp_f32_e32 v81, v81
	v_fmamk_f32 v83, v83, 0x3dd53b94, v97
	v_exp_f32_e32 v82, v82
	v_fmamk_f32 v84, v84, 0x3dd53b94, v97
	v_exp_f32_e32 v83, v83
	v_fmamk_f32 v65, v65, 0x3dd53b94, v97
	v_fmamk_f32 v85, v85, 0x3dd53b94, v97
	v_exp_f32_e32 v84, v84
	v_exp_f32_e32 v99, v65
	v_add_f32_e32 v65, 0, v80
	v_fmamk_f32 v86, v86, 0x3dd53b94, v97
	v_exp_f32_e32 v85, v85
	v_add_f32_e32 v65, v81, v65
	v_fmamk_f32 v87, v87, 0x3dd53b94, v97
	v_exp_f32_e32 v86, v86
	v_add_f32_e32 v65, v82, v65
	v_fmamk_f32 v88, v88, 0x3dd53b94, v97
	v_exp_f32_e32 v87, v87
	v_add_f32_e32 v65, v83, v65
	v_fmamk_f32 v89, v89, 0x3dd53b94, v97
	v_exp_f32_e32 v88, v88
	v_add_f32_e32 v65, v84, v65
	v_fmamk_f32 v90, v90, 0x3dd53b94, v97
	v_exp_f32_e32 v89, v89
	v_add_f32_e32 v65, v85, v65
	v_fmamk_f32 v91, v91, 0x3dd53b94, v97
	v_exp_f32_e32 v90, v90
	v_add_f32_e32 v65, v86, v65
	v_fmamk_f32 v92, v92, 0x3dd53b94, v97
	v_exp_f32_e32 v91, v91
	v_add_f32_e32 v65, v87, v65
	v_fmamk_f32 v93, v93, 0x3dd53b94, v97
	v_exp_f32_e32 v92, v92
	v_add_f32_e32 v65, v88, v65
	v_fmamk_f32 v94, v94, 0x3dd53b94, v97
	v_exp_f32_e32 v93, v93
	v_add_f32_e32 v65, v89, v65
	v_fmamk_f32 v95, v95, 0x3dd53b94, v97
	v_exp_f32_e32 v94, v94
	v_add_f32_e32 v65, v90, v65
	v_exp_f32_e32 v95, v95
	v_fmamk_f32 v79, v79, 0x3dd53b94, v97
	v_fmamk_f32 v78, v78, 0x3dd53b94, v97
	v_fmamk_f32 v77, v77, 0x3dd53b94, v97
	v_fmamk_f32 v76, v76, 0x3dd53b94, v97
	v_fmamk_f32 v75, v75, 0x3dd53b94, v97
	v_fmamk_f32 v74, v74, 0x3dd53b94, v97
	v_fmamk_f32 v73, v73, 0x3dd53b94, v97
	v_fmamk_f32 v72, v72, 0x3dd53b94, v97
	v_fmamk_f32 v71, v71, 0x3dd53b94, v97
	v_fmamk_f32 v70, v70, 0x3dd53b94, v97
	v_fmamk_f32 v69, v69, 0x3dd53b94, v97
	v_fmamk_f32 v68, v68, 0x3dd53b94, v97
	v_fmamk_f32 v67, v67, 0x3dd53b94, v97
	v_fmamk_f32 v98, v66, 0x3dd53b94, v97
	v_fmac_f32_e32 v97, 0x3dd53b94, v64
	v_add_f32_e32 v65, v91, v65
	v_exp_f32_e32 v97, v97
	v_add_f32_e32 v65, v92, v65
	v_add_f32_e32 v65, v93, v65
	v_exp_f32_e32 v98, v98
	v_add_f32_e32 v65, v94, v65
	v_add_f32_e32 v66, v100, v101
	v_exp_f32_e32 v100, v67
	v_add_f32_e32 v65, v95, v65
	v_exp_f32_e32 v101, v68
	v_add_f32_e32 v65, v97, v65
	v_exp_f32_e32 v102, v69
	v_add_f32_e32 v65, v99, v65
	v_exp_f32_e32 v103, v70
	v_add_f32_e32 v65, v98, v65
	v_exp_f32_e32 v104, v71
	v_add_f32_e32 v65, v100, v65
	v_exp_f32_e32 v105, v72
	v_add_f32_e32 v65, v101, v65
	v_exp_f32_e32 v106, v73
	v_add_f32_e32 v65, v102, v65
	v_exp_f32_e32 v107, v74
	v_add_f32_e32 v65, v103, v65
	v_exp_f32_e32 v108, v75
	v_add_f32_e32 v65, v104, v65
	v_exp_f32_e32 v109, v76
	v_add_f32_e32 v65, v105, v65
	v_exp_f32_e32 v110, v77
	v_add_f32_e32 v65, v106, v65
	v_exp_f32_e32 v111, v78
	v_add_f32_e32 v65, v107, v65
	v_exp_f32_e32 v112, v79
	v_add_f32_e32 v65, v108, v65
	v_add_f32_e32 v65, v109, v65
	v_add_f32_e32 v65, v110, v65
	v_add_f32_e32 v65, v111, v65
	s_lshl_b64 s[12:13], s[12:13], 11
	v_add_f32_e32 v65, v112, v65
	s_add_u32 s12, s28, s12
	v_mov_b32_e32 v67, v65
	s_addc_u32 s13, s29, s13
	s_lshl_b32 s14, s37, 1
	v_mul_f32_e32 v64, v162, v144
	v_permlane32_swap_b32_e32 v65, v67
	s_add_u32 s12, s12, s14
	v_pk_add_f32 v[64:65], v[64:65], v[66:67]
	v_cvt_pk_bf16_f32 v66, v80, v81
	v_cvt_pk_bf16_f32 v67, v82, v83
	v_cvt_pk_bf16_f32 v68, v84, v85
	v_cvt_pk_bf16_f32 v69, v86, v87
	v_cvt_pk_bf16_f32 v70, v88, v89
	v_cvt_pk_bf16_f32 v71, v90, v91
	v_cvt_pk_bf16_f32 v72, v92, v93
	v_cvt_pk_bf16_f32 v73, v94, v95
	v_cvt_pk_bf16_f32 v74, v97, v99
	v_cvt_pk_bf16_f32 v75, v98, v100
	v_cvt_pk_bf16_f32 v76, v101, v102
	v_cvt_pk_bf16_f32 v77, v103, v104
	v_cvt_pk_bf16_f32 v78, v105, v106
	v_cvt_pk_bf16_f32 v79, v107, v108
	v_cvt_pk_bf16_f32 v80, v109, v110
	v_cvt_pk_bf16_f32 v81, v111, v112
	s_addc_u32 s13, s13, 0
	v_fmac_f32_e32 v65, v64, v96
	ds_read_b64_tr_b16 v[82:83], v196 offset:0
	ds_read_b64_tr_b16 v[84:85], v196 offset:0x800
	ds_read_b64_tr_b16 v[86:87], v196 offset:0x1000
	ds_read_b64_tr_b16 v[88:89], v196 offset:0x1800
	ds_read_b64_tr_b16 v[90:91], v196 offset:0x2000
	ds_read_b64_tr_b16 v[92:93], v196 offset:0x2800
	ds_read_b64_tr_b16 v[94:95], v196 offset:0x3000
	ds_read_b64_tr_b16 v[96:97], v196 offset:0x3800
	s_waitcnt lgkmcnt(0)
	s_nop 0
	v_mfma_f32_32x32x16_bf16 v[0:15], v[82:85], v[66:69], v[0:15]
	ds_read_b64_tr_b16 v[82:83], v196 offset:0x200
	ds_read_b64_tr_b16 v[84:85], v196 offset:0xa00
	v_mfma_f32_32x32x16_bf16 v[0:15], v[86:89], v[70:73], v[0:15]
	ds_read_b64_tr_b16 v[86:87], v196 offset:0x1200
	ds_read_b64_tr_b16 v[88:89], v196 offset:0x1a00
	v_mfma_f32_32x32x16_bf16 v[0:15], v[90:93], v[74:77], v[0:15]
	ds_read_b64_tr_b16 v[90:91], v196 offset:0x2200
	ds_read_b64_tr_b16 v[92:93], v196 offset:0x2a00
	v_mfma_f32_32x32x16_bf16 v[0:15], v[94:97], v[78:81], v[0:15]
	ds_read_b64_tr_b16 v[94:95], v196 offset:0x3200
	ds_read_b64_tr_b16 v[96:97], v196 offset:0x3a00
	s_waitcnt lgkmcnt(0)
	v_mfma_f32_32x32x16_bf16 v[48:63], v[82:85], v[66:69], v[48:63]
	ds_read_b64_tr_b16 v[82:83], v196 offset:0x400
	ds_read_b64_tr_b16 v[84:85], v196 offset:0xc00
	v_mfma_f32_32x32x16_bf16 v[48:63], v[86:89], v[70:73], v[48:63]
	ds_read_b64_tr_b16 v[86:87], v196 offset:0x1400
	ds_read_b64_tr_b16 v[88:89], v196 offset:0x1c00
	v_mfma_f32_32x32x16_bf16 v[48:63], v[90:93], v[74:77], v[48:63]
	ds_read_b64_tr_b16 v[90:91], v196 offset:0x2400
	ds_read_b64_tr_b16 v[92:93], v196 offset:0x2c00
	v_mfma_f32_32x32x16_bf16 v[48:63], v[94:97], v[78:81], v[48:63]
	ds_read_b64_tr_b16 v[94:95], v196 offset:0x3400
	ds_read_b64_tr_b16 v[96:97], v196 offset:0x3c00
	s_waitcnt lgkmcnt(0)
; #define SBAR() __builtin_amdgcn_sched_barrier(0)
; #define RESC(a) do { if (__any((a) < 1.f)) { if (hi == 0) al_l[r32] = (a); asm volatile("s_waitcnt lgkmcnt(0)" ::: "memory"); \
;     for (int d = 0; d < 4; ++d) for (int r = 0; r < 16; ++r) o[d][r] *= al_l[crow_(r, hi)]; } } while (0)
; #define RESC(a) do { if (__any((a) < 1.f)) { for (int d = 0; d < 4; ++d) for (int r = 0; r < 16; ++r) o[d][r] *= (a); } } while (0)
; #define RESC(a) do { if (__any((a) < 1.f)) { for (int d = 0; d < 4; ++d) for (int r = 0; r < 16; ++r) o[d][r] *= (a); } } while (0)
; __device__ __forceinline__ void attn_mla_dma(const bf16_t* __restrict__ Qb, const bf16_t* __restrict__ Kh, const bf16_t* __restrict__ Vh, bf16_t* __restrict__ Ob,
;                                              int seq, char* lds, const int tid) {
;     ...
;   pv_d0_t(o, vb0 + vprev * SHM_VV, pa0, pa1, pa2, pa3); partialSM<MLA>(pB0, pB1, m_reg, mnB, alB);
;   RESC(alB);
;   finishSM(pB0, pB1, alB, l_reg, pa0, pa1, pa2, pa3); SBAR();
;   pv_d0_t(o, vb0 + vcur * SHM_VV, pa0, pa1, pa2, pa3);
;   int tide = tid; asm volatile("" : "+v"(tide));
;   const int wide = tide >> 6, r32e = tide & 31, hie = (tide >> 5) & 1;
;   const float rl = __builtin_amdgcn_rcpf(l_reg);
;   bf16_t* Ow = Ob + (long)(wide * QBLK + r32e) * LDO + hie * 8;
; #pragma unroll
;   for (int d0 = 0; d0 < 4; ++d0)
; #pragma unroll
;     for (int b = 0; b < 16; b += 8) {
;       const u32x4 w = pack8_row(o[d0][b] * rl, o[d0][b + 1] * rl, o[d0][b + 2] * rl, o[d0][b + 3] * rl, o[d0][b + 4] * rl, o[d0][b + 5] * rl, o[d0][b + 6] * rl, o[d0][b + 7] * rl);
;       *reinterpret_cast<u32x4*>(Ow + d0 * 32 + b * 2) = w;
;     }
;   __syncthreads();
	v_mfma_f32_32x32x16_bf16 v[32:47], v[82:85], v[66:69], v[32:47]
	ds_read_b64_tr_b16 v[82:83], v196 offset:0x600
	ds_read_b64_tr_b16 v[84:85], v196 offset:0xe00
	v_mfma_f32_32x32x16_bf16 v[32:47], v[86:89], v[70:73], v[32:47]
	ds_read_b64_tr_b16 v[86:87], v196 offset:0x1600
	ds_read_b64_tr_b16 v[88:89], v196 offset:0x1e00
	v_mfma_f32_32x32x16_bf16 v[32:47], v[90:93], v[74:77], v[32:47]
	ds_read_b64_tr_b16 v[90:91], v196 offset:0x2600
	ds_read_b64_tr_b16 v[92:93], v196 offset:0x2e00
	v_mfma_f32_32x32x16_bf16 v[32:47], v[94:97], v[78:81], v[32:47]
	ds_read_b64_tr_b16 v[94:95], v196 offset:0x3600
	ds_read_b64_tr_b16 v[96:97], v196 offset:0x3e00
	s_waitcnt lgkmcnt(0)
	v_mfma_f32_32x32x16_bf16 v[16:31], v[82:85], v[66:69], v[16:31]
	v_rcp_f32_e32 v66, v65
	s_movk_i32 s4, 0xffe0
	v_ashrrev_i32_e32 v64, 1, v156
	v_bfi_b32 v64, s4, v64, v156
	v_ashrrev_i32_e32 v65, 31, v64
	v_lshlrev_b64 v[64:65], 11, v[64:65]
	v_mfma_f32_32x32x16_bf16 v[16:31], v[86:89], v[70:73], v[16:31]
	v_lshrrev_b32_e32 v67, 1, v156
	v_mul_f32_e32 v0, v66, v0
	v_mul_f32_e32 v1, v66, v1
	v_mul_f32_e32 v2, v66, v2
	v_mul_f32_e32 v3, v66, v3
	v_lshl_add_u64 v[64:65], s[12:13], 0, v[64:65]
	v_and_b32_e32 v162, 16, v67
	v_mul_f32_e32 v4, v66, v4
	v_mul_f32_e32 v5, v66, v5
	v_mul_f32_e32 v6, v66, v6
	v_mul_f32_e32 v7, v66, v7
	v_cvt_pk_bf16_f32 v0, v0, v1
	v_cvt_pk_bf16_f32 v1, v2, v3
	v_cvt_pk_bf16_f32 v2, v4, v5
	v_cvt_pk_bf16_f32 v3, v6, v7
	v_mfma_f32_32x32x16_bf16 v[16:31], v[90:93], v[74:77], v[16:31]
	v_lshl_add_u64 v[64:65], v[64:65], 0, v[162:163]
	v_permlane32_swap_b32_e32 v0, v2
	v_permlane32_swap_b32_e32 v1, v3
	flat_store_dwordx4 v[64:65], v[0:3]
	v_mul_f32_e32 v4, v66, v12
	v_mul_f32_e32 v5, v66, v13
	v_mul_f32_e32 v0, v66, v8
	v_mul_f32_e32 v1, v66, v9
	v_mul_f32_e32 v2, v66, v10
	v_mul_f32_e32 v3, v66, v11
	v_mul_f32_e32 v6, v66, v14
	v_mul_f32_e32 v7, v66, v15
	v_cvt_pk_bf16_f32 v0, v0, v1
	v_cvt_pk_bf16_f32 v1, v2, v3
	v_cvt_pk_bf16_f32 v2, v4, v5
	v_cvt_pk_bf16_f32 v3, v6, v7
	v_mul_f32_e32 v4, v66, v52
	v_permlane32_swap_b32_e32 v0, v2
	v_permlane32_swap_b32_e32 v1, v3
	flat_store_dwordx4 v[64:65], v[0:3] offset:32
	v_mul_f32_e32 v5, v66, v53
	v_mul_f32_e32 v6, v66, v54
	v_mul_f32_e32 v0, v66, v48
	v_mul_f32_e32 v1, v66, v49
	v_mul_f32_e32 v2, v66, v50
	v_mul_f32_e32 v3, v66, v51
	v_mul_f32_e32 v7, v66, v55
	v_cvt_pk_bf16_f32 v0, v0, v1
	v_cvt_pk_bf16_f32 v1, v2, v3
	v_cvt_pk_bf16_f32 v2, v4, v5
	v_cvt_pk_bf16_f32 v3, v6, v7
	v_mfma_f32_32x32x16_bf16 v[16:31], v[94:97], v[78:81], v[16:31]
	v_permlane32_swap_b32_e32 v0, v2
	v_permlane32_swap_b32_e32 v1, v3
	flat_store_dwordx4 v[64:65], v[0:3] offset:64
	v_mul_f32_e32 v4, v66, v60
	v_mul_f32_e32 v5, v66, v61
	v_mul_f32_e32 v0, v66, v56
	v_mul_f32_e32 v1, v66, v57
	v_mul_f32_e32 v2, v66, v58
	v_mul_f32_e32 v3, v66, v59
	v_mul_f32_e32 v6, v66, v62
	v_mul_f32_e32 v7, v66, v63
	v_cvt_pk_bf16_f32 v0, v0, v1
	v_cvt_pk_bf16_f32 v1, v2, v3
	v_cvt_pk_bf16_f32 v2, v4, v5
	v_cvt_pk_bf16_f32 v3, v6, v7
	v_mul_f32_e32 v4, v66, v36
	v_permlane32_swap_b32_e32 v0, v2
	v_permlane32_swap_b32_e32 v1, v3
	flat_store_dwordx4 v[64:65], v[0:3] offset:96
	v_mul_f32_e32 v5, v66, v37
	v_mul_f32_e32 v6, v66, v38
	v_mul_f32_e32 v0, v66, v32
	v_mul_f32_e32 v1, v66, v33
	v_mul_f32_e32 v2, v66, v34
	v_mul_f32_e32 v3, v66, v35
	v_mul_f32_e32 v7, v66, v39
	v_cvt_pk_bf16_f32 v0, v0, v1
	v_cvt_pk_bf16_f32 v1, v2, v3
	v_cvt_pk_bf16_f32 v2, v4, v5
	v_cvt_pk_bf16_f32 v3, v6, v7
	v_mul_f32_e32 v4, v66, v44
	v_permlane32_swap_b32_e32 v0, v2
	v_permlane32_swap_b32_e32 v1, v3
	flat_store_dwordx4 v[64:65], v[0:3] offset:128
	v_mul_f32_e32 v5, v66, v45
	v_mul_f32_e32 v6, v66, v46
	v_mul_f32_e32 v0, v66, v40
	v_mul_f32_e32 v1, v66, v41
	v_mul_f32_e32 v2, v66, v42
	v_mul_f32_e32 v3, v66, v43
	v_mul_f32_e32 v7, v66, v47
	v_cvt_pk_bf16_f32 v0, v0, v1
	v_cvt_pk_bf16_f32 v1, v2, v3
	v_cvt_pk_bf16_f32 v2, v4, v5
	v_cvt_pk_bf16_f32 v3, v6, v7
	v_mul_f32_e32 v4, v66, v20
	v_permlane32_swap_b32_e32 v0, v2
	v_permlane32_swap_b32_e32 v1, v3
	flat_store_dwordx4 v[64:65], v[0:3] offset:160
	v_mul_f32_e32 v5, v66, v21
	v_mul_f32_e32 v6, v66, v22
	v_mul_f32_e32 v0, v66, v16
	v_mul_f32_e32 v1, v66, v17
	v_mul_f32_e32 v2, v66, v18
	v_mul_f32_e32 v3, v66, v19
	v_mul_f32_e32 v7, v66, v23
	v_cvt_pk_bf16_f32 v0, v0, v1
	v_cvt_pk_bf16_f32 v1, v2, v3
	v_cvt_pk_bf16_f32 v2, v4, v5
	v_cvt_pk_bf16_f32 v3, v6, v7
	v_mul_f32_e32 v4, v66, v28
	v_permlane32_swap_b32_e32 v0, v2
	v_permlane32_swap_b32_e32 v1, v3
	flat_store_dwordx4 v[64:65], v[0:3] offset:192
	v_mul_f32_e32 v5, v66, v29
	v_mul_f32_e32 v6, v66, v30
	v_mul_f32_e32 v0, v66, v24
	v_mul_f32_e32 v1, v66, v25
	v_mul_f32_e32 v2, v66, v26
	v_mul_f32_e32 v3, v66, v27
	v_mul_f32_e32 v7, v66, v31
	v_cvt_pk_bf16_f32 v0, v0, v1
	v_cvt_pk_bf16_f32 v1, v2, v3
	v_cvt_pk_bf16_f32 v2, v4, v5
	v_cvt_pk_bf16_f32 v3, v6, v7
	s_add_i32 s36, s36, s72
	s_add_i32 s31, s31, s72
	v_permlane32_swap_b32_e32 v0, v2
	v_permlane32_swap_b32_e32 v1, v3
	s_cmpk_gt_i32 s36, 0x1ff
	flat_store_dwordx4 v[64:65], v[0:3] offset:224
	s_waitcnt vmcnt(0) lgkmcnt(0)
	s_barrier
	s_cbranch_scc1 .LBB0_125
; __device__ __forceinline__ int v_rd_base(int lane) { return ((lane & 3) << 3) | (((lane >> 2) & 3) << 6) | (((lane >> 4) & 1) << 5) | (((lane >> 5) & 1) << 8); }
; __device__ __forceinline__ bf16x8 ld8(const bf16_t* p) { return gld8(p); }
; #define TILE_BAR() do { asm volatile("s_waitcnt vmcnt(0) lgkmcnt(0)" ::: "memory"); __builtin_amdgcn_s_barrier(); } while (0)
; #define TILE_BAR() do { asm volatile("s_waitcnt vmcnt(0) lgkmcnt(0)" ::: "memory"); __builtin_amdgcn_s_barrier(); } while (0)
; __device__ __forceinline__ void attn_mla_dma(const bf16_t* __restrict__ Qb, const bf16_t* __restrict__ Kh, const bf16_t* __restrict__ Vh, bf16_t* __restrict__ Ob,
;                                              int seq, char* lds, const int tid) {
;     ...
;   const bf16_t* Qw = Qb + (long)(wid * QBLK + r32) * LDQ + hi * 8;
; #pragma unroll
;   for (int d0 = 0; d0 < 12; ++d0) qr[d0] = ld8(Qw + d0 * 16);
;   const char* qlds = nullptr;
;   unsigned kof[3], vof[2];
; #pragma unroll
;   for (int i = 0; i < 3; ++i) { const int ob = (i * 8 + wid) * 1024 + lane * 16, row = ob / 384, within = ob - row * 384;
;     kof[i] = (unsigned)(row * (LDKK * 2) + (within ^ (((row >> 1) & 7) << 4))); }
; #pragma unroll
;   for (int i = 0; i < 2; ++i) { const int ob = (i * 8 + wid) * 1024 + lane * 16, st = ob >> 9, sw = (ob & 511) >> 1;
;     const int kk = (st >> 2) * 8 + (sw >> 5), c = (st & 3) * 32 + (sw & 31);
;     const int k = (kk & ~0xC) | ((kk & 4) << 1) | ((kk & 8) >> 1);
;     vof[i] = (unsigned)(k * (LDV * 2) + c * 2); }
;   const int vb0 = (int)(uintptr_t)V_lds + v_rd_base(lane);
;   int ka[4];
; #pragma unroll
;   for (int q = 0; q < 4; ++q) ka[q] = (int)(uintptr_t)K_lds + r32 * 384 + ((q * 32 + hi * 16) ^ (((r32 >> 1) & 7) << 4));
;     ...
;   f32x16 pA0, pA1, pB0, pB1; float mnA, mnB, alA, alB; bf16x8 pa0, pa1, pa2, pa3; const int NT = seq / KVBLK;
;   DMA_TILE(0, 0, 0); TILE_BAR();
; __global__ __launch_bounds__(512, 2) void mega(Params p) {
;     ...
;       for (int t = blockIdx.x; t < 512; t += gridDim.x) {
;         int bid = t & 255, rnd = t >> 8, h = bid & 7, qbg = (bid >> 3) + 32 * rnd;
;         int b = qbg / nqb_m, qb = qbg % nqb_m;
;         int ttid = tid; asm volatile("" : "+v"(ttid));
;         long tok0 = (long)b * S, q0 = tok0 + (long)qb * 256;
;         attn_mla_dma((const bf16_t*)(ws + O_Q) + q0 * 1536 + h * 192, (const bf16_t*)(ws + O_K) + tok0 * 1536 + h * 192,
.LBB0_114:
	s_ashr_i32 s5, s36, 3
	s_bfe_u32 s4, s36, 0x50003
	s_andn2_b32 s5, s5, 31
	s_or_b32 s5, s4, s5
	s_abs_i32 s12, s5
	s_mul_hi_u32 s13, s12, s35
	s_mul_i32 s14, s13, s30
	s_and_b32 s43, s31, 7
	s_ashr_i32 s4, s36, 31
	s_sub_i32 s12, s12, s14
	s_lshl_b32 s47, s43, 8
	s_and_b32 s16, s36, 7
	s_xor_b32 s4, s4, s34
	s_add_i32 s14, s13, 1
	s_sub_i32 s15, s12, s30
	s_cmp_ge_u32 s12, s30
	s_cselect_b32 s13, s14, s13
	s_cselect_b32 s12, s15, s12
	s_add_i32 s14, s13, 1
	s_cmp_ge_u32 s12, s30
	s_cselect_b32 s12, s14, s13
	s_xor_b32 s12, s12, s4
	s_sub_i32 s4, s12, s4
	s_mul_i32 s12, s4, s20
	s_sub_i32 s12, s5, s12
	s_ashr_i32 s5, s4, 31
	s_ashr_i32 s13, s12, 31
	s_lshl_b64 s[14:15], s[4:5], s18
	s_lshl_b64 s[4:5], s[12:13], 8
	s_add_u32 s12, s4, s14
	s_addc_u32 s13, s5, s15
	s_mul_i32 s4, s13, 0xc00
	s_mul_hi_u32 s5, s12, 0xc00
	s_add_i32 s5, s5, s4
	s_mul_i32 s4, s12, 0xc00
	s_add_u32 s4, s21, s4
	s_addc_u32 s5, s23, s5
	s_mul_i32 s17, s16, 0x180
	v_mov_b32_e32 v156, v168
	s_add_u32 s40, s4, s17
	s_addc_u32 s41, s5, 0
	v_ashrrev_i32_e32 v2, 6, v156
	v_and_b32_e32 v4, 31, v156
	v_lshl_or_b32 v5, v2, 5, v4
	v_mov_b64_e32 v[0:1], s[40:41]
	v_mad_i64_i32 v[0:1], s[40:41], v5, s33, v[0:1]
	v_lshrrev_b32_e32 v5, 1, v156
	v_and_b32_e32 v162, 16, v5
	v_lshl_add_u64 v[0:1], v[0:1], 0, v[162:163]
	global_load_dwordx4 v[140:143], v[0:1], off
	global_load_dwordx4 v[136:139], v[0:1], off offset:32
	global_load_dwordx4 v[132:135], v[0:1], off offset:64
	global_load_dwordx4 v[128:131], v[0:1], off offset:96
	global_load_dwordx4 v[124:127], v[0:1], off offset:128
	global_load_dwordx4 v[120:123], v[0:1], off offset:160
	global_load_dwordx4 v[116:119], v[0:1], off offset:192
	global_load_dwordx4 v[112:115], v[0:1], off offset:224
	global_load_dwordx4 v[108:111], v[0:1], off offset:256
	global_load_dwordx4 v[104:107], v[0:1], off offset:288
	global_load_dwordx4 v[100:103], v[0:1], off offset:320
	global_load_dwordx4 v[96:99], v[0:1], off offset:352
	v_and_b32_e32 v3, 63, v156
	v_lshlrev_b32_e32 v0, 10, v2
	v_lshlrev_b32_e32 v68, 4, v3
	v_or_b32_e32 v1, v0, v68
	v_mul_hi_i32 v6, v1, s49
	v_lshrrev_b32_e32 v7, 31, v6
	v_ashrrev_i32_e32 v6, 6, v6
	v_add_u32_e32 v6, v6, v7
	s_movk_i32 s40, 0xfe80
	v_mad_i32_i24 v7, v6, s40, v1
	v_mul_i32_i24_e32 v8, 0xc00, v6
	v_lshlrev_b32_e32 v6, 3, v6
	v_and_b32_e32 v6, 0x70, v6
	v_xad_u32 v188, v7, v6, v8
	v_add_u32_e32 v6, 0x2000, v1
	v_mul_hi_i32 v7, v6, s49
	v_lshrrev_b32_e32 v8, 31, v7
	v_ashrrev_i32_e32 v7, 6, v7
	v_add_u32_e32 v7, v7, v8
	v_mad_i32_i24 v6, v7, s40, v6
	v_mul_i32_i24_e32 v8, 0xc00, v7
	v_lshlrev_b32_e32 v7, 3, v7
	v_and_b32_e32 v7, 0x70, v7
	v_add_u32_e32 v1, 0x4000, v1
	s_mul_i32 s4, s15, 0xc00
	s_mul_hi_u32 s50, s14, 0xc00
	v_xad_u32 v189, v6, v7, v8
	v_mul_hi_i32 v6, v1, s49
	s_add_i32 s50, s50, s4
	s_mul_i32 s70, s14, 0xc00
	v_lshrrev_b32_e32 v7, 31, v6
	v_ashrrev_i32_e32 v6, 6, v6
	s_add_u32 s4, s24, s70
	v_add_u32_e32 v6, v6, v7
	s_addc_u32 s5, s25, s50
	v_mad_i32_i24 v1, v6, s40, v1
	v_mul_i32_i24_e32 v7, 0xc00, v6
	v_lshlrev_b32_e32 v6, 3, v6
	s_add_u32 s4, s4, s17
	v_and_b32_e32 v6, 0x70, v6
	s_addc_u32 s5, s5, 0
	s_lshl_b64 s[14:15], s[14:15], 11
	v_xad_u32 v191, v1, v6, v7
	v_lshlrev_b32_e32 v69, 3, v3
	v_ashrrev_i32_e32 v6, 8, v0
	s_add_u32 s17, s26, s14
	v_bfe_u32 v1, v156, 2, 2
	v_and_b32_e32 v70, 24, v69
	s_movk_i32 s56, 0x60
	v_and_b32_e32 v7, 0x1ffff0, v6
	v_lshrrev_b32_e32 v6, 1, v6
	s_addc_u32 s42, s27, s15
	s_lshl_b32 s37, s16, 7
	s_lshl_b32 s16, s16, 8
	v_and_or_b32 v3, v156, s56, v70
	v_and_or_b32 v1, v5, 8, v1
	v_and_b32_e32 v6, 4, v6
	v_add_u32_e32 v0, 0x2000, v0
	s_add_u32 s16, s17, s16
	v_lshlrev_b32_e32 v3, 1, v3
	v_or3_b32 v6, v7, v6, v1
	v_ashrrev_i32_e32 v0, 8, v0
	s_addc_u32 s17, s42, 0
	v_lshl_or_b32 v194, v6, 11, v3
	v_and_b32_e32 v6, 0x1ffff0, v0
	v_lshrrev_b32_e32 v0, 1, v0
	s_add_i32 s40, 0, 0xc000
	v_and_b32_e32 v0, 4, v0
	s_cmp_lg_u32 s40, -1
	v_or3_b32 v0, v6, v0, v1
	s_cselect_b32 s40, s40, 0
	v_lshl_or_b32 v195, v0, 11, v3
	v_mov_b32_e32 v0, s40
	s_movk_i32 s40, 0x180
	v_mad_u32_u24 v56, v4, s40, v0
	v_readfirstlane_b32 s40, v2
	s_cmp_lg_u32 0, -1
	v_lshlrev_b32_e32 v0, 3, v156
	s_cselect_b32 s44, 0, 0
	s_lshl_b32 s40, s40, 10
	v_and_b32_e32 v57, 0x70, v0
	s_add_i32 s40, s40, 0
	v_bitop3_b32 v0, v5, v57, 16 bitop3:0x6c
	s_add_i32 s41, s40, 0xc000
	v_bfe_u32 v244, v160, 2, 1
	v_bfe_u32 v245, v160, 3, 1
	v_xor_b32_e32 v243, v244, v245
	v_sub_u32_e32 v242, v244, v245
	v_mul_i32_i24_e32 v242, 0x600, v242
	v_mul_u32_u24_e32 v243, 0x60, v243
	v_add_u32_e32 v169, v0, v56
	v_xor_b32_e32 v169, v169, v243
	v_add_u32_e32 v169, v169, v242
	s_mov_b64 s[52:53], s[4:5]
	s_mov_b64 s[54:55], s[16:17]
	v_mov_b32_e32 v0, v189
	v_mov_b32_e32 v1, v194
	v_mov_b32_e32 v2, v188
	v_mov_b32_e32 v3, v191
	v_mov_b32_e32 v4, v195
	s_mov_b32 m0, s41
	s_add_i32 s42, s40, 0xe000
	v_bitop3_b32 v8, v162, v57, 32 bitop3:0x36
	global_load_lds_dwordx4 v2, s[52:53]
	s_mov_b32 m0, s42
	v_add_u32_e32 v190, v8, v56
	v_xor_b32_e32 v190, v190, v243
	v_add_u32_e32 v190, v190, v242
	global_load_lds_dwordx4 v0, s[52:53]
	s_add_i32 m0, s40, 0x10000
	v_bitop3_b32 v48, v162, v57, 64 bitop3:0x36
	global_load_lds_dwordx4 v3, s[52:53]
	s_mov_b32 m0, s40
	v_add_u32_e32 v193, v48, v56
	v_xor_b32_e32 v193, v193, v243
	v_add_u32_e32 v193, v193, v242
	global_load_lds_dwordx4 v1, s[54:55]
	s_add_i32 m0, s40, 0x2000
	v_bitop3_b32 v57, v162, v57, s56 bitop3:0x36
	global_load_lds_dwordx4 v4, s[54:55]
	s_waitcnt vmcnt(0) lgkmcnt(0)
	s_barrier
; template <int MLA>
; __device__ __forceinline__ void partialSM(f32x16& p0, f32x16& p1, float& m_reg, float& mn, float& alpha) {
;   constexpr float SCALE = AttC<MLA>::SCALE;
;   constexpr float C = SCALE * 1.4426950408889634f;
;   float pmax = p0[0];
; #pragma unroll
;   for (int r = 1; r < 16; ++r) pmax = fmaxf(pmax, p0[r]);
; #pragma unroll
;   for (int r = 0; r < 16; ++r) pmax = fmaxf(pmax, p1[r]);
;   { auto rr = __builtin_amdgcn_permlane32_swap(__float_as_uint(pmax), __float_as_uint(pmax), false, false);
;     pmax = fmaxf(__uint_as_float(rr[0]), __uint_as_float(rr[1])); }
;   if (__builtin_expect(__all(pmax - m_reg <= THR / SCALE), 1)) { mn = m_reg; alpha = 1.f; }
;   else { mn = fmaxf(m_reg, pmax); alpha = __builtin_amdgcn_exp2f((m_reg - mn) * C); m_reg = mn; }
;   float mnC = -mn * C;
; #pragma unroll
;   for (int r = 0; r < 16; ++r) p0[r] = fmaf(p0[r], C, mnC);
; #pragma unroll
;   for (int r = 0; r < 16; ++r) p1[r] = fmaf(p1[r], C, mnC);
; #pragma unroll
;   for (int r = 0; r < 16; ++r) p0[r] = __builtin_amdgcn_exp2f(p0[r]);
; template <int BUFOFF>
; __device__ __forceinline__ void qkt_mla(f32x16& p0, f32x16& p1, const int* ka, const bf16x8* qr, const char* qlds) {
;   typedef __attribute__((address_space(3))) const bf16x8* lp;
;   p0 = f32x16{}; p1 = f32x16{};
; #pragma unroll
;   for (int d0 = 0; d0 < 12; ++d0) {
;     const int a = ka[d0 & 3] + (d0 >> 2) * 128 + BUFOFF;
;     const bf16x8 b0 = *(lp)(a), b1 = *(lp)(a + 12288);
;     bf16x8 qf;
;     qf = qr[d0];
;     p0 = __builtin_amdgcn_mfma_f32_32x32x16_bf16(b0, qf, p0, 0, 0, 0);
;     p1 = __builtin_amdgcn_mfma_f32_32x32x16_bf16(b1, qf, p1, 0, 0, 0);
;   }
; }
	ds_read_b128 v[0:3], v169
	ds_read_b128 v[4:7], v169 offset:128
	s_waitcnt vmcnt(0) lgkmcnt(0)
	v_mfma_f32_32x32x16_bf16 v[16:31], v[0:3], v[140:143], 0
	ds_read_b128 v[0:3], v169 offset:12288
	ds_read_b128 v[8:11], v169 offset:256
	v_add_u32_e32 v192, v57, v56
	v_xor_b32_e32 v192, v192, v243
	v_add_u32_e32 v192, v192, v242
	s_mov_b32 s52, 0
	s_mov_b32 s53, s52
	s_add_u32 s4, s4, 0x30000
	s_mov_b32 s54, s52
	s_waitcnt lgkmcnt(1)
	v_mfma_f32_32x32x16_bf16 v[32:47], v[0:3], v[140:143], 0
	ds_read_b128 v[0:3], v190
	ds_read_b128 v[12:15], v190 offset:128
	ds_read_b128 v[48:51], v190 offset:256
	s_mov_b32 s55, s52
	s_mov_b32 s56, s52
	s_mov_b32 s57, s52
	s_mov_b32 s58, s52
	s_mov_b32 s59, s52
	s_waitcnt lgkmcnt(2)
	v_mfma_f32_32x32x16_bf16 v[16:31], v[0:3], v[136:139], v[16:31]
	ds_read_b128 v[0:3], v190 offset:12288
	s_mov_b32 s60, s52
	s_mov_b32 s61, s52
	s_mov_b32 s62, s52
	s_mov_b32 s63, s52
	s_mov_b32 s64, s52
	s_mov_b32 s65, s52
	s_waitcnt lgkmcnt(0)
	v_mfma_f32_32x32x16_bf16 v[32:47], v[0:3], v[136:139], v[32:47]
	ds_read_b128 v[0:3], v193
	ds_read_b128 v[52:55], v193 offset:128
	ds_read_b128 v[56:59], v193 offset:256
	s_mov_b32 s66, s52
	s_mov_b32 s67, s52
	s_addc_u32 s5, s5, 0
	s_mov_b32 s73, 0x42ddb3d8
	s_mul_i32 s74, s43, 0x180
	s_waitcnt lgkmcnt(2)
	v_mfma_f32_32x32x16_bf16 v[16:31], v[0:3], v[132:135], v[16:31]
	ds_read_b128 v[0:3], v193 offset:12288
	s_mov_b32 s43, 1
	v_mov_b32_e32 v162, 0
	s_waitcnt lgkmcnt(0)
	v_mfma_f32_32x32x16_bf16 v[32:47], v[0:3], v[132:135], v[32:47]
	ds_read_b128 v[0:3], v192
	ds_read_b128 v[60:63], v192 offset:128
	s_waitcnt lgkmcnt(1)
	v_mfma_f32_32x32x16_bf16 v[16:31], v[0:3], v[128:131], v[16:31]
	ds_read_b128 v[0:3], v192 offset:12288
	ds_read_b128 v[64:67], v192 offset:256
	v_mfma_f32_32x32x16_bf16 v[16:31], v[4:7], v[124:127], v[16:31]
	v_mfma_f32_32x32x16_bf16 v[16:31], v[12:15], v[120:123], v[16:31]
	s_waitcnt lgkmcnt(1)
	v_mfma_f32_32x32x16_bf16 v[32:47], v[0:3], v[128:131], v[32:47]
	ds_read_b128 v[0:3], v169 offset:12416
	ds_read_b128 v[4:7], v169 offset:12544
	v_mfma_f32_32x32x16_bf16 v[16:31], v[52:55], v[116:119], v[16:31]
	s_waitcnt lgkmcnt(1)
	v_mfma_f32_32x32x16_bf16 v[32:47], v[0:3], v[124:127], v[32:47]
	ds_read_b128 v[0:3], v190 offset:12416
	ds_read_b128 v[12:15], v190 offset:12544
	v_mfma_f32_32x32x16_bf16 v[16:31], v[60:63], v[112:115], v[16:31]
	s_waitcnt lgkmcnt(1)
	v_mfma_f32_32x32x16_bf16 v[32:47], v[0:3], v[120:123], v[32:47]
	ds_read_b128 v[0:3], v193 offset:12416
	ds_read_b128 v[52:55], v193 offset:12544
	v_mfma_f32_32x32x16_bf16 v[16:31], v[8:11], v[108:111], v[16:31]
	s_waitcnt lgkmcnt(1)
	v_mfma_f32_32x32x16_bf16 v[32:47], v[0:3], v[116:119], v[32:47]
	ds_read_b128 v[0:3], v192 offset:12416
	ds_read_b128 v[60:63], v192 offset:12544
	v_mfma_f32_32x32x16_bf16 v[16:31], v[48:51], v[104:107], v[16:31]
	v_mov_b32_e32 v50, v191
	v_mov_b32_e32 v51, v195
	s_waitcnt lgkmcnt(1)
	v_mfma_f32_32x32x16_bf16 v[32:47], v[0:3], v[112:115], v[32:47]
	v_lshlrev_b32_e32 v0, 1, v156
	v_and_b32_e32 v0, 32, v0
	v_and_or_b32 v0, v68, s48, v0
	v_and_b32_e32 v1, 0x100, v69
	v_or3_b32 v0, v0, v1, v70
	v_add_u32_e32 v167, s44, v0
	v_mfma_f32_32x32x16_bf16 v[16:31], v[56:59], v[100:103], v[16:31]
	v_mfma_f32_32x32x16_bf16 v[32:47], v[4:7], v[108:111], v[32:47]
	v_mfma_f32_32x32x16_bf16 v[16:31], v[64:67], v[96:99], v[16:31]
	v_mfma_f32_32x32x16_bf16 v[32:47], v[12:15], v[104:107], v[32:47]
	v_mov_b64_e32 v[0:1], s[52:53]
	v_mov_b64_e32 v[2:3], s[54:55]
	v_mov_b64_e32 v[4:5], s[56:57]
	v_mov_b64_e32 v[6:7], s[58:59]
	v_mov_b64_e32 v[8:9], s[60:61]
	v_mov_b64_e32 v[10:11], s[62:63]
	v_mov_b64_e32 v[12:13], s[64:65]
	v_mov_b64_e32 v[14:15], s[66:67]
	s_add_u32 s54, s16, 0x20000
	s_nop 1
	v_max_f32_e32 v48, v17, v17
	v_max_f32_e32 v49, v16, v16
	s_addc_u32 s55, s17, 0
	s_add_i32 s16, s40, 0x12000
	v_mfma_f32_32x32x16_bf16 v[32:47], v[52:55], v[100:103], v[32:47]
	v_max_f32_e32 v48, v49, v48
	v_mov_b32_e32 v49, v188
	v_mov_b32_e32 v52, v189
	v_mov_b32_e32 v53, v194
	s_mov_b32 m0, s16
	s_add_i32 s17, s40, 0x14000
	s_add_i32 s44, s40, 0x16000
	global_load_lds_dwordx4 v49, s[4:5]
	s_mov_b32 m0, s17
	s_add_i32 s53, s40, 0x4000
	global_load_lds_dwordx4 v52, s[4:5]
	s_mov_b32 m0, s44
	s_waitcnt lgkmcnt(0)
	v_mfma_f32_32x32x16_bf16 v[32:47], v[60:63], v[96:99], v[32:47]
	global_load_lds_dwordx4 v50, s[4:5]
	s_mov_b32 m0, s53
	v_max3_f32 v48, v48, v18, v19
	global_load_lds_dwordx4 v53, s[54:55]
	s_add_i32 m0, s40, 0x6000
	v_max3_f32 v48, v48, v20, v21
	global_load_lds_dwordx4 v51, s[54:55]
	v_max3_f32 v48, v48, v22, v23
	v_max3_f32 v48, v48, v24, v25
	v_max3_f32 v48, v48, v26, v27
	v_max3_f32 v48, v48, v28, v29
	v_max3_f32 v48, v48, v30, v31
	v_max3_f32 v48, v48, v32, v33
	v_max3_f32 v48, v48, v34, v35
	v_max3_f32 v48, v48, v36, v37
	v_max3_f32 v48, v48, v38, v39
	v_max3_f32 v48, v48, v40, v41
	v_max3_f32 v48, v48, v42, v43
	v_max3_f32 v48, v48, v44, v45
	v_max3_f32 v48, v48, v46, v47
	v_mov_b32_e32 v49, v48
	s_nop 1
	v_permlane32_swap_b32_e32 v48, v49
	v_max_f32_e32 v49, v49, v49
	v_max_f32_e32 v48, v48, v48
	v_max_f32_e32 v48, v48, v49
	v_add_f32_e32 v49, 0x7149f2ca, v48
	v_cmp_ge_f32_e32 vcc, s73, v49
	s_cmp_eq_u64 vcc, exec
	v_max_f32_e32 v49, 0xf149f2ca, v48
	s_cselect_b64 vcc, -1, 0
	v_cndmask_b32_e32 v197, v49, v183, vcc
	v_mul_f32_e32 v48, 0xbdd53b94, v197
	v_fmamk_f32 v16, v16, 0x3dd53b94, v48
	v_exp_f32_e32 v145, v16
	v_fmamk_f32 v16, v17, 0x3dd53b94, v48
	v_exp_f32_e32 v210, v16
	v_fmamk_f32 v16, v18, 0x3dd53b94, v48
	v_exp_f32_e32 v208, v16
	v_fmamk_f32 v16, v19, 0x3dd53b94, v48
	v_exp_f32_e32 v212, v16
	v_fmamk_f32 v16, v20, 0x3dd53b94, v48
	v_exp_f32_e32 v211, v16
	v_fmamk_f32 v16, v21, 0x3dd53b94, v48
	v_exp_f32_e32 v213, v16
	v_fmamk_f32 v16, v22, 0x3dd53b94, v48
	v_exp_f32_e32 v207, v16
	v_fmamk_f32 v16, v23, 0x3dd53b94, v48
	v_exp_f32_e32 v209, v16
	v_fmamk_f32 v16, v24, 0x3dd53b94, v48
	v_exp_f32_e32 v200, v16
	v_fmamk_f32 v16, v25, 0x3dd53b94, v48
	v_exp_f32_e32 v203, v16
	v_fmamk_f32 v16, v26, 0x3dd53b94, v48
	v_exp_f32_e32 v202, v16
	v_fmamk_f32 v16, v27, 0x3dd53b94, v48
	v_exp_f32_e32 v205, v16
	v_fmamk_f32 v16, v28, 0x3dd53b94, v48
	v_sub_f32_e32 v17, 0xf149f2ca, v49
	v_exp_f32_e32 v199, v16
	v_fmamk_f32 v16, v29, 0x3dd53b94, v48
	v_mul_f32_e32 v17, 0x3dd53b94, v17
	v_exp_f32_e32 v201, v16
	v_fmamk_f32 v16, v30, 0x3dd53b94, v48
	v_exp_f32_e32 v17, v17
	v_exp_f32_e32 v204, v16
	v_fmamk_f32 v16, v31, 0x3dd53b94, v48
	v_exp_f32_e32 v206, v16
	s_waitcnt vmcnt(0) lgkmcnt(0)
; #define SBAR() __builtin_amdgcn_sched_barrier(0)
; template <int BUFOFF>
; __device__ __forceinline__ void qkt_mla(f32x16& p0, f32x16& p1, const int* ka, const bf16x8* qr, const char* qlds) {
;   typedef __attribute__((address_space(3))) const bf16x8* lp;
;   p0 = f32x16{}; p1 = f32x16{};
; #pragma unroll
;   for (int d0 = 0; d0 < 12; ++d0) {
;     const int a = ka[d0 & 3] + (d0 >> 2) * 128 + BUFOFF;
;     const bf16x8 b0 = *(lp)(a), b1 = *(lp)(a + 12288);
;     bf16x8 qf;
;     qf = qr[d0];
;     p0 = __builtin_amdgcn_mfma_f32_32x32x16_bf16(b0, qf, p0, 0, 0, 0);
;     p1 = __builtin_amdgcn_mfma_f32_32x32x16_bf16(b1, qf, p1, 0, 0, 0);
;   }
; }
; __device__ __forceinline__ void attn_mla_dma(const bf16_t* __restrict__ Qb, const bf16_t* __restrict__ Kh, const bf16_t* __restrict__ Vh, bf16_t* __restrict__ Ob,
;                                              int seq, char* lds, const int tid) {
;     ...
;   for (int j = 1; j + 1 < NT; j += 2) {
;     SBAR(); qkt_mla<(int)SHM_K192>(pB0, pB1, ka, qr, qlds);
;     finishSM(pA0, pA1, alA, l_reg, pa0, pa1, pa2, pa3); SBAR();
	s_mov_b32 s4, 0x3dd53b94
	s_or_b32 s14, s14, s47
	v_cndmask_b32_e64 v198, v17, 1.0, vcc
	v_pk_fma_f32 v[154:155], v[46:47], s[4:5], v[48:49] op_sel_hi:[1,0,0]
	v_pk_fma_f32 v[146:147], v[44:45], s[4:5], v[48:49] op_sel_hi:[1,0,0]
	v_pk_fma_f32 v[148:149], v[42:43], s[4:5], v[48:49] op_sel_hi:[1,0,0]
	v_pk_fma_f32 v[150:151], v[40:41], s[4:5], v[48:49] op_sel_hi:[1,0,0]
	v_pk_fma_f32 v[152:153], v[38:39], s[4:5], v[48:49] op_sel_hi:[1,0,0]
	v_pk_fma_f32 v[158:159], v[36:37], s[4:5], v[48:49] op_sel_hi:[1,0,0]
	v_pk_fma_f32 v[170:171], v[34:35], s[4:5], v[48:49] op_sel_hi:[1,0,0]
	v_pk_fma_f32 v[172:173], v[32:33], s[4:5], v[48:49] op_sel_hi:[1,0,0]
	s_add_u32 s47, s70, s74
	v_mov_b64_e32 v[62:63], v[14:15]
	v_mov_b64_e32 v[46:47], v[14:15]
	v_mov_b64_e32 v[30:31], v[14:15]
	v_readlane_b32 s73, v249, 57
	s_mov_b32 s63, 0x42ddb3d8
	s_addc_u32 s50, s50, 0
	s_mov_b32 s53, 2
	v_mov_b64_e32 v[60:61], v[12:13]
	v_mov_b64_e32 v[58:59], v[10:11]
	v_mov_b64_e32 v[56:57], v[8:9]
	v_mov_b64_e32 v[54:55], v[6:7]
	v_mov_b64_e32 v[52:53], v[4:5]
	v_mov_b64_e32 v[50:51], v[2:3]
	v_mov_b64_e32 v[48:49], v[0:1]
	v_mov_b64_e32 v[44:45], v[12:13]
	v_mov_b64_e32 v[42:43], v[10:11]
	v_mov_b64_e32 v[40:41], v[8:9]
	v_mov_b64_e32 v[38:39], v[6:7]
	v_mov_b64_e32 v[36:37], v[4:5]
	v_mov_b64_e32 v[34:35], v[2:3]
	v_mov_b64_e32 v[32:33], v[0:1]
	s_mov_b32 s54, 2
	v_mov_b64_e32 v[28:29], v[12:13]
	v_mov_b64_e32 v[26:27], v[10:11]
	v_mov_b64_e32 v[24:25], v[8:9]
	v_mov_b64_e32 v[22:23], v[6:7]
	v_mov_b64_e32 v[20:21], v[4:5]
	v_mov_b64_e32 v[18:19], v[2:3]
	v_mov_b64_e32 v[16:17], v[0:1]
	s_barrier
.LBB0_115:
	s_mov_b32 s55, s43
	s_mov_b32 s43, s52
	ds_read_b128 v[64:67], v169 offset:24576
	ds_read_b128 v[68:71], v169 offset:36864
	ds_read_b128 v[214:217], v190 offset:24576
	ds_read_b128 v[218:221], v190 offset:36864
	v_add_f32_e32 v144, v210, v145
	s_waitcnt lgkmcnt(0)
	v_mfma_f32_32x32x16_bf16 v[80:95], v[64:67], v[140:143], 0
	v_add_f32_e32 v144, v208, v144
	v_add_f32_e32 v144, v212, v144
	v_add_f32_e32 v144, v211, v144
	v_add_f32_e32 v144, v213, v144
	v_add_f32_e32 v144, v207, v144
	v_add_f32_e32 v144, v209, v144
	v_add_f32_e32 v144, v200, v144
	v_mfma_f32_32x32x16_bf16 v[64:79], v[68:71], v[140:143], 0
	v_add_f32_e32 v144, v203, v144
	v_add_f32_e32 v144, v202, v144
	v_add_f32_e32 v144, v205, v144
	v_exp_f32_e32 v172, v172
	v_add_f32_e32 v144, v199, v144
	v_exp_f32_e32 v173, v173
	v_add_f32_e32 v144, v201, v144
	v_mfma_f32_32x32x16_bf16 v[80:95], v[214:217], v[136:139], v[80:95]
	v_exp_f32_e32 v170, v170
	v_add_f32_e32 v144, v204, v144
	v_exp_f32_e32 v171, v171
	v_add_f32_e32 v144, v206, v144
	v_exp_f32_e32 v196, v158
	v_add_f32_e32 v144, v172, v144
	v_add_f32_e32 v144, v173, v144
	v_mfma_f32_32x32x16_bf16 v[64:79], v[218:221], v[136:139], v[64:79]
	ds_read_b128 v[214:217], v193 offset:24576
	ds_read_b128 v[218:221], v193 offset:36864
	v_add_f32_e32 v144, v170, v144
	v_add_f32_e32 v144, v171, v144
	v_add_f32_e32 v144, v196, v144
	v_exp_f32_e32 v222, v147
	v_exp_f32_e32 v223, v154
	v_exp_f32_e32 v224, v155
	s_waitcnt lgkmcnt(0)
	v_mfma_f32_32x32x16_bf16 v[80:95], v[214:217], v[132:135], v[80:95]
	v_mfma_f32_32x32x16_bf16 v[64:79], v[218:221], v[132:135], v[64:79]
	ds_read_b128 v[214:217], v192 offset:24576
	ds_read_b128 v[218:221], v192 offset:36864
	s_waitcnt lgkmcnt(0)
	v_mfma_f32_32x32x16_bf16 v[80:95], v[214:217], v[128:131], v[80:95]
	v_mfma_f32_32x32x16_bf16 v[64:79], v[218:221], v[128:131], v[64:79]
	ds_read_b128 v[214:217], v169 offset:24704
	ds_read_b128 v[218:221], v169 offset:36992
	s_waitcnt lgkmcnt(0)
	v_mfma_f32_32x32x16_bf16 v[80:95], v[214:217], v[124:127], v[80:95]
	v_mfma_f32_32x32x16_bf16 v[64:79], v[218:221], v[124:127], v[64:79]
	ds_read_b128 v[214:217], v190 offset:24704
	ds_read_b128 v[218:221], v190 offset:36992
	s_waitcnt lgkmcnt(0)
	v_mfma_f32_32x32x16_bf16 v[80:95], v[214:217], v[120:123], v[80:95]
	v_mfma_f32_32x32x16_bf16 v[64:79], v[218:221], v[120:123], v[64:79]
	ds_read_b128 v[214:217], v193 offset:24704
	ds_read_b128 v[218:221], v193 offset:36992
	s_waitcnt lgkmcnt(0)
	v_mfma_f32_32x32x16_bf16 v[80:95], v[214:217], v[116:119], v[80:95]
	v_mfma_f32_32x32x16_bf16 v[64:79], v[218:221], v[116:119], v[64:79]
	ds_read_b128 v[214:217], v192 offset:24704
	ds_read_b128 v[218:221], v192 offset:36992
	s_waitcnt lgkmcnt(0)
	v_mfma_f32_32x32x16_bf16 v[80:95], v[214:217], v[112:115], v[80:95]
	v_mfma_f32_32x32x16_bf16 v[64:79], v[218:221], v[112:115], v[64:79]
	ds_read_b128 v[214:217], v169 offset:24832
	ds_read_b128 v[218:221], v169 offset:37120
	s_waitcnt lgkmcnt(0)
	v_mfma_f32_32x32x16_bf16 v[80:95], v[214:217], v[108:111], v[80:95]
	v_mfma_f32_32x32x16_bf16 v[64:79], v[218:221], v[108:111], v[64:79]
	ds_read_b128 v[214:217], v190 offset:24832
	ds_read_b128 v[218:221], v190 offset:37120
	s_waitcnt lgkmcnt(0)
	v_mfma_f32_32x32x16_bf16 v[80:95], v[214:217], v[104:107], v[80:95]
	v_mfma_f32_32x32x16_bf16 v[64:79], v[218:221], v[104:107], v[64:79]
	ds_read_b128 v[214:217], v193 offset:24832
	ds_read_b128 v[218:221], v193 offset:37120
	s_waitcnt lgkmcnt(0)
	v_mfma_f32_32x32x16_bf16 v[80:95], v[214:217], v[100:103], v[80:95]
	v_mfma_f32_32x32x16_bf16 v[64:79], v[218:221], v[100:103], v[64:79]
	ds_read_b128 v[214:217], v192 offset:24832
	ds_read_b128 v[218:221], v192 offset:37120
	s_waitcnt lgkmcnt(0)
; #define SBAR() __builtin_amdgcn_sched_barrier(0)
; #define TILE_BAR() do { asm volatile("s_waitcnt vmcnt(0) lgkmcnt(0)" ::: "memory"); __builtin_amdgcn_s_barrier(); } while (0)
; #define TILE_BAR() do { asm volatile("s_waitcnt vmcnt(0) lgkmcnt(0)" ::: "memory"); __builtin_amdgcn_s_barrier(); } while (0)
; template <int D0> __device__ __forceinline__ void pv_one_t(f32x16& od, int vb, bf16x8 pa0, bf16x8 pa1, bf16x8 pa2, bf16x8 pa3) {
;   const s16x4 l0 = tr_read<v_rd_off(D0, 0, 0)>(vb), h0 = tr_read<v_rd_off(D0, 0, 1)>(vb), l1 = tr_read<v_rd_off(D0, 1, 0)>(vb), h1 = tr_read<v_rd_off(D0, 1, 1)>(vb);
;   const s16x4 l2 = tr_read<v_rd_off(D0, 2, 0)>(vb), h2 = tr_read<v_rd_off(D0, 2, 1)>(vb), l3 = tr_read<v_rd_off(D0, 3, 0)>(vb), h3 = tr_read<v_rd_off(D0, 3, 1)>(vb);
;   asm volatile("s_waitcnt lgkmcnt(0)" ::: "memory"); SBAR();
;     ...
;   od = __builtin_amdgcn_mfma_f32_32x32x16_bf16(PK(l0, h0), pa0, od, 0, 0, 0);
;   od = __builtin_amdgcn_mfma_f32_32x32x16_bf16(PK(l1, h1), pa1, od, 0, 0, 0);
;   od = __builtin_amdgcn_mfma_f32_32x32x16_bf16(PK(l2, h2), pa2, od, 0, 0, 0);
;   od = __builtin_amdgcn_mfma_f32_32x32x16_bf16(PK(l3, h3), pa3, od, 0, 0, 0);
;     ...
; }
; __device__ __forceinline__ void pv_d0_t(f32x16* o, int vb, bf16x8 pa0, bf16x8 pa1, bf16x8 pa2, bf16x8 pa3) {
;   pv_one_t<0>(o[0], vb, pa0, pa1, pa2, pa3); pv_one_t<1>(o[1], vb, pa0, pa1, pa2, pa3); pv_one_t<2>(o[2], vb, pa0, pa1, pa2, pa3); pv_one_t<3>(o[3], vb, pa0, pa1, pa2, pa3);
; }
; __device__ __forceinline__ void attn_mla_dma(const bf16_t* __restrict__ Qb, const bf16_t* __restrict__ Kh, const bf16_t* __restrict__ Vh, bf16_t* __restrict__ Ob,
;                                              int seq, char* lds, const int tid) {
;     ...
;     finishSM(pA0, pA1, alA, l_reg, pa0, pa1, pa2, pa3); SBAR();
;     DMA_TILE((j + 1) * KVBLK, 0, vnxt); SBAR();
;     pv_d0_t(o, vb0 + vprev * SHM_VV, pa0, pa1, pa2, pa3); partialSM<MLA>(pB0, pB1, m_reg, mnB, alB);
;     TILE_BAR();
	v_mfma_f32_32x32x16_bf16 v[80:95], v[214:217], v[96:99], v[80:95]
	v_exp_f32_e32 v214, v159
	v_exp_f32_e32 v215, v152
	v_exp_f32_e32 v216, v153
	v_exp_f32_e32 v217, v150
	v_add_f32_e32 v144, v214, v144
	v_add_f32_e32 v144, v215, v144
	v_add_f32_e32 v144, v216, v144
	v_mfma_f32_32x32x16_bf16 v[64:79], v[218:221], v[96:99], v[64:79]
	v_exp_f32_e32 v218, v151
	v_exp_f32_e32 v219, v148
	v_exp_f32_e32 v220, v149
	v_exp_f32_e32 v221, v146
	v_add_f32_e32 v144, v217, v144
	v_add_f32_e32 v144, v218, v144
	v_add_f32_e32 v144, v219, v144
	v_add_f32_e32 v144, v220, v144
	v_add_f32_e32 v144, v221, v144
	v_add_f32_e32 v144, v222, v144
	v_add_f32_e32 v144, v223, v144
	v_add_f32_e32 v158, v224, v144
	v_mov_b32_e32 v159, v158
	v_cvt_pk_bf16_f32 v144, v145, v210
	v_cvt_pk_bf16_f32 v145, v208, v212
	v_cvt_pk_bf16_f32 v146, v211, v213
	v_cvt_pk_bf16_f32 v147, v207, v209
	v_cvt_pk_bf16_f32 v148, v200, v203
	v_cvt_pk_bf16_f32 v149, v202, v205
	v_cvt_pk_bf16_f32 v150, v199, v201
	v_cvt_pk_bf16_f32 v151, v204, v206
	v_cvt_pk_bf16_f32 v152, v172, v173
	v_cvt_pk_bf16_f32 v153, v170, v171
	v_cvt_pk_bf16_f32 v154, v196, v214
	s_nop 1
	v_permlane32_swap_b32_e32 v158, v159
	v_cvt_pk_bf16_f32 v155, v215, v216
	v_cvt_pk_bf16_f32 v170, v217, v218
	v_cvt_pk_bf16_f32 v171, v219, v220
	v_cvt_pk_bf16_f32 v172, v221, v222
	v_cvt_pk_bf16_f32 v173, v223, v224
	v_readlane_b32 s58, v249, 37
	v_readlane_b32 s59, v249, 38
	s_add_u32 s56, s58, s47
	s_addc_u32 s57, s59, s50
	s_add_u32 s4, s56, 0x17060000
	s_addc_u32 s5, s57, 0
	s_add_u32 s58, s58, s14
	s_addc_u32 s59, s59, s15
	s_add_u32 s60, s58, 0x1a040000
	s_mov_b32 m0, s41
	s_addc_u32 s61, s59, 0
	s_lshl_b32 s52, s54, 14
	s_add_i32 s62, s40, s52
	global_load_lds_dwordx4 v188, s[4:5]
	s_mov_b32 m0, s42
	s_nop 0
	global_load_lds_dwordx4 v189, s[4:5]
	s_add_i32 m0, s41, 0x4000
	s_nop 0
	global_load_lds_dwordx4 v191, s[4:5]
	s_mov_b32 m0, s62
	s_nop 0
	global_load_lds_dwordx4 v194, s[60:61]
	s_add_i32 m0, s62, 0x2000
	s_nop 0
	global_load_lds_dwordx4 v195, s[60:61]
	s_lshl_b32 s60, s43, 14
	v_add_u32_e32 v196, s60, v167
	ds_read_b64_tr_b16 v[200:201], v196 offset:0
	ds_read_b64_tr_b16 v[202:203], v196 offset:0x800
	ds_read_b64_tr_b16 v[204:205], v196 offset:0x1000
	ds_read_b64_tr_b16 v[206:207], v196 offset:0x1800
	ds_read_b64_tr_b16 v[208:209], v196 offset:0x2000
	ds_read_b64_tr_b16 v[210:211], v196 offset:0x2800
	ds_read_b64_tr_b16 v[212:213], v196 offset:0x3000
	ds_read_b64_tr_b16 v[214:215], v196 offset:0x3800
	s_waitcnt lgkmcnt(0)
	s_nop 0
	v_mfma_f32_32x32x16_bf16 v[0:15], v[200:203], v[144:147], v[0:15]
	ds_read_b64_tr_b16 v[200:201], v196 offset:0x200
	ds_read_b64_tr_b16 v[202:203], v196 offset:0xa00
	v_mfma_f32_32x32x16_bf16 v[0:15], v[204:207], v[148:151], v[0:15]
	ds_read_b64_tr_b16 v[204:205], v196 offset:0x1200
	ds_read_b64_tr_b16 v[206:207], v196 offset:0x1a00
	v_mfma_f32_32x32x16_bf16 v[0:15], v[208:211], v[152:155], v[0:15]
	ds_read_b64_tr_b16 v[208:209], v196 offset:0x2200
	ds_read_b64_tr_b16 v[210:211], v196 offset:0x2a00
	v_mfma_f32_32x32x16_bf16 v[0:15], v[212:215], v[170:173], v[0:15]
	ds_read_b64_tr_b16 v[212:213], v196 offset:0x3200
	ds_read_b64_tr_b16 v[214:215], v196 offset:0x3a00
	s_waitcnt lgkmcnt(0)
	v_mfma_f32_32x32x16_bf16 v[48:63], v[200:203], v[144:147], v[48:63]
	ds_read_b64_tr_b16 v[200:201], v196 offset:0x400
	ds_read_b64_tr_b16 v[202:203], v196 offset:0xc00
	v_mfma_f32_32x32x16_bf16 v[48:63], v[204:207], v[148:151], v[48:63]
	ds_read_b64_tr_b16 v[204:205], v196 offset:0x1400
	ds_read_b64_tr_b16 v[206:207], v196 offset:0x1c00
	v_mfma_f32_32x32x16_bf16 v[48:63], v[208:211], v[152:155], v[48:63]
	ds_read_b64_tr_b16 v[208:209], v196 offset:0x2400
	ds_read_b64_tr_b16 v[210:211], v196 offset:0x2c00
	v_mfma_f32_32x32x16_bf16 v[48:63], v[212:215], v[170:173], v[48:63]
	ds_read_b64_tr_b16 v[212:213], v196 offset:0x3400
	ds_read_b64_tr_b16 v[214:215], v196 offset:0x3c00
	s_waitcnt lgkmcnt(0)
	v_mfma_f32_32x32x16_bf16 v[32:47], v[200:203], v[144:147], v[32:47]
	ds_read_b64_tr_b16 v[200:201], v196 offset:0x600
	ds_read_b64_tr_b16 v[202:203], v196 offset:0xe00
	v_mfma_f32_32x32x16_bf16 v[32:47], v[204:207], v[148:151], v[32:47]
	ds_read_b64_tr_b16 v[204:205], v196 offset:0x1600
	ds_read_b64_tr_b16 v[206:207], v196 offset:0x1e00
	v_mfma_f32_32x32x16_bf16 v[32:47], v[208:211], v[152:155], v[32:47]
	ds_read_b64_tr_b16 v[208:209], v196 offset:0x2600
	ds_read_b64_tr_b16 v[210:211], v196 offset:0x2e00
	v_mfma_f32_32x32x16_bf16 v[32:47], v[212:215], v[170:173], v[32:47]
	ds_read_b64_tr_b16 v[212:213], v196 offset:0x3600
	ds_read_b64_tr_b16 v[214:215], v196 offset:0x3e00
	s_waitcnt lgkmcnt(0)
	v_mfma_f32_32x32x16_bf16 v[16:31], v[200:203], v[144:147], v[16:31]
	v_max_f32_e32 v144, v80, v81
	v_max3_f32 v144, v144, v82, v83
	v_max3_f32 v144, v144, v84, v85
	v_max3_f32 v144, v144, v86, v87
	v_max3_f32 v144, v144, v88, v89
	v_max3_f32 v144, v144, v90, v91
	v_max3_f32 v144, v144, v92, v93
	v_mfma_f32_32x32x16_bf16 v[16:31], v[204:207], v[148:151], v[16:31]
	v_max3_f32 v144, v144, v94, v95
	v_max3_f32 v144, v144, v64, v65
	v_max3_f32 v144, v144, v66, v67
	v_max3_f32 v144, v144, v68, v69
	v_max3_f32 v144, v144, v70, v71
	v_max3_f32 v144, v144, v72, v73
	v_max3_f32 v144, v144, v74, v75
	v_max3_f32 v144, v144, v76, v77
	v_mfma_f32_32x32x16_bf16 v[16:31], v[208:211], v[152:155], v[16:31]
	v_max3_f32 v144, v144, v78, v79
	v_mov_b32_e32 v145, v144
	s_nop 1
	v_permlane32_swap_b32_e32 v144, v145
	v_max_f32_e32 v144, v144, v145
	v_sub_f32_e32 v145, v144, v197
	v_cmp_ge_f32_e32 vcc, s63, v145
	v_max_f32_e32 v144, v197, v144
	v_mfma_f32_32x32x16_bf16 v[16:31], v[212:215], v[170:173], v[16:31]
	v_sub_f32_e32 v145, v197, v144
	v_mul_f32_e32 v145, 0x3dd53b94, v145
	v_exp_f32_e32 v145, v145
	s_cmp_eq_u64 vcc, exec
	s_cselect_b64 s[4:5], -1, 0
	s_waitcnt vmcnt(0) lgkmcnt(0)
	v_cndmask_b32_e64 v152, v145, 1.0, s[4:5]
	v_cmp_gt_f32_e32 vcc, 1.0, v152
	s_barrier
; #define SBAR() __builtin_amdgcn_sched_barrier(0)
; #define RESC(a) do { if (__any((a) < 1.f)) { if (hi == 0) al_l[r32] = (a); asm volatile("s_waitcnt lgkmcnt(0)" ::: "memory"); \
;     for (int d = 0; d < 4; ++d) for (int r = 0; r < 16; ++r) o[d][r] *= al_l[crow_(r, hi)]; } } while (0)
; #define RESC(a) do { if (__any((a) < 1.f)) { for (int d = 0; d < 4; ++d) for (int r = 0; r < 16; ++r) o[d][r] *= (a); } } while (0)
; #define RESC(a) do { if (__any((a) < 1.f)) { for (int d = 0; d < 4; ++d) for (int r = 0; r < 16; ++r) o[d][r] *= (a); } } while (0)
; template <int BUFOFF>
; __device__ __forceinline__ void qkt_mla(f32x16& p0, f32x16& p1, const int* ka, const bf16x8* qr, const char* qlds) {
;   typedef __attribute__((address_space(3))) const bf16x8* lp;
;   p0 = f32x16{}; p1 = f32x16{};
; #pragma unroll
;   for (int d0 = 0; d0 < 12; ++d0) {
;     const int a = ka[d0 & 3] + (d0 >> 2) * 128 + BUFOFF;
;     const bf16x8 b0 = *(lp)(a), b1 = *(lp)(a + 12288);
;     bf16x8 qf;
;     qf = qr[d0];
;     p0 = __builtin_amdgcn_mfma_f32_32x32x16_bf16(b0, qf, p0, 0, 0, 0);
;     p1 = __builtin_amdgcn_mfma_f32_32x32x16_bf16(b1, qf, p1, 0, 0, 0);
;   }
; }
; __device__ __forceinline__ void attn_mla_dma(const bf16_t* __restrict__ Qb, const bf16_t* __restrict__ Kh, const bf16_t* __restrict__ Vh, bf16_t* __restrict__ Ob,
;                                              int seq, char* lds, const int tid) {
;     ...
;     RESC(alB);
;     { const int t = vprev; vprev = vcur; vcur = vnxt; vnxt = t; }
;     SBAR(); qkt_mla<0>(pA0, pA1, ka, qr, qlds);
	s_cbranch_vccz .LBB0_117
	v_pk_mul_f32 v[14:15], v[14:15], v[152:153] op_sel_hi:[1,0]
	v_pk_mul_f32 v[12:13], v[12:13], v[152:153] op_sel_hi:[1,0]
	v_pk_mul_f32 v[10:11], v[10:11], v[152:153] op_sel_hi:[1,0]
	v_pk_mul_f32 v[8:9], v[8:9], v[152:153] op_sel_hi:[1,0]
	v_pk_mul_f32 v[6:7], v[6:7], v[152:153] op_sel_hi:[1,0]
	v_pk_mul_f32 v[4:5], v[4:5], v[152:153] op_sel_hi:[1,0]
	v_pk_mul_f32 v[2:3], v[2:3], v[152:153] op_sel_hi:[1,0]
	v_pk_mul_f32 v[0:1], v[0:1], v[152:153] op_sel_hi:[1,0]
	v_pk_mul_f32 v[62:63], v[62:63], v[152:153] op_sel_hi:[1,0]
	v_pk_mul_f32 v[60:61], v[60:61], v[152:153] op_sel_hi:[1,0]
	v_pk_mul_f32 v[58:59], v[58:59], v[152:153] op_sel_hi:[1,0]
	v_pk_mul_f32 v[56:57], v[56:57], v[152:153] op_sel_hi:[1,0]
	v_pk_mul_f32 v[54:55], v[54:55], v[152:153] op_sel_hi:[1,0]
	v_pk_mul_f32 v[52:53], v[52:53], v[152:153] op_sel_hi:[1,0]
	v_pk_mul_f32 v[50:51], v[50:51], v[152:153] op_sel_hi:[1,0]
	v_pk_mul_f32 v[48:49], v[48:49], v[152:153] op_sel_hi:[1,0]
	v_pk_mul_f32 v[46:47], v[46:47], v[152:153] op_sel_hi:[1,0]
	v_pk_mul_f32 v[44:45], v[44:45], v[152:153] op_sel_hi:[1,0]
	v_pk_mul_f32 v[42:43], v[42:43], v[152:153] op_sel_hi:[1,0]
	v_pk_mul_f32 v[40:41], v[40:41], v[152:153] op_sel_hi:[1,0]
	v_pk_mul_f32 v[38:39], v[38:39], v[152:153] op_sel_hi:[1,0]
	v_pk_mul_f32 v[36:37], v[36:37], v[152:153] op_sel_hi:[1,0]
	v_pk_mul_f32 v[34:35], v[34:35], v[152:153] op_sel_hi:[1,0]
	v_pk_mul_f32 v[32:33], v[32:33], v[152:153] op_sel_hi:[1,0]
	v_pk_mul_f32 v[30:31], v[30:31], v[152:153] op_sel_hi:[1,0]
	v_pk_mul_f32 v[28:29], v[28:29], v[152:153] op_sel_hi:[1,0]
	v_pk_mul_f32 v[26:27], v[26:27], v[152:153] op_sel_hi:[1,0]
	v_pk_mul_f32 v[24:25], v[24:25], v[152:153] op_sel_hi:[1,0]
	v_pk_mul_f32 v[22:23], v[22:23], v[152:153] op_sel_hi:[1,0]
	v_pk_mul_f32 v[20:21], v[20:21], v[152:153] op_sel_hi:[1,0]
	v_pk_mul_f32 v[18:19], v[18:19], v[152:153] op_sel_hi:[1,0]
	v_pk_mul_f32 v[16:17], v[16:17], v[152:153] op_sel_hi:[1,0]
.LBB0_117:
	v_cndmask_b32_e64 v153, v144, v197, s[4:5]
	v_mul_f32_e32 v154, 0xbdd53b94, v153
	v_fmamk_f32 v80, v80, 0x3dd53b94, v154
	v_fmamk_f32 v81, v81, 0x3dd53b94, v154
	v_fmamk_f32 v82, v82, 0x3dd53b94, v154
	v_fmamk_f32 v83, v83, 0x3dd53b94, v154
	v_fmamk_f32 v84, v84, 0x3dd53b94, v154
	v_fmamk_f32 v85, v85, 0x3dd53b94, v154
	v_fmamk_f32 v86, v86, 0x3dd53b94, v154
	v_fmamk_f32 v87, v87, 0x3dd53b94, v154
	v_fmamk_f32 v88, v88, 0x3dd53b94, v154
	v_fmamk_f32 v89, v89, 0x3dd53b94, v154
	v_fmamk_f32 v90, v90, 0x3dd53b94, v154
	v_fmamk_f32 v91, v91, 0x3dd53b94, v154
	v_fmamk_f32 v92, v92, 0x3dd53b94, v154
	v_fmamk_f32 v93, v93, 0x3dd53b94, v154
	v_fmamk_f32 v94, v94, 0x3dd53b94, v154
	v_fmamk_f32 v95, v95, 0x3dd53b94, v154
	v_fmamk_f32 v155, v64, 0x3dd53b94, v154
	v_fmamk_f32 v170, v65, 0x3dd53b94, v154
	v_fmamk_f32 v171, v66, 0x3dd53b94, v154
	v_fmamk_f32 v172, v67, 0x3dd53b94, v154
	v_fmamk_f32 v173, v68, 0x3dd53b94, v154
	v_fmamk_f32 v197, v69, 0x3dd53b94, v154
	v_fmamk_f32 v199, v70, 0x3dd53b94, v154
	v_fmamk_f32 v200, v71, 0x3dd53b94, v154
	v_fmamk_f32 v201, v72, 0x3dd53b94, v154
	v_fmamk_f32 v202, v73, 0x3dd53b94, v154
	v_fmamk_f32 v203, v74, 0x3dd53b94, v154
	v_fmamk_f32 v204, v75, 0x3dd53b94, v154
	v_fmamk_f32 v205, v76, 0x3dd53b94, v154
	v_fmamk_f32 v222, v77, 0x3dd53b94, v154
	v_fmamk_f32 v223, v78, 0x3dd53b94, v154
	v_fmac_f32_e32 v154, 0x3dd53b94, v79
	v_exp_f32_e32 v206, v80
	v_exp_f32_e32 v207, v81
	v_exp_f32_e32 v208, v82
	v_exp_f32_e32 v209, v83
	v_exp_f32_e32 v210, v84
	v_exp_f32_e32 v211, v85
	v_exp_f32_e32 v212, v86
	v_exp_f32_e32 v213, v87
	v_exp_f32_e32 v214, v88
	v_exp_f32_e32 v215, v89
	v_exp_f32_e32 v216, v90
	v_exp_f32_e32 v217, v91
	v_exp_f32_e32 v218, v92
	v_exp_f32_e32 v219, v93
	v_exp_f32_e32 v220, v94
	v_exp_f32_e32 v221, v95
	ds_read_b128 v[64:67], v169
	ds_read_b128 v[68:71], v169 offset:12288
	ds_read_b128 v[144:147], v190
	ds_read_b128 v[148:151], v190 offset:12288
	v_exp_f32_e32 v224, v155
	v_exp_f32_e32 v170, v170
	s_waitcnt lgkmcnt(0)
	v_mfma_f32_32x32x16_bf16 v[80:95], v[64:67], v[140:143], 0
	v_exp_f32_e32 v171, v171
	v_exp_f32_e32 v172, v172
	v_exp_f32_e32 v173, v173
	v_exp_f32_e32 v197, v197
	v_exp_f32_e32 v199, v199
	v_exp_f32_e32 v200, v200
	v_exp_f32_e32 v201, v201
	v_mfma_f32_32x32x16_bf16 v[64:79], v[68:71], v[140:143], 0
	v_exp_f32_e32 v202, v202
	v_exp_f32_e32 v203, v203
	v_exp_f32_e32 v204, v204
	v_exp_f32_e32 v205, v205
	v_exp_f32_e32 v222, v222
	v_exp_f32_e32 v223, v223
	v_exp_f32_e32 v225, v154
	v_mfma_f32_32x32x16_bf16 v[80:95], v[144:147], v[136:139], v[80:95]
	v_mfma_f32_32x32x16_bf16 v[64:79], v[148:151], v[136:139], v[64:79]
	ds_read_b128 v[144:147], v193
	ds_read_b128 v[148:151], v193 offset:12288
	s_waitcnt lgkmcnt(0)
	v_mfma_f32_32x32x16_bf16 v[80:95], v[144:147], v[132:135], v[80:95]
	v_mfma_f32_32x32x16_bf16 v[64:79], v[148:151], v[132:135], v[64:79]
	ds_read_b128 v[144:147], v192
	ds_read_b128 v[148:151], v192 offset:12288
	s_waitcnt lgkmcnt(0)
	v_mfma_f32_32x32x16_bf16 v[80:95], v[144:147], v[128:131], v[80:95]
	v_mfma_f32_32x32x16_bf16 v[64:79], v[148:151], v[128:131], v[64:79]
	ds_read_b128 v[144:147], v169 offset:128
	ds_read_b128 v[148:151], v169 offset:12416
	s_waitcnt lgkmcnt(0)
	v_mfma_f32_32x32x16_bf16 v[80:95], v[144:147], v[124:127], v[80:95]
	v_mfma_f32_32x32x16_bf16 v[64:79], v[148:151], v[124:127], v[64:79]
	ds_read_b128 v[144:147], v190 offset:128
	ds_read_b128 v[148:151], v190 offset:12416
	s_waitcnt lgkmcnt(0)
	v_mfma_f32_32x32x16_bf16 v[80:95], v[144:147], v[120:123], v[80:95]
	v_mfma_f32_32x32x16_bf16 v[64:79], v[148:151], v[120:123], v[64:79]
	ds_read_b128 v[144:147], v193 offset:128
	ds_read_b128 v[148:151], v193 offset:12416
	s_waitcnt lgkmcnt(0)
; #define SBAR() __builtin_amdgcn_sched_barrier(0)
; __device__ __forceinline__ void finishSM(f32x16& p0, f32x16& p1, float alpha, float& l_reg, bf16x8& pa0, bf16x8& pa1, bf16x8& pa2, bf16x8& pa3) {
; #pragma unroll
;   for (int r = 0; r < 16; ++r) p1[r] = __builtin_amdgcn_exp2f(p1[r]);
;   float ps = 0;
; #pragma unroll
;   for (int r = 0; r < 16; ++r) ps += p0[r];
; #pragma unroll
;   for (int r = 0; r < 16; ++r) ps += p1[r];
;   { auto rr = __builtin_amdgcn_permlane32_swap(__float_as_uint(ps), __float_as_uint(ps), false, false);
;     ps = __uint_as_float(rr[0]) + __uint_as_float(rr[1]); }
;   l_reg = l_reg * alpha + ps;
;     ...
;   PK4(p0, 0, pa0); PK4(p0, 8, pa1); PK4(p1, 0, pa2); PK4(p1, 8, pa3);
;     ...
; }
; __device__ __forceinline__ void attn_mla_dma(const bf16_t* __restrict__ Qb, const bf16_t* __restrict__ Kh, const bf16_t* __restrict__ Vh, bf16_t* __restrict__ Ob,
;                                              int seq, char* lds, const int tid) {
;     ...
;     finishSM(pB0, pB1, alB, l_reg, pa0, pa1, pa2, pa3); SBAR();
;     DMA_TILE((j + 2) * KVBLK, 1, vnxt); SBAR();
;     pv_d0_t(o, vb0 + vprev * SHM_VV, pa0, pa1, pa2, pa3); partialSM<MLA>(pA0, pA1, m_reg, mnA, alA);
	v_mfma_f32_32x32x16_bf16 v[80:95], v[144:147], v[116:119], v[80:95]
	v_mfma_f32_32x32x16_bf16 v[64:79], v[148:151], v[116:119], v[64:79]
	ds_read_b128 v[144:147], v192 offset:128
	ds_read_b128 v[148:151], v192 offset:12416
	s_waitcnt lgkmcnt(0)
	v_mfma_f32_32x32x16_bf16 v[80:95], v[144:147], v[112:115], v[80:95]
	v_mfma_f32_32x32x16_bf16 v[64:79], v[148:151], v[112:115], v[64:79]
	ds_read_b128 v[144:147], v169 offset:256
	ds_read_b128 v[148:151], v169 offset:12544
	s_waitcnt lgkmcnt(0)
	v_mfma_f32_32x32x16_bf16 v[80:95], v[144:147], v[108:111], v[80:95]
	v_mfma_f32_32x32x16_bf16 v[64:79], v[148:151], v[108:111], v[64:79]
	ds_read_b128 v[144:147], v190 offset:256
	ds_read_b128 v[148:151], v190 offset:12544
	s_waitcnt lgkmcnt(0)
	v_mfma_f32_32x32x16_bf16 v[80:95], v[144:147], v[104:107], v[80:95]
	v_mfma_f32_32x32x16_bf16 v[64:79], v[148:151], v[104:107], v[64:79]
	ds_read_b128 v[144:147], v193 offset:256
	ds_read_b128 v[148:151], v193 offset:12544
	s_waitcnt lgkmcnt(0)
	v_mfma_f32_32x32x16_bf16 v[80:95], v[144:147], v[100:103], v[80:95]
	v_mfma_f32_32x32x16_bf16 v[64:79], v[148:151], v[100:103], v[64:79]
	ds_read_b128 v[144:147], v192 offset:256
	ds_read_b128 v[148:151], v192 offset:12544
	s_waitcnt lgkmcnt(0)
	v_mfma_f32_32x32x16_bf16 v[80:95], v[144:147], v[96:99], v[80:95]
	v_add_f32_e32 v144, 0, v206
	v_add_f32_e32 v144, v207, v144
	v_add_f32_e32 v144, v208, v144
	v_add_f32_e32 v144, v209, v144
	v_add_f32_e32 v144, v210, v144
	v_add_f32_e32 v144, v211, v144
	v_add_f32_e32 v144, v212, v144
	v_add_f32_e32 v144, v213, v144
	v_add_f32_e32 v144, v214, v144
	v_add_f32_e32 v144, v215, v144
	v_add_f32_e32 v144, v216, v144
	v_add_f32_e32 v144, v217, v144
	v_add_f32_e32 v144, v218, v144
	v_add_f32_e32 v144, v219, v144
	v_add_f32_e32 v144, v220, v144
	v_add_f32_e32 v144, v221, v144
	v_add_f32_e32 v144, v224, v144
	v_add_f32_e32 v144, v170, v144
	v_add_f32_e32 v144, v171, v144
	v_add_f32_e32 v144, v172, v144
	v_add_f32_e32 v144, v173, v144
	v_add_f32_e32 v144, v197, v144
	v_add_f32_e32 v144, v199, v144
	v_add_f32_e32 v144, v200, v144
	v_add_f32_e32 v144, v201, v144
	v_add_f32_e32 v144, v202, v144
	v_mfma_f32_32x32x16_bf16 v[64:79], v[148:151], v[96:99], v[64:79]
	v_add_f32_e32 v144, v203, v144
	v_add_f32_e32 v144, v204, v144
	v_add_f32_e32 v144, v205, v144
	v_add_f32_e32 v144, v222, v144
	v_add_f32_e32 v144, v223, v144
	v_add_f32_e32 v154, v225, v144
	v_mov_b32_e32 v155, v154
	v_cvt_pk_bf16_f32 v144, v206, v207
	v_cvt_pk_bf16_f32 v145, v208, v209
	v_cvt_pk_bf16_f32 v146, v210, v211
	v_cvt_pk_bf16_f32 v147, v212, v213
	s_nop 1
	v_permlane32_swap_b32_e32 v154, v155
	v_cvt_pk_bf16_f32 v148, v214, v215
	v_cvt_pk_bf16_f32 v149, v216, v217
	v_cvt_pk_bf16_f32 v150, v218, v219
	v_cvt_pk_bf16_f32 v151, v220, v221
	v_cvt_pk_bf16_f32 v170, v224, v170
	v_cvt_pk_bf16_f32 v171, v171, v172
	v_cvt_pk_bf16_f32 v172, v173, v197
	v_cvt_pk_bf16_f32 v173, v199, v200
	v_cvt_pk_bf16_f32 v200, v201, v202
	v_cvt_pk_bf16_f32 v201, v203, v204
	v_cvt_pk_bf16_f32 v202, v205, v222
	v_cvt_pk_bf16_f32 v203, v223, v225
	s_nop 0
	s_add_u32 s4, s56, 0x17090000
	s_addc_u32 s5, s57, 0
	s_add_u32 s56, s58, 0x1a060000
	s_mov_b32 m0, s16
	s_addc_u32 s57, s59, 0
	s_add_i32 s58, s40, s60
	global_load_lds_dwordx4 v188, s[4:5]
	s_mov_b32 m0, s17
	s_nop 0
	global_load_lds_dwordx4 v189, s[4:5]
	s_mov_b32 m0, s44
	s_nop 0
	global_load_lds_dwordx4 v191, s[4:5]
	s_mov_b32 m0, s58
	s_nop 0
	global_load_lds_dwordx4 v194, s[56:57]
	s_add_i32 m0, s58, 0x2000
	s_nop 0
	global_load_lds_dwordx4 v195, s[56:57]
	v_lshl_add_u32 v197, s55, 14, v167
	ds_read_b64_tr_b16 v[204:205], v197 offset:0
	ds_read_b64_tr_b16 v[206:207], v197 offset:0x800
	ds_read_b64_tr_b16 v[208:209], v197 offset:0x1000
	ds_read_b64_tr_b16 v[210:211], v197 offset:0x1800
	ds_read_b64_tr_b16 v[212:213], v197 offset:0x2000
	ds_read_b64_tr_b16 v[214:215], v197 offset:0x2800
	ds_read_b64_tr_b16 v[216:217], v197 offset:0x3000
	ds_read_b64_tr_b16 v[218:219], v197 offset:0x3800
	s_waitcnt lgkmcnt(0)
	s_nop 0
	v_mfma_f32_32x32x16_bf16 v[0:15], v[204:207], v[144:147], v[0:15]
	ds_read_b64_tr_b16 v[204:205], v197 offset:0x200
	ds_read_b64_tr_b16 v[206:207], v197 offset:0xa00
	v_mfma_f32_32x32x16_bf16 v[0:15], v[208:211], v[148:151], v[0:15]
	ds_read_b64_tr_b16 v[208:209], v197 offset:0x1200
	ds_read_b64_tr_b16 v[210:211], v197 offset:0x1a00
	v_mfma_f32_32x32x16_bf16 v[0:15], v[212:215], v[170:173], v[0:15]
	ds_read_b64_tr_b16 v[212:213], v197 offset:0x2200
	ds_read_b64_tr_b16 v[214:215], v197 offset:0x2a00
	v_mfma_f32_32x32x16_bf16 v[0:15], v[216:219], v[200:203], v[0:15]
	ds_read_b64_tr_b16 v[216:217], v197 offset:0x3200
	ds_read_b64_tr_b16 v[218:219], v197 offset:0x3a00
	s_waitcnt lgkmcnt(0)
; #define RESC(a) do { if (__any((a) < 1.f)) { if (hi == 0) al_l[r32] = (a); asm volatile("s_waitcnt lgkmcnt(0)" ::: "memory"); \
;     for (int d = 0; d < 4; ++d) for (int r = 0; r < 16; ++r) o[d][r] *= al_l[crow_(r, hi)]; } } while (0)
; #define TILE_BAR() do { asm volatile("s_waitcnt vmcnt(0) lgkmcnt(0)" ::: "memory"); __builtin_amdgcn_s_barrier(); } while (0)
; #define RESC(a) do { if (__any((a) < 1.f)) { for (int d = 0; d < 4; ++d) for (int r = 0; r < 16; ++r) o[d][r] *= (a); } } while (0)
; #define TILE_BAR() do { asm volatile("s_waitcnt vmcnt(0) lgkmcnt(0)" ::: "memory"); __builtin_amdgcn_s_barrier(); } while (0)
; #define RESC(a) do { if (__any((a) < 1.f)) { for (int d = 0; d < 4; ++d) for (int r = 0; r < 16; ++r) o[d][r] *= (a); } } while (0)
; template <int MLA>
; __device__ __forceinline__ void partialSM(f32x16& p0, f32x16& p1, float& m_reg, float& mn, float& alpha) {
;   constexpr float SCALE = AttC<MLA>::SCALE;
;   constexpr float C = SCALE * 1.4426950408889634f;
;   float pmax = p0[0];
; #pragma unroll
;   for (int r = 1; r < 16; ++r) pmax = fmaxf(pmax, p0[r]);
; #pragma unroll
;   for (int r = 0; r < 16; ++r) pmax = fmaxf(pmax, p1[r]);
;   { auto rr = __builtin_amdgcn_permlane32_swap(__float_as_uint(pmax), __float_as_uint(pmax), false, false);
;     pmax = fmaxf(__uint_as_float(rr[0]), __uint_as_float(rr[1])); }
;   if (__builtin_expect(__all(pmax - m_reg <= THR / SCALE), 1)) { mn = m_reg; alpha = 1.f; }
;   else { mn = fmaxf(m_reg, pmax); alpha = __builtin_amdgcn_exp2f((m_reg - mn) * C); m_reg = mn; }
; __device__ __forceinline__ void attn_mla_dma(const bf16_t* __restrict__ Qb, const bf16_t* __restrict__ Kh, const bf16_t* __restrict__ Vh, bf16_t* __restrict__ Ob,
;                                              int seq, char* lds, const int tid) {
;     ...
;     pv_d0_t(o, vb0 + vprev * SHM_VV, pa0, pa1, pa2, pa3); partialSM<MLA>(pA0, pA1, m_reg, mnA, alA);
;     TILE_BAR();
;     RESC(alA);
	v_mfma_f32_32x32x16_bf16 v[48:63], v[204:207], v[144:147], v[48:63]
	ds_read_b64_tr_b16 v[204:205], v197 offset:0x400
	ds_read_b64_tr_b16 v[206:207], v197 offset:0xc00
	v_mfma_f32_32x32x16_bf16 v[48:63], v[208:211], v[148:151], v[48:63]
	ds_read_b64_tr_b16 v[208:209], v197 offset:0x1400
	ds_read_b64_tr_b16 v[210:211], v197 offset:0x1c00
	v_mfma_f32_32x32x16_bf16 v[48:63], v[212:215], v[170:173], v[48:63]
	ds_read_b64_tr_b16 v[212:213], v197 offset:0x2400
	ds_read_b64_tr_b16 v[214:215], v197 offset:0x2c00
	v_mfma_f32_32x32x16_bf16 v[48:63], v[216:219], v[200:203], v[48:63]
	ds_read_b64_tr_b16 v[216:217], v197 offset:0x3400
	ds_read_b64_tr_b16 v[218:219], v197 offset:0x3c00
	s_waitcnt lgkmcnt(0)
	v_mfma_f32_32x32x16_bf16 v[32:47], v[204:207], v[144:147], v[32:47]
	ds_read_b64_tr_b16 v[204:205], v197 offset:0x600
	ds_read_b64_tr_b16 v[206:207], v197 offset:0xe00
	v_mfma_f32_32x32x16_bf16 v[32:47], v[208:211], v[148:151], v[32:47]
	ds_read_b64_tr_b16 v[208:209], v197 offset:0x1600
	ds_read_b64_tr_b16 v[210:211], v197 offset:0x1e00
	v_mfma_f32_32x32x16_bf16 v[32:47], v[212:215], v[170:173], v[32:47]
	ds_read_b64_tr_b16 v[212:213], v197 offset:0x2600
	ds_read_b64_tr_b16 v[214:215], v197 offset:0x2e00
	v_mfma_f32_32x32x16_bf16 v[32:47], v[216:219], v[200:203], v[32:47]
	ds_read_b64_tr_b16 v[216:217], v197 offset:0x3600
	ds_read_b64_tr_b16 v[218:219], v197 offset:0x3e00
	s_waitcnt lgkmcnt(0)
	v_mfma_f32_32x32x16_bf16 v[16:31], v[204:207], v[144:147], v[16:31]
	v_max_f32_e32 v144, v80, v81
	v_max3_f32 v144, v144, v82, v83
	v_max3_f32 v144, v144, v84, v85
	v_max3_f32 v144, v144, v86, v87
	v_max3_f32 v144, v144, v88, v89
	v_max3_f32 v144, v144, v90, v91
	v_max3_f32 v144, v144, v92, v93
	v_mfma_f32_32x32x16_bf16 v[16:31], v[208:211], v[148:151], v[16:31]
	v_max3_f32 v144, v144, v94, v95
	v_max3_f32 v144, v144, v64, v65
	v_max3_f32 v144, v144, v66, v67
	v_max3_f32 v144, v144, v68, v69
	v_max3_f32 v144, v144, v70, v71
	v_max3_f32 v144, v144, v72, v73
	v_max3_f32 v144, v144, v74, v75
	v_max3_f32 v144, v144, v76, v77
	v_mfma_f32_32x32x16_bf16 v[16:31], v[212:215], v[170:173], v[16:31]
	v_max3_f32 v144, v144, v78, v79
	v_mov_b32_e32 v145, v144
	s_nop 1
	v_permlane32_swap_b32_e32 v144, v145
	v_max_f32_e32 v144, v144, v145
	v_sub_f32_e32 v145, v144, v153
	v_cmp_ge_f32_e32 vcc, s63, v145
	v_max_f32_e32 v145, v153, v153
	v_max_f32_e32 v145, v145, v144
	v_mfma_f32_32x32x16_bf16 v[16:31], v[216:219], v[200:203], v[16:31]
	v_sub_f32_e32 v144, v153, v145
	v_mul_f32_e32 v144, 0x3dd53b94, v144
	v_exp_f32_e32 v144, v144
	s_cmp_eq_u64 vcc, exec
	s_cselect_b64 s[4:5], -1, 0
	s_waitcnt vmcnt(0) lgkmcnt(0)
	v_cndmask_b32_e64 v144, v144, 1.0, s[4:5]
	v_cmp_gt_f32_e32 vcc, 1.0, v144
	s_barrier
	s_cbranch_vccz .LBB0_119
	v_pk_mul_f32 v[14:15], v[14:15], v[144:145] op_sel_hi:[1,0]
	v_pk_mul_f32 v[12:13], v[12:13], v[144:145] op_sel_hi:[1,0]
	v_pk_mul_f32 v[10:11], v[10:11], v[144:145] op_sel_hi:[1,0]
	v_pk_mul_f32 v[8:9], v[8:9], v[144:145] op_sel_hi:[1,0]
	v_pk_mul_f32 v[6:7], v[6:7], v[144:145] op_sel_hi:[1,0]
	v_pk_mul_f32 v[4:5], v[4:5], v[144:145] op_sel_hi:[1,0]
	v_pk_mul_f32 v[2:3], v[2:3], v[144:145] op_sel_hi:[1,0]
	v_pk_mul_f32 v[0:1], v[0:1], v[144:145] op_sel_hi:[1,0]
	v_pk_mul_f32 v[62:63], v[62:63], v[144:145] op_sel_hi:[1,0]
	v_pk_mul_f32 v[60:61], v[60:61], v[144:145] op_sel_hi:[1,0]
	v_pk_mul_f32 v[58:59], v[58:59], v[144:145] op_sel_hi:[1,0]
	v_pk_mul_f32 v[56:57], v[56:57], v[144:145] op_sel_hi:[1,0]
	v_pk_mul_f32 v[54:55], v[54:55], v[144:145] op_sel_hi:[1,0]
	v_pk_mul_f32 v[52:53], v[52:53], v[144:145] op_sel_hi:[1,0]
	v_pk_mul_f32 v[50:51], v[50:51], v[144:145] op_sel_hi:[1,0]
	v_pk_mul_f32 v[48:49], v[48:49], v[144:145] op_sel_hi:[1,0]
	v_pk_mul_f32 v[46:47], v[46:47], v[144:145] op_sel_hi:[1,0]
	v_pk_mul_f32 v[44:45], v[44:45], v[144:145] op_sel_hi:[1,0]
	v_pk_mul_f32 v[42:43], v[42:43], v[144:145] op_sel_hi:[1,0]
	v_pk_mul_f32 v[40:41], v[40:41], v[144:145] op_sel_hi:[1,0]
	v_pk_mul_f32 v[38:39], v[38:39], v[144:145] op_sel_hi:[1,0]
	v_pk_mul_f32 v[36:37], v[36:37], v[144:145] op_sel_hi:[1,0]
	v_pk_mul_f32 v[34:35], v[34:35], v[144:145] op_sel_hi:[1,0]
	v_pk_mul_f32 v[32:33], v[32:33], v[144:145] op_sel_hi:[1,0]
	v_pk_mul_f32 v[30:31], v[30:31], v[144:145] op_sel_hi:[1,0]
	v_pk_mul_f32 v[28:29], v[28:29], v[144:145] op_sel_hi:[1,0]
	v_pk_mul_f32 v[26:27], v[26:27], v[144:145] op_sel_hi:[1,0]
	v_pk_mul_f32 v[24:25], v[24:25], v[144:145] op_sel_hi:[1,0]
	v_pk_mul_f32 v[22:23], v[22:23], v[144:145] op_sel_hi:[1,0]
	v_pk_mul_f32 v[20:21], v[20:21], v[144:145] op_sel_hi:[1,0]
	v_pk_mul_f32 v[18:19], v[18:19], v[144:145] op_sel_hi:[1,0]
	v_pk_mul_f32 v[16:17], v[16:17], v[144:145] op_sel_hi:[1,0]

; #define SBAR() __builtin_amdgcn_sched_barrier(0)
; template <int BUFOFF>
; __device__ __forceinline__ void qkt_mla(f32x16& p0, f32x16& p1, const int* ka, const bf16x8* qr, const char* qlds) {
;   typedef __attribute__((address_space(3))) const bf16x8* lp;
;   p0 = f32x16{}; p1 = f32x16{};
; #pragma unroll
;   for (int d0 = 0; d0 < 12; ++d0) {
;     const int a = ka[d0 & 3] + (d0 >> 2) * 128 + BUFOFF;
;     const bf16x8 b0 = *(lp)(a), b1 = *(lp)(a + 12288);
;     bf16x8 qf;
;     qf = qr[d0];
;     p0 = __builtin_amdgcn_mfma_f32_32x32x16_bf16(b0, qf, p0, 0, 0, 0);
;     p1 = __builtin_amdgcn_mfma_f32_32x32x16_bf16(b1, qf, p1, 0, 0, 0);
;   }
; }
; __device__ __forceinline__ void attn_mla_dma(const bf16_t* __restrict__ Qb, const bf16_t* __restrict__ Kh, const bf16_t* __restrict__ Vh, bf16_t* __restrict__ Ob,
;                                              int seq, char* lds, const int tid) {
;     ...
;   SBAR(); qkt_mla<(int)SHM_K192>(pB0, pB1, ka, qr, qlds);
;   finishSM(pA0, pA1, alA, l_reg, pa0, pa1, pa2, pa3); SBAR();
;   pv_d0_t(o, vb0 + vprev * SHM_VV, pa0, pa1, pa2, pa3); partialSM<MLA>(pB0, pB1, m_reg, mnB, alB);
.LBB0_121:
	ds_read_b128 v[64:67], v169 offset:24576
	ds_read_b128 v[68:71], v169 offset:36864
	s_waitcnt lgkmcnt(0)
	v_mfma_f32_32x32x16_bf16 v[80:95], v[64:67], v[140:143], 0
	v_mfma_f32_32x32x16_bf16 v[64:79], v[68:71], v[140:143], 0
	ds_read_b128 v[140:143], v190 offset:24576
	ds_read_b128 v[214:217], v190 offset:36864
	s_waitcnt lgkmcnt(0)
	v_mfma_f32_32x32x16_bf16 v[80:95], v[140:143], v[136:139], v[80:95]
	v_mfma_f32_32x32x16_bf16 v[64:79], v[214:217], v[136:139], v[64:79]
	ds_read_b128 v[136:139], v193 offset:24576
	ds_read_b128 v[140:143], v193 offset:36864
	s_waitcnt lgkmcnt(0)
	v_mfma_f32_32x32x16_bf16 v[80:95], v[136:139], v[132:135], v[80:95]
	v_mfma_f32_32x32x16_bf16 v[64:79], v[140:143], v[132:135], v[64:79]
	ds_read_b128 v[132:135], v192 offset:24576
	ds_read_b128 v[136:139], v192 offset:36864
	s_waitcnt lgkmcnt(0)
	v_mfma_f32_32x32x16_bf16 v[80:95], v[132:135], v[128:131], v[80:95]
	v_mfma_f32_32x32x16_bf16 v[64:79], v[136:139], v[128:131], v[64:79]
	ds_read_b128 v[128:131], v169 offset:24704
	ds_read_b128 v[132:135], v169 offset:36992
	s_waitcnt lgkmcnt(0)
	v_mfma_f32_32x32x16_bf16 v[80:95], v[128:131], v[124:127], v[80:95]
	v_mfma_f32_32x32x16_bf16 v[64:79], v[132:135], v[124:127], v[64:79]
	ds_read_b128 v[124:127], v190 offset:24704
	ds_read_b128 v[128:131], v190 offset:36992
	s_waitcnt lgkmcnt(0)
	v_mfma_f32_32x32x16_bf16 v[80:95], v[124:127], v[120:123], v[80:95]
	v_mfma_f32_32x32x16_bf16 v[64:79], v[128:131], v[120:123], v[64:79]
	ds_read_b128 v[120:123], v193 offset:24704
	ds_read_b128 v[124:127], v193 offset:36992
	s_waitcnt lgkmcnt(0)
	v_mfma_f32_32x32x16_bf16 v[80:95], v[120:123], v[116:119], v[80:95]
	v_mfma_f32_32x32x16_bf16 v[64:79], v[124:127], v[116:119], v[64:79]
	ds_read_b128 v[116:119], v192 offset:24704
	ds_read_b128 v[120:123], v192 offset:36992
	s_waitcnt lgkmcnt(0)
	v_mfma_f32_32x32x16_bf16 v[80:95], v[116:119], v[112:115], v[80:95]
	v_mfma_f32_32x32x16_bf16 v[64:79], v[120:123], v[112:115], v[64:79]
	ds_read_b128 v[112:115], v169 offset:24832
	ds_read_b128 v[116:119], v169 offset:37120
	v_exp_f32_e32 v120, v154
	v_exp_f32_e32 v121, v155
	s_waitcnt lgkmcnt(0)
	v_mfma_f32_32x32x16_bf16 v[80:95], v[112:115], v[108:111], v[80:95]
	v_mfma_f32_32x32x16_bf16 v[64:79], v[116:119], v[108:111], v[64:79]
	ds_read_b128 v[108:111], v190 offset:24832
	ds_read_b128 v[112:115], v190 offset:37120
	v_exp_f32_e32 v116, v148
	v_exp_f32_e32 v117, v149
	v_exp_f32_e32 v118, v146
	v_exp_f32_e32 v119, v147
	s_waitcnt lgkmcnt(0)
	v_mfma_f32_32x32x16_bf16 v[80:95], v[108:111], v[104:107], v[80:95]
	v_mfma_f32_32x32x16_bf16 v[64:79], v[112:115], v[104:107], v[64:79]
	ds_read_b128 v[104:107], v193 offset:24832
	ds_read_b128 v[108:111], v193 offset:37120
	v_exp_f32_e32 v112, v152
	v_exp_f32_e32 v113, v153
	v_exp_f32_e32 v114, v150
	v_exp_f32_e32 v115, v151
	s_waitcnt lgkmcnt(0)
	v_mfma_f32_32x32x16_bf16 v[80:95], v[104:107], v[100:103], v[80:95]
	v_mfma_f32_32x32x16_bf16 v[64:79], v[108:111], v[100:103], v[64:79]
	ds_read_b128 v[100:103], v192 offset:24832
	ds_read_b128 v[104:107], v192 offset:37120
	v_exp_f32_e32 v108, v170
	v_exp_f32_e32 v109, v171
	v_exp_f32_e32 v110, v158
	v_exp_f32_e32 v111, v159
	s_waitcnt lgkmcnt(0)
	v_mfma_f32_32x32x16_bf16 v[80:95], v[100:103], v[96:99], v[80:95]
	v_mfma_f32_32x32x16_bf16 v[64:79], v[104:107], v[96:99], v[64:79]
	v_add_f32_e32 v96, 0, v145
	v_add_f32_e32 v96, v210, v96
	v_add_f32_e32 v96, v208, v96
	v_add_f32_e32 v96, v212, v96
	v_add_f32_e32 v96, v211, v96
	v_add_f32_e32 v96, v213, v96
	v_add_f32_e32 v96, v207, v96
	v_add_f32_e32 v96, v209, v96
	v_add_f32_e32 v96, v200, v96
	v_add_f32_e32 v96, v203, v96
	v_add_f32_e32 v96, v202, v96
	v_add_f32_e32 v96, v205, v96
	v_exp_f32_e32 v106, v172
	v_add_f32_e32 v96, v199, v96
	v_exp_f32_e32 v107, v173
	v_add_f32_e32 v96, v201, v96
	v_add_f32_e32 v96, v204, v96
	v_add_f32_e32 v96, v206, v96
	v_add_f32_e32 v96, v106, v96
	v_add_f32_e32 v96, v107, v96
	v_add_f32_e32 v96, v108, v96
	v_add_f32_e32 v96, v109, v96
	v_add_f32_e32 v96, v110, v96
	v_add_f32_e32 v96, v111, v96
	v_add_f32_e32 v96, v112, v96
	v_add_f32_e32 v96, v113, v96
	v_add_f32_e32 v96, v114, v96
	v_add_f32_e32 v96, v115, v96
	v_add_f32_e32 v96, v116, v96
	v_add_f32_e32 v96, v117, v96
	v_add_f32_e32 v96, v118, v96
	v_add_f32_e32 v96, v119, v96
	v_add_f32_e32 v96, v120, v96
	v_add_f32_e32 v100, v121, v96
	v_mov_b32_e32 v101, v100
	v_cvt_pk_bf16_f32 v96, v145, v210
	v_cvt_pk_bf16_f32 v97, v208, v212
	v_cvt_pk_bf16_f32 v98, v211, v213
	v_cvt_pk_bf16_f32 v99, v207, v209
	s_nop 1
	v_permlane32_swap_b32_e32 v100, v101
	v_cvt_pk_bf16_f32 v102, v200, v203
	v_cvt_pk_bf16_f32 v103, v202, v205
	v_cvt_pk_bf16_f32 v104, v199, v201
	v_cvt_pk_bf16_f32 v105, v204, v206
	v_cvt_pk_bf16_f32 v106, v106, v107
	v_cvt_pk_bf16_f32 v107, v108, v109
	v_cvt_pk_bf16_f32 v108, v110, v111
	v_cvt_pk_bf16_f32 v109, v112, v113
	v_cvt_pk_bf16_f32 v110, v114, v115
	v_cvt_pk_bf16_f32 v111, v116, v117
	v_cvt_pk_bf16_f32 v112, v118, v119
	v_cvt_pk_bf16_f32 v113, v120, v121
	s_nop 0
	v_add_u32_e32 v130, s52, v167
	ds_read_b64_tr_b16 v[114:115], v130 offset:0
	ds_read_b64_tr_b16 v[116:117], v130 offset:0x800
	ds_read_b64_tr_b16 v[118:119], v130 offset:0x1000
	ds_read_b64_tr_b16 v[120:121], v130 offset:0x1800
	ds_read_b64_tr_b16 v[122:123], v130 offset:0x2000
	ds_read_b64_tr_b16 v[124:125], v130 offset:0x2800
	ds_read_b64_tr_b16 v[126:127], v130 offset:0x3000
	ds_read_b64_tr_b16 v[128:129], v130 offset:0x3800
	s_waitcnt lgkmcnt(0)
; #define RESC(a) do { if (__any((a) < 1.f)) { if (hi == 0) al_l[r32] = (a); asm volatile("s_waitcnt lgkmcnt(0)" ::: "memory"); \
;     for (int d = 0; d < 4; ++d) for (int r = 0; r < 16; ++r) o[d][r] *= al_l[crow_(r, hi)]; } } while (0)
; #define RESC(a) do { if (__any((a) < 1.f)) { for (int d = 0; d < 4; ++d) for (int r = 0; r < 16; ++r) o[d][r] *= (a); } } while (0)
; #define RESC(a) do { if (__any((a) < 1.f)) { for (int d = 0; d < 4; ++d) for (int r = 0; r < 16; ++r) o[d][r] *= (a); } } while (0)
; template <int MLA>
; __device__ __forceinline__ void partialSM(f32x16& p0, f32x16& p1, float& m_reg, float& mn, float& alpha) {
;   constexpr float SCALE = AttC<MLA>::SCALE;
;   constexpr float C = SCALE * 1.4426950408889634f;
;   float pmax = p0[0];
; #pragma unroll
;   for (int r = 1; r < 16; ++r) pmax = fmaxf(pmax, p0[r]);
; #pragma unroll
;   for (int r = 0; r < 16; ++r) pmax = fmaxf(pmax, p1[r]);
;   { auto rr = __builtin_amdgcn_permlane32_swap(__float_as_uint(pmax), __float_as_uint(pmax), false, false);
;     pmax = fmaxf(__uint_as_float(rr[0]), __uint_as_float(rr[1])); }
;   if (__builtin_expect(__all(pmax - m_reg <= THR / SCALE), 1)) { mn = m_reg; alpha = 1.f; }
;   else { mn = fmaxf(m_reg, pmax); alpha = __builtin_amdgcn_exp2f((m_reg - mn) * C); m_reg = mn; }
; __device__ __forceinline__ void attn_mla_dma(const bf16_t* __restrict__ Qb, const bf16_t* __restrict__ Kh, const bf16_t* __restrict__ Vh, bf16_t* __restrict__ Ob,
;                                              int seq, char* lds, const int tid) {
;     ...
;   pv_d0_t(o, vb0 + vprev * SHM_VV, pa0, pa1, pa2, pa3); partialSM<MLA>(pB0, pB1, m_reg, mnB, alB);
;   RESC(alB);
	s_nop 0
	v_mfma_f32_32x32x16_bf16 v[0:15], v[114:117], v[96:99], v[0:15]
	ds_read_b64_tr_b16 v[114:115], v130 offset:0x200
	ds_read_b64_tr_b16 v[116:117], v130 offset:0xa00
	v_mfma_f32_32x32x16_bf16 v[0:15], v[118:121], v[102:105], v[0:15]
	ds_read_b64_tr_b16 v[118:119], v130 offset:0x1200
	ds_read_b64_tr_b16 v[120:121], v130 offset:0x1a00
	v_mfma_f32_32x32x16_bf16 v[0:15], v[122:125], v[106:109], v[0:15]
	ds_read_b64_tr_b16 v[122:123], v130 offset:0x2200
	ds_read_b64_tr_b16 v[124:125], v130 offset:0x2a00
	v_mfma_f32_32x32x16_bf16 v[0:15], v[126:129], v[110:113], v[0:15]
	ds_read_b64_tr_b16 v[126:127], v130 offset:0x3200
	ds_read_b64_tr_b16 v[128:129], v130 offset:0x3a00
	s_waitcnt lgkmcnt(0)
	v_mfma_f32_32x32x16_bf16 v[48:63], v[114:117], v[96:99], v[48:63]
	ds_read_b64_tr_b16 v[114:115], v130 offset:0x400
	ds_read_b64_tr_b16 v[116:117], v130 offset:0xc00
	v_mfma_f32_32x32x16_bf16 v[48:63], v[118:121], v[102:105], v[48:63]
	ds_read_b64_tr_b16 v[118:119], v130 offset:0x1400
	ds_read_b64_tr_b16 v[120:121], v130 offset:0x1c00
	v_mfma_f32_32x32x16_bf16 v[48:63], v[122:125], v[106:109], v[48:63]
	ds_read_b64_tr_b16 v[122:123], v130 offset:0x2400
	ds_read_b64_tr_b16 v[124:125], v130 offset:0x2c00
	v_mfma_f32_32x32x16_bf16 v[48:63], v[126:129], v[110:113], v[48:63]
	ds_read_b64_tr_b16 v[126:127], v130 offset:0x3400
	ds_read_b64_tr_b16 v[128:129], v130 offset:0x3c00
	s_waitcnt lgkmcnt(0)
	v_mfma_f32_32x32x16_bf16 v[32:47], v[114:117], v[96:99], v[32:47]
	ds_read_b64_tr_b16 v[114:115], v130 offset:0x600
	ds_read_b64_tr_b16 v[116:117], v130 offset:0xe00
	v_mfma_f32_32x32x16_bf16 v[32:47], v[118:121], v[102:105], v[32:47]
	ds_read_b64_tr_b16 v[118:119], v130 offset:0x1600
	ds_read_b64_tr_b16 v[120:121], v130 offset:0x1e00
	v_mfma_f32_32x32x16_bf16 v[32:47], v[122:125], v[106:109], v[32:47]
	ds_read_b64_tr_b16 v[122:123], v130 offset:0x2600
	ds_read_b64_tr_b16 v[124:125], v130 offset:0x2e00
	v_mfma_f32_32x32x16_bf16 v[32:47], v[126:129], v[110:113], v[32:47]
	ds_read_b64_tr_b16 v[126:127], v130 offset:0x3600
	ds_read_b64_tr_b16 v[128:129], v130 offset:0x3e00
	s_waitcnt lgkmcnt(0)
	v_mfma_f32_32x32x16_bf16 v[16:31], v[114:117], v[96:99], v[16:31]
	v_max_f32_e32 v96, v81, v81
	v_max_f32_e32 v97, v80, v80
	v_max_f32_e32 v96, v97, v96
	v_max3_f32 v96, v96, v82, v83
	v_max3_f32 v96, v96, v84, v85
	v_max3_f32 v96, v96, v86, v87
	v_max3_f32 v96, v96, v88, v89
	v_max3_f32 v96, v96, v90, v91
	v_max3_f32 v96, v96, v92, v93
	v_mfma_f32_32x32x16_bf16 v[16:31], v[118:121], v[102:105], v[16:31]
	v_max3_f32 v96, v96, v94, v95
	v_max3_f32 v96, v96, v64, v65
	v_max3_f32 v96, v96, v66, v67
	v_max3_f32 v96, v96, v68, v69
	v_max3_f32 v96, v96, v70, v71
	v_max3_f32 v96, v96, v72, v73
	v_max3_f32 v96, v96, v74, v75
	v_max3_f32 v96, v96, v76, v77
	v_mfma_f32_32x32x16_bf16 v[16:31], v[122:125], v[106:109], v[16:31]
	v_max3_f32 v96, v96, v78, v79
	v_mov_b32_e32 v97, v96
	s_nop 1
	v_permlane32_swap_b32_e32 v96, v97
	v_max_f32_e32 v97, v97, v97
	v_max_f32_e32 v96, v96, v96
	v_max_f32_e32 v96, v96, v97
	v_sub_f32_e32 v97, v96, v197
	v_cmp_ge_f32_e32 vcc, s63, v97
	v_max_f32_e32 v97, v197, v197
	v_max_f32_e32 v97, v97, v96
	v_mfma_f32_32x32x16_bf16 v[16:31], v[126:129], v[110:113], v[16:31]
	v_sub_f32_e32 v96, v197, v97
	v_mul_f32_e32 v96, 0x3dd53b94, v96
	v_exp_f32_e32 v96, v96
	s_cmp_eq_u64 vcc, exec
	s_cselect_b64 s[4:5], -1, 0
	v_cndmask_b32_e64 v96, v96, 1.0, s[4:5]
	v_cmp_gt_f32_e32 vcc, 1.0, v96
	s_cbranch_vccz .LBB0_113
	v_pk_mul_f32 v[14:15], v[14:15], v[96:97] op_sel_hi:[1,0]
	v_pk_mul_f32 v[12:13], v[12:13], v[96:97] op_sel_hi:[1,0]
	v_pk_mul_f32 v[10:11], v[10:11], v[96:97] op_sel_hi:[1,0]
	v_pk_mul_f32 v[8:9], v[8:9], v[96:97] op_sel_hi:[1,0]
	v_pk_mul_f32 v[6:7], v[6:7], v[96:97] op_sel_hi:[1,0]
	v_pk_mul_f32 v[4:5], v[4:5], v[96:97] op_sel_hi:[1,0]
	v_pk_mul_f32 v[2:3], v[2:3], v[96:97] op_sel_hi:[1,0]
	v_pk_mul_f32 v[0:1], v[0:1], v[96:97] op_sel_hi:[1,0]
	v_pk_mul_f32 v[62:63], v[62:63], v[96:97] op_sel_hi:[1,0]
	v_pk_mul_f32 v[60:61], v[60:61], v[96:97] op_sel_hi:[1,0]
	v_pk_mul_f32 v[58:59], v[58:59], v[96:97] op_sel_hi:[1,0]
	v_pk_mul_f32 v[56:57], v[56:57], v[96:97] op_sel_hi:[1,0]
	v_pk_mul_f32 v[54:55], v[54:55], v[96:97] op_sel_hi:[1,0]
	v_pk_mul_f32 v[52:53], v[52:53], v[96:97] op_sel_hi:[1,0]
	v_pk_mul_f32 v[50:51], v[50:51], v[96:97] op_sel_hi:[1,0]
	v_pk_mul_f32 v[48:49], v[48:49], v[96:97] op_sel_hi:[1,0]
	v_pk_mul_f32 v[46:47], v[46:47], v[96:97] op_sel_hi:[1,0]
	v_pk_mul_f32 v[44:45], v[44:45], v[96:97] op_sel_hi:[1,0]
	v_pk_mul_f32 v[42:43], v[42:43], v[96:97] op_sel_hi:[1,0]
	v_pk_mul_f32 v[40:41], v[40:41], v[96:97] op_sel_hi:[1,0]
	v_pk_mul_f32 v[38:39], v[38:39], v[96:97] op_sel_hi:[1,0]
	v_pk_mul_f32 v[36:37], v[36:37], v[96:97] op_sel_hi:[1,0]
	v_pk_mul_f32 v[34:35], v[34:35], v[96:97] op_sel_hi:[1,0]
	v_pk_mul_f32 v[32:33], v[32:33], v[96:97] op_sel_hi:[1,0]
	v_pk_mul_f32 v[30:31], v[30:31], v[96:97] op_sel_hi:[1,0]
	v_pk_mul_f32 v[28:29], v[28:29], v[96:97] op_sel_hi:[1,0]
	v_pk_mul_f32 v[26:27], v[26:27], v[96:97] op_sel_hi:[1,0]
	v_pk_mul_f32 v[24:25], v[24:25], v[96:97] op_sel_hi:[1,0]
	v_pk_mul_f32 v[22:23], v[22:23], v[96:97] op_sel_hi:[1,0]
	v_pk_mul_f32 v[20:21], v[20:21], v[96:97] op_sel_hi:[1,0]
	v_pk_mul_f32 v[18:19], v[18:19], v[96:97] op_sel_hi:[1,0]
	v_pk_mul_f32 v[16:17], v[16:17], v[96:97] op_sel_hi:[1,0]
	s_branch .LBB0_113

; __device__ __forceinline__ int v_rd_base(int lane) { return ((lane & 3) << 3) | (((lane >> 2) & 3) << 6) | (((lane >> 4) & 1) << 5) | (((lane >> 5) & 1) << 8); }
; __device__ __forceinline__ bf16x8 ld8(const bf16_t* p) { return gld8(p); }
; #define TILE_BAR() do { asm volatile("s_waitcnt vmcnt(0) lgkmcnt(0)" ::: "memory"); __builtin_amdgcn_s_barrier(); } while (0)
; __device__ __forceinline__ void attn_diff_dma(const bf16_t* __restrict__ Qb, const bf16_t* __restrict__ Kh, const bf16_t* __restrict__ Vh, bf16_t* __restrict__ Ob,
;                                               int seq, char* lds, float lam, const float* __restrict__ gsub, const int tid) {
;     ...
;   const int wid = tid >> 6, lane = tid & 63, r32 = lane & 31, hi = lane >> 5;
;   const int comp = wid >> 2, wrow = wid & 3;
;   const int wu = __builtin_amdgcn_readfirstlane(wid);
;   char* V_lds = lds; char* K_lds = lds + 3 * SHM_VV;
;   float* wsl = (float*)(lds + 3 * SHM_VV + 2 * SHM_K) + wid * 64; float* li_l = wsl; float* al_l = wsl + 32;
;   float m_reg = -1e30f, l_reg = 0; f32x16 o[4] = {}; bf16x8 qr[4];
;   const bf16_t* Qw = Qb + (long)(wrow * QBLK + r32) * LD + comp * 64 + hi * 8;
; #pragma unroll
;   for (int d0 = 0; d0 < 4; ++d0) qr[d0] = ld8(Qw + d0 * 16);
;   unsigned kof[2], vof[2];
; #pragma unroll
;   for (int i = 0; i < 2; ++i) { const int ob = (i * 8 + wid) * 1024 + lane * 16, row = ob >> 8, within = ob & 255;
;     kof[i] = (unsigned)(row * (LD * 2) + (within ^ ((row & 7) << 4))); }
; #pragma unroll
;   for (int i = 0; i < 2; ++i) { const int ob = (i * 8 + wid) * 1024 + lane * 16, st = ob >> 9, sw = (ob & 511) >> 1;
;     const int kk = (st >> 2) * 8 + (sw >> 5), c = (st & 3) * 32 + (sw & 31);
;     const int k = (kk & ~0xC) | ((kk & 4) << 1) | ((kk & 8) >> 1);
;     vof[i] = (unsigned)(k * (LD * 2) + c * 2); }
;   const int vb0 = (int)(uintptr_t)V_lds + v_rd_base(lane);
;   int ka[4];
; #pragma unroll
;   for (int q = 0; q < 4; ++q) ka[q] = (int)(uintptr_t)K_lds + r32 * 256 + comp * 128 + ((q * 32 + hi * 16) ^ ((r32 & 7) << 4));
;     ...
;   f32x16 pA0, pA1, pB0, pB1; float mnA, mnB, alA, alB; bf16x8 pa0, pa1, pa2, pa3; const int NT = seq / KVBLK;
;   DMA_TILE(0, 0, 0); TILE_BAR();
;   qkt_diff<0>(pA0, pA1, ka, qr); partialSM<0>(pA0, pA1, m_reg, mnA, alA);
;   DMA_TILE(KVBLK, 1, 1); TILE_BAR();
.LBB0_128:
	s_lshl_b32 s4, s31, 1
	s_ashr_i32 s5, s40, 3
	s_and_b32 s50, s4, 0x700
	s_bfe_u32 s4, s40, 0x50003
	s_andn2_b32 s5, s5, 31
	s_or_b32 s5, s4, s5
	s_abs_i32 s12, s5
	s_mul_hi_u32 s13, s12, s35
	s_mul_i32 s14, s13, s30
	s_ashr_i32 s4, s40, 31
	s_sub_i32 s12, s12, s14
	s_xor_b32 s4, s4, s34
	s_add_i32 s14, s13, 1
	s_sub_i32 s15, s12, s30
	s_cmp_ge_u32 s12, s30
	s_cselect_b32 s13, s14, s13
	s_cselect_b32 s12, s15, s12
	s_add_i32 s14, s13, 1
	s_cmp_ge_u32 s12, s30
	s_cselect_b32 s12, s14, s13
	s_xor_b32 s12, s12, s4
	s_sub_i32 s4, s12, s4
	s_mul_i32 s12, s4, s29
	s_sub_i32 s12, s5, s12
	s_ashr_i32 s5, s4, 31
	s_lshl_b64 s[4:5], s[4:5], s18
	s_ashr_i32 s13, s12, 31
	s_lshl_b64 s[12:13], s[12:13], 17
	s_lshl_b64 s[14:15], s[4:5], 10
	s_add_u32 s12, s12, s14
	s_addc_u32 s13, s13, s15
	s_lshl_b64 s[12:13], s[12:13], 1
	s_add_u32 s14, s20, s12
	v_mov_b32_e32 v130, v168
	s_addc_u32 s15, s21, s13
	s_lshl_b32 s16, s40, 7
	s_and_b32 s41, s16, 0x380
	v_ashrrev_i32_e32 v4, 6, v130
	s_lshl_b32 s16, s41, 1
	v_and_b32_e32 v6, 31, v130
	v_lshlrev_b32_e32 v0, 5, v4
	s_movk_i32 s57, 0x60
	s_add_u32 s42, s14, s16
	v_ashrrev_i32_e32 v7, 8, v130
	v_and_or_b32 v0, v0, s57, v6
	s_addc_u32 s43, s15, 0
	v_lshlrev_b32_e32 v162, 11, v0
	v_lshlrev_b32_e32 v2, 6, v7
	v_lshl_add_u64 v[0:1], s[42:43], 0, v[162:163]
	v_ashrrev_i32_e32 v3, 31, v2
	v_lshl_add_u64 v[0:1], v[2:3], 1, v[0:1]
	v_lshrrev_b32_e32 v2, 1, v130
	v_and_b32_e32 v162, 16, v2
	v_lshl_add_u64 v[0:1], v[0:1], 0, v[162:163]
	global_load_dwordx4 v[108:111], v[0:1], off
	global_load_dwordx4 v[104:107], v[0:1], off offset:32
	global_load_dwordx4 v[100:103], v[0:1], off offset:64
	global_load_dwordx4 v[96:99], v[0:1], off offset:96
	v_and_b32_e32 v5, 63, v130
	v_lshlrev_b32_e32 v0, 10, v4
	v_lshlrev_b32_e32 v40, 4, v5
	v_or_b32_e32 v1, v0, v40
	v_ashrrev_i32_e32 v8, 8, v1
	s_lshl_b64 s[4:5], s[4:5], 11
	v_lshlrev_b32_e32 v9, 11, v8
	v_lshlrev_b32_e32 v8, 4, v8
	v_add_u32_e32 v1, 0x2000, v1
	s_add_u32 s14, s23, s4
	v_and_b32_e32 v3, 0xf0, v40
	v_and_b32_e32 v8, 0x70, v8
	v_ashrrev_i32_e32 v1, 8, v1
	s_addc_u32 s15, s24, s5
	v_bitop3_b32 v134, v8, v9, v3 bitop3:0xde
	v_lshlrev_b32_e32 v8, 11, v1
	v_lshlrev_b32_e32 v1, 4, v1
	s_add_u32 s14, s14, s16
	v_and_b32_e32 v1, 0x70, v1
	v_lshlrev_b32_e32 v41, 3, v5
	v_ashrrev_i32_e32 v5, 8, v0
	s_addc_u32 s15, s15, 0
	v_bitop3_b32 v135, v1, v8, v3 bitop3:0xde
	v_bfe_u32 v1, v130, 2, 2
	v_and_b32_e32 v42, 24, v41
	v_and_b32_e32 v8, 0x1ffff0, v5
	v_lshrrev_b32_e32 v5, 1, v5
	s_add_u32 s17, s25, s4
	v_and_or_b32 v3, v130, s57, v42
	v_and_or_b32 v1, v2, 8, v1
	v_and_b32_e32 v5, 4, v5
	v_add_u32_e32 v0, 0x2000, v0
	s_addc_u32 s44, s26, s5
	v_lshlrev_b32_e32 v3, 1, v3
	v_or3_b32 v5, v8, v5, v1
	v_ashrrev_i32_e32 v0, 8, v0
	s_add_u32 s16, s17, s16
	v_lshl_or_b32 v136, v5, 11, v3
	v_and_b32_e32 v5, 0x1ffff0, v0
	v_lshrrev_b32_e32 v0, 1, v0
	s_addc_u32 s17, s44, 0
	v_and_b32_e32 v0, 4, v0
	s_add_i32 s42, 0, 0xc000
	v_or3_b32 v0, v5, v0, v1
	s_cmp_lg_u32 s42, -1
	v_lshl_or_b32 v137, v0, 11, v3
	v_lshlrev_b32_e32 v0, 8, v6
	s_cselect_b32 s42, s42, 0
	v_lshlrev_b32_e32 v1, 7, v7
	v_add3_u32 v43, v0, s42, v1
	v_readfirstlane_b32 s42, v4
	s_cmp_lg_u32 0, -1
	v_lshlrev_b32_e32 v0, 4, v130
	s_cselect_b32 s56, 0, 0
	s_lshl_b32 s42, s42, 10
	v_and_b32_e32 v44, 0x70, v0
	s_add_i32 s42, s42, 0
	v_bitop3_b32 v0, v2, v44, 16 bitop3:0x6c
	s_add_i32 s43, s42, 0xc000
	v_bfe_u32 v244, v160, 2, 1
	v_bfe_u32 v245, v160, 3, 1
	v_xor_b32_e32 v243, v244, v245
	v_sub_u32_e32 v242, v244, v245
	v_lshlrev_b32_e32 v242, 10, v242
	v_lshlrev_b32_e32 v243, 6, v243
	v_add_u32_e32 v138, v43, v0
	v_xor_b32_e32 v138, v138, v243
	v_add_u32_e32 v138, v138, v242
	s_mov_b64 s[52:53], s[14:15]
	s_mov_b64 s[54:55], s[16:17]
	v_mov_b32_e32 v0, v137
	v_mov_b32_e32 v1, v134
	v_mov_b32_e32 v2, v136
	v_mov_b32_e32 v3, v135
	s_mov_b32 m0, s43
	s_add_i32 s44, s42, 0xe000
	v_bitop3_b32 v20, v162, v44, 32 bitop3:0x36
	global_load_lds_dwordx4 v1, s[52:53]
	s_mov_b32 m0, s44
	v_add_u32_e32 v141, v20, v43
	v_xor_b32_e32 v141, v141, v243
	v_add_u32_e32 v141, v141, v242
	global_load_lds_dwordx4 v3, s[52:53]
	s_mov_b32 m0, s42
	s_mov_b32 s52, 0
	global_load_lds_dwordx4 v2, s[54:55]
	s_add_i32 m0, s42, 0x2000
	s_mov_b32 s53, s52
	global_load_lds_dwordx4 v0, s[54:55]
	s_waitcnt vmcnt(0) lgkmcnt(0)
	s_barrier
; #define TILE_BAR() do { asm volatile("s_waitcnt vmcnt(0) lgkmcnt(0)" ::: "memory"); __builtin_amdgcn_s_barrier(); } while (0)
; #define TILE_BAR() do { asm volatile("s_waitcnt vmcnt(0) lgkmcnt(0)" ::: "memory"); __builtin_amdgcn_s_barrier(); } while (0)
; template <int BUFOFF>
; __device__ __forceinline__ void qkt_diff(f32x16& p0, f32x16& p1, const int* ka, const bf16x8* qr) {
;   typedef __attribute__((address_space(3))) const bf16x8* lp;
;   p0 = f32x16{}; p1 = f32x16{};
; #pragma unroll
;   for (int d0 = 0; d0 < 4; ++d0) {
;     const int a = ka[d0] + BUFOFF;
;     const bf16x8 b0 = *(lp)(a), b1 = *(lp)(a + 8192);
;     p0 = __builtin_amdgcn_mfma_f32_32x32x16_bf16(b0, qr[d0], p0, 0, 0, 0);
;     p1 = __builtin_amdgcn_mfma_f32_32x32x16_bf16(b1, qr[d0], p1, 0, 0, 0);
;   }
; }
; __device__ __forceinline__ void attn_diff_dma(const bf16_t* __restrict__ Qb, const bf16_t* __restrict__ Kh, const bf16_t* __restrict__ Vh, bf16_t* __restrict__ Ob,
;                                               int seq, char* lds, float lam, const float* __restrict__ gsub, const int tid) {
;     ...
;   DMA_TILE(0, 0, 0); TILE_BAR();
;   qkt_diff<0>(pA0, pA1, ka, qr); partialSM<0>(pA0, pA1, m_reg, mnA, alA);
;   DMA_TILE(KVBLK, 1, 1); TILE_BAR();
	ds_read_b128 v[0:3], v138
	ds_read_b128 v[16:19], v138 offset:8192
	s_waitcnt vmcnt(0) lgkmcnt(0)
	v_mfma_f32_32x32x16_bf16 v[0:15], v[0:3], v[108:111], 0
	ds_read_b128 v[32:35], v141
	ds_read_b128 v[36:39], v141 offset:8192
	s_add_u32 s14, s14, 0x20000
	s_mov_b32 s54, s52
	s_mov_b32 s55, s52
	s_mov_b32 s58, s52
	s_mov_b32 s59, s52
	s_mov_b32 s60, s52
	v_mfma_f32_32x32x16_bf16 v[16:31], v[16:19], v[108:111], 0
	s_mov_b32 s61, s52
	s_mov_b32 s62, s52
	s_mov_b32 s63, s52
	s_mov_b32 s64, s52
	s_mov_b32 s65, s52
	s_mov_b32 s66, s52
	s_mov_b32 s67, s52
	s_waitcnt lgkmcnt(1)
	v_mfma_f32_32x32x16_bf16 v[0:15], v[32:35], v[104:107], v[0:15]
	v_bitop3_b32 v32, v162, v44, 64 bitop3:0x36
	v_add_u32_e32 v140, v32, v43
	v_xor_b32_e32 v140, v140, v243
	v_add_u32_e32 v140, v140, v242
	ds_read_b128 v[32:35], v140
	s_addc_u32 s15, s15, 0
	v_mov_b32_e32 v52, v136
	s_mov_b32 s47, 1
	v_mov_b32_e32 v131, 0
	s_waitcnt lgkmcnt(1)
	v_mfma_f32_32x32x16_bf16 v[16:31], v[36:39], v[104:107], v[16:31]
	v_lshlrev_b32_e32 v36, 1, v130
	v_and_b32_e32 v36, 32, v36
	v_and_or_b32 v36, v40, s48, v36
	v_and_b32_e32 v37, 0x100, v41
	v_or3_b32 v40, v36, v37, v42
	ds_read_b128 v[36:39], v140 offset:8192
	v_add_u32_e32 v133, s56, v40
	s_waitcnt lgkmcnt(1)
	v_mfma_f32_32x32x16_bf16 v[0:15], v[32:35], v[100:103], v[0:15]
	v_bitop3_b32 v32, v162, v44, s57 bitop3:0x36
	v_add_u32_e32 v139, v32, v43
	v_xor_b32_e32 v139, v139, v243
	v_add_u32_e32 v139, v139, v242
	ds_read_b128 v[32:35], v139
	ds_read_b128 v[48:51], v139 offset:8192
	s_mov_b32 s56, s52
	s_mov_b32 s57, s52
	s_waitcnt lgkmcnt(2)
	v_mfma_f32_32x32x16_bf16 v[16:31], v[36:39], v[100:103], v[16:31]
	s_waitcnt lgkmcnt(1)
	v_mfma_f32_32x32x16_bf16 v[0:15], v[32:35], v[96:99], v[0:15]
	v_mov_b64_e32 v[32:33], s[52:53]
	v_mov_b64_e32 v[34:35], s[54:55]
	v_mov_b64_e32 v[36:37], s[56:57]
	v_mov_b64_e32 v[38:39], s[58:59]
	v_mov_b64_e32 v[40:41], s[60:61]
	v_mov_b64_e32 v[42:43], s[62:63]
	v_mov_b64_e32 v[44:45], s[64:65]
	v_mov_b64_e32 v[46:47], s[66:67]
	s_add_u32 s54, s16, 0x20000
	s_waitcnt lgkmcnt(0)
	v_mfma_f32_32x32x16_bf16 v[16:31], v[48:51], v[96:99], v[16:31]
	s_nop 0
	v_max_f32_e32 v48, v1, v1
	v_max_f32_e32 v49, v0, v0
	s_addc_u32 s55, s17, 0
	s_add_i32 s16, s42, 0x10000
	v_max_f32_e32 v48, v49, v48
	v_mov_b32_e32 v49, v135
	v_mov_b32_e32 v50, v137
	v_mov_b32_e32 v51, v134
	s_mov_b32 m0, s16
	s_add_i32 s17, s42, 0x12000
	s_add_i32 s53, s42, 0x4000
	v_max3_f32 v48, v48, v2, v3
	global_load_lds_dwordx4 v51, s[14:15]
	s_mov_b32 m0, s17
	v_max3_f32 v48, v48, v4, v5
	global_load_lds_dwordx4 v49, s[14:15]
	s_mov_b32 m0, s53
	v_max3_f32 v48, v48, v6, v7
	global_load_lds_dwordx4 v52, s[54:55]
	s_add_i32 m0, s42, 0x6000
	v_max3_f32 v48, v48, v8, v9
	global_load_lds_dwordx4 v50, s[54:55]
	v_max3_f32 v48, v48, v10, v11
	v_max3_f32 v48, v48, v12, v13
	v_max3_f32 v48, v48, v14, v15
	v_max3_f32 v48, v48, v16, v17
	v_max3_f32 v48, v48, v18, v19
	v_max3_f32 v48, v48, v20, v21
	v_max3_f32 v48, v48, v22, v23
	v_max3_f32 v48, v48, v24, v25
	v_max3_f32 v48, v48, v26, v27
	v_max3_f32 v48, v48, v28, v29
	v_max3_f32 v48, v48, v30, v31
	v_mov_b32_e32 v49, v48
	s_nop 1
	v_permlane32_swap_b32_e32 v48, v49
	v_max_f32_e32 v49, v49, v49
	v_max_f32_e32 v48, v48, v48
	v_max_f32_e32 v48, v48, v49
	v_add_f32_e32 v49, 0x7149f2ca, v48
	v_cmp_ge_f32_e32 vcc, s70, v49
	s_cmp_eq_u64 vcc, exec
	v_max_f32_e32 v48, 0xf149f2ca, v48
	s_cselect_b64 vcc, -1, 0
	v_cndmask_b32_e32 v143, v48, v183, vcc
	v_sub_f32_e32 v49, 0xf149f2ca, v48
	v_mul_f32_e32 v48, 0xbe38aa3b, v143
	v_fmamk_f32 v0, v0, 0x3e38aa3b, v48
	v_exp_f32_e32 v113, v0
	v_fmamk_f32 v0, v1, 0x3e38aa3b, v48
	v_exp_f32_e32 v155, v0
	v_fmamk_f32 v0, v2, 0x3e38aa3b, v48
	v_exp_f32_e32 v152, v0
	v_fmamk_f32 v0, v3, 0x3e38aa3b, v48
	v_exp_f32_e32 v156, v0
	v_fmamk_f32 v0, v4, 0x3e38aa3b, v48
	v_exp_f32_e32 v153, v0
	v_fmamk_f32 v0, v5, 0x3e38aa3b, v48
	v_exp_f32_e32 v158, v0
	v_fmamk_f32 v0, v6, 0x3e38aa3b, v48
	v_exp_f32_e32 v154, v0
	v_fmamk_f32 v0, v7, 0x3e38aa3b, v48
	v_exp_f32_e32 v159, v0
	v_fmamk_f32 v0, v8, 0x3e38aa3b, v48
	v_mul_f32_e32 v49, 0x3e38aa3b, v49
	v_exp_f32_e32 v144, v0
	v_fmamk_f32 v0, v9, 0x3e38aa3b, v48
	v_exp_f32_e32 v49, v49
	v_exp_f32_e32 v148, v0
	v_fmamk_f32 v0, v10, 0x3e38aa3b, v48
	v_exp_f32_e32 v145, v0
	v_fmamk_f32 v0, v11, 0x3e38aa3b, v48
	v_exp_f32_e32 v149, v0
	v_fmamk_f32 v0, v12, 0x3e38aa3b, v48
	s_mov_b32 s14, 0x3e38aa3b
	v_exp_f32_e32 v146, v0
	v_fmamk_f32 v0, v13, 0x3e38aa3b, v48
	v_pk_fma_f32 v[122:123], v[30:31], s[14:15], v[48:49] op_sel_hi:[1,0,0]
	v_pk_fma_f32 v[114:115], v[28:29], s[14:15], v[48:49] op_sel_hi:[1,0,0]
	v_pk_fma_f32 v[116:117], v[26:27], s[14:15], v[48:49] op_sel_hi:[1,0,0]
	v_pk_fma_f32 v[118:119], v[24:25], s[14:15], v[48:49] op_sel_hi:[1,0,0]
	v_pk_fma_f32 v[120:121], v[22:23], s[14:15], v[48:49] op_sel_hi:[1,0,0]
	v_pk_fma_f32 v[124:125], v[20:21], s[14:15], v[48:49] op_sel_hi:[1,0,0]
	v_pk_fma_f32 v[126:127], v[18:19], s[14:15], v[48:49] op_sel_hi:[1,0,0]
	v_pk_fma_f32 v[128:129], v[16:17], s[14:15], v[48:49] op_sel_hi:[1,0,0]
	v_exp_f32_e32 v150, v0
	v_fmamk_f32 v0, v14, 0x3e38aa3b, v48
	v_fmac_f32_e32 v48, 0x3e38aa3b, v15
	v_exp_f32_e32 v147, v0
	v_exp_f32_e32 v151, v48
	s_waitcnt vmcnt(0) lgkmcnt(0)
	s_or_b32 s4, s4, s50
	v_cndmask_b32_e64 v142, v49, 1.0, vcc
	s_add_u32 s14, s36, s4
	v_mov_b64_e32 v[62:63], v[46:47]
	v_mov_b64_e32 v[16:17], v[32:33]
	v_mov_b64_e32 v[0:1], v[32:33]
	s_addc_u32 s15, s37, s5
	s_mov_b32 s50, 2
	v_mov_b64_e32 v[60:61], v[44:45]
	v_mov_b64_e32 v[58:59], v[42:43]
	v_mov_b64_e32 v[56:57], v[40:41]
	v_mov_b64_e32 v[54:55], v[38:39]
	v_mov_b64_e32 v[52:53], v[36:37]
	v_mov_b64_e32 v[50:51], v[34:35]
	v_mov_b64_e32 v[48:49], v[32:33]
	v_mov_b64_e32 v[18:19], v[34:35]
	v_mov_b64_e32 v[20:21], v[36:37]
	v_mov_b64_e32 v[22:23], v[38:39]
	v_mov_b64_e32 v[24:25], v[40:41]
	v_mov_b64_e32 v[26:27], v[42:43]
	v_mov_b64_e32 v[28:29], v[44:45]
	v_mov_b64_e32 v[30:31], v[46:47]
	v_mov_b64_e32 v[2:3], v[34:35]
	v_mov_b64_e32 v[4:5], v[36:37]
	v_mov_b64_e32 v[6:7], v[38:39]
	v_mov_b64_e32 v[8:9], v[40:41]
	v_mov_b64_e32 v[10:11], v[42:43]
	v_mov_b64_e32 v[12:13], v[44:45]
	v_mov_b64_e32 v[14:15], v[46:47]
	s_mov_b32 s53, 2
	s_barrier
; #define SBAR() __builtin_amdgcn_sched_barrier(0)
; __device__ __forceinline__ void finishSM(f32x16& p0, f32x16& p1, float alpha, float& l_reg, bf16x8& pa0, bf16x8& pa1, bf16x8& pa2, bf16x8& pa3) {
; #pragma unroll
;   for (int r = 0; r < 16; ++r) p1[r] = __builtin_amdgcn_exp2f(p1[r]);
;   float ps = 0;
; #pragma unroll
;   for (int r = 0; r < 16; ++r) ps += p0[r];
; #pragma unroll
;   for (int r = 0; r < 16; ++r) ps += p1[r];
;   { auto rr = __builtin_amdgcn_permlane32_swap(__float_as_uint(ps), __float_as_uint(ps), false, false);
;     ps = __uint_as_float(rr[0]) + __uint_as_float(rr[1]); }
;   l_reg = l_reg * alpha + ps;
;     ...
;   PK4(p0, 0, pa0); PK4(p0, 8, pa1); PK4(p1, 0, pa2); PK4(p1, 8, pa3);
;     ...
; }
; __device__ __forceinline__ void attn_diff_dma(const bf16_t* __restrict__ Qb, const bf16_t* __restrict__ Kh, const bf16_t* __restrict__ Vh, bf16_t* __restrict__ Ob,
;                                               int seq, char* lds, float lam, const float* __restrict__ gsub, const int tid) {
;     ...
;     SBAR(); qkt_diff<(int)SHM_K128>(pB0, pB1, ka, qr);
;     finishSM(pA0, pA1, alA, l_reg, pa0, pa1, pa2, pa3); SBAR();
;     DMA_TILE((j + 1) * KVBLK, 0, vnxt); SBAR();
;     pv_d0_t(o, vb0 + vprev * SHM_VV, pa0, pa1, pa2, pa3); partialSM<0>(pB0, pB1, m_reg, mnB, alB);
.LBB0_129:
	s_mov_b32 s54, s47
	s_mov_b32 s47, s52
	ds_read_b128 v[64:67], v138 offset:16384
	ds_read_b128 v[68:71], v138 offset:24576
	ds_read_b128 v[170:173], v141 offset:16384
	ds_read_b128 v[188:191], v141 offset:24576
	v_add_f32_e32 v112, v155, v113
	s_waitcnt lgkmcnt(0)
	v_mfma_f32_32x32x16_bf16 v[80:95], v[64:67], v[108:111], 0
	v_add_f32_e32 v112, v152, v112
	v_add_f32_e32 v112, v156, v112
	v_add_f32_e32 v112, v153, v112
	v_add_f32_e32 v112, v158, v112
	v_add_f32_e32 v112, v154, v112
	v_add_f32_e32 v112, v159, v112
	v_add_f32_e32 v112, v144, v112
	v_mfma_f32_32x32x16_bf16 v[64:79], v[68:71], v[108:111], 0
	v_add_f32_e32 v112, v148, v112
	v_add_f32_e32 v112, v145, v112
	v_add_f32_e32 v112, v149, v112
	v_exp_f32_e32 v128, v128
	v_add_f32_e32 v112, v146, v112
	v_exp_f32_e32 v129, v129
	v_add_f32_e32 v112, v150, v112
	v_mfma_f32_32x32x16_bf16 v[80:95], v[170:173], v[104:107], v[80:95]
	v_exp_f32_e32 v126, v126
	v_add_f32_e32 v112, v147, v112
	v_exp_f32_e32 v127, v127
	v_add_f32_e32 v112, v151, v112
	v_exp_f32_e32 v132, v124
	v_add_f32_e32 v112, v128, v112
	v_exp_f32_e32 v162, v125
	v_mfma_f32_32x32x16_bf16 v[64:79], v[188:191], v[104:107], v[64:79]
	ds_read_b128 v[170:173], v140 offset:16384
	ds_read_b128 v[188:191], v140 offset:24576
	v_add_f32_e32 v112, v129, v112
	v_exp_f32_e32 v167, v120
	v_add_f32_e32 v112, v126, v112
	v_exp_f32_e32 v169, v121
	v_add_f32_e32 v112, v127, v112
	v_add_f32_e32 v112, v132, v112
	s_waitcnt lgkmcnt(0)
	v_mfma_f32_32x32x16_bf16 v[80:95], v[170:173], v[100:103], v[80:95]
	v_exp_f32_e32 v119, v119
	v_add_f32_e32 v112, v162, v112
	v_exp_f32_e32 v116, v116
	v_add_f32_e32 v112, v167, v112
	v_add_f32_e32 v112, v169, v112
	v_mfma_f32_32x32x16_bf16 v[64:79], v[188:191], v[100:103], v[64:79]
	ds_read_b128 v[170:173], v139 offset:16384
	ds_read_b128 v[188:191], v139 offset:24576
	s_waitcnt lgkmcnt(0)
	v_mfma_f32_32x32x16_bf16 v[80:95], v[170:173], v[96:99], v[80:95]
	v_exp_f32_e32 v170, v118
	v_exp_f32_e32 v171, v117
	v_exp_f32_e32 v172, v114
	v_exp_f32_e32 v173, v115
	v_add_f32_e32 v112, v170, v112
	v_add_f32_e32 v112, v119, v112
	v_add_f32_e32 v112, v116, v112
	v_mfma_f32_32x32x16_bf16 v[64:79], v[188:191], v[96:99], v[64:79]
	v_exp_f32_e32 v188, v122
	v_exp_f32_e32 v189, v123
	v_add_f32_e32 v112, v171, v112
	v_add_f32_e32 v112, v172, v112
	v_add_f32_e32 v112, v173, v112
	v_add_f32_e32 v112, v188, v112
	v_add_f32_e32 v117, v189, v112
	v_mov_b32_e32 v118, v117
	v_cvt_pk_bf16_f32 v112, v113, v155
	v_cvt_pk_bf16_f32 v113, v152, v156
	v_cvt_pk_bf16_f32 v114, v153, v158
	s_nop 1
	v_permlane32_swap_b32_e32 v117, v118
	v_cvt_pk_bf16_f32 v115, v154, v159
	v_cvt_pk_bf16_f32 v120, v144, v148
	v_cvt_pk_bf16_f32 v121, v145, v149
	v_cvt_pk_bf16_f32 v122, v146, v150
	v_cvt_pk_bf16_f32 v123, v147, v151
	v_cvt_pk_bf16_f32 v124, v128, v129
	v_cvt_pk_bf16_f32 v125, v126, v127
	v_cvt_pk_bf16_f32 v126, v132, v162
	v_cvt_pk_bf16_f32 v127, v167, v169
	v_cvt_pk_bf16_f32 v144, v170, v119
	v_cvt_pk_bf16_f32 v145, v116, v171
	v_cvt_pk_bf16_f32 v146, v172, v173
	v_cvt_pk_bf16_f32 v147, v188, v189
	s_add_u32 s4, s14, 0x2000000
	s_mov_b32 m0, s43
	s_addc_u32 s5, s15, 0
	s_mov_b64 s[56:57], s[14:15]
	s_lshl_b32 s52, s53, 14
	s_add_i32 s55, s42, s52
	s_nop 0
	global_load_lds_dwordx4 v134, s[56:57]
	s_mov_b32 m0, s44
	s_nop 0
	global_load_lds_dwordx4 v135, s[56:57]
	s_mov_b32 m0, s55
	s_nop 0
	global_load_lds_dwordx4 v136, s[4:5]
	s_add_i32 m0, s55, 0x2000
	s_nop 0
	global_load_lds_dwordx4 v137, s[4:5]
	s_lshl_b32 s55, s47, 14
	v_add_u32_e32 v132, s55, v133
	ds_read_b64_tr_b16 v[148:149], v132 offset:0
	ds_read_b64_tr_b16 v[150:151], v132 offset:0x800
	ds_read_b64_tr_b16 v[152:153], v132 offset:0x1000
	ds_read_b64_tr_b16 v[154:155], v132 offset:0x1800
	ds_read_b64_tr_b16 v[170:171], v132 offset:0x2000
	ds_read_b64_tr_b16 v[172:173], v132 offset:0x2800
	ds_read_b64_tr_b16 v[188:189], v132 offset:0x3000
	ds_read_b64_tr_b16 v[190:191], v132 offset:0x3800
	s_waitcnt lgkmcnt(0)
	s_nop 0
	v_mfma_f32_32x32x16_bf16 v[32:47], v[148:151], v[112:115], v[32:47]
	ds_read_b64_tr_b16 v[148:149], v132 offset:0x200
	ds_read_b64_tr_b16 v[150:151], v132 offset:0xa00
	v_mfma_f32_32x32x16_bf16 v[32:47], v[152:155], v[120:123], v[32:47]
	ds_read_b64_tr_b16 v[152:153], v132 offset:0x1200
	ds_read_b64_tr_b16 v[154:155], v132 offset:0x1a00
	v_mfma_f32_32x32x16_bf16 v[32:47], v[170:173], v[124:127], v[32:47]
	ds_read_b64_tr_b16 v[170:171], v132 offset:0x2200
	ds_read_b64_tr_b16 v[172:173], v132 offset:0x2a00
	v_mfma_f32_32x32x16_bf16 v[32:47], v[188:191], v[144:147], v[32:47]
	ds_read_b64_tr_b16 v[188:189], v132 offset:0x3200
	ds_read_b64_tr_b16 v[190:191], v132 offset:0x3a00
	s_waitcnt lgkmcnt(0)
	v_mfma_f32_32x32x16_bf16 v[48:63], v[148:151], v[112:115], v[48:63]
	ds_read_b64_tr_b16 v[148:149], v132 offset:0x400
	ds_read_b64_tr_b16 v[150:151], v132 offset:0xc00
	v_mfma_f32_32x32x16_bf16 v[48:63], v[152:155], v[120:123], v[48:63]
	ds_read_b64_tr_b16 v[152:153], v132 offset:0x1400
	ds_read_b64_tr_b16 v[154:155], v132 offset:0x1c00
	v_mfma_f32_32x32x16_bf16 v[48:63], v[170:173], v[124:127], v[48:63]
	ds_read_b64_tr_b16 v[170:171], v132 offset:0x2400
	ds_read_b64_tr_b16 v[172:173], v132 offset:0x2c00
	v_mfma_f32_32x32x16_bf16 v[48:63], v[188:191], v[144:147], v[48:63]
	ds_read_b64_tr_b16 v[188:189], v132 offset:0x3400
	ds_read_b64_tr_b16 v[190:191], v132 offset:0x3c00
	s_waitcnt lgkmcnt(0)
; #define SBAR() __builtin_amdgcn_sched_barrier(0)
; #define RESC(a) do { if (__any((a) < 1.f)) { if (hi == 0) al_l[r32] = (a); asm volatile("s_waitcnt lgkmcnt(0)" ::: "memory"); \
;     for (int d = 0; d < 4; ++d) for (int r = 0; r < 16; ++r) o[d][r] *= al_l[crow_(r, hi)]; } } while (0)
; #define TILE_BAR() do { asm volatile("s_waitcnt vmcnt(0) lgkmcnt(0)" ::: "memory"); __builtin_amdgcn_s_barrier(); } while (0)
; #define RESC(a) do { if (__any((a) < 1.f)) { for (int d = 0; d < 4; ++d) for (int r = 0; r < 16; ++r) o[d][r] *= (a); } } while (0)
; #define TILE_BAR() do { asm volatile("s_waitcnt vmcnt(0) lgkmcnt(0)" ::: "memory"); __builtin_amdgcn_s_barrier(); } while (0)
; template <int MLA>
; __device__ __forceinline__ void partialSM(f32x16& p0, f32x16& p1, float& m_reg, float& mn, float& alpha) {
;   constexpr float SCALE = AttC<MLA>::SCALE;
;   constexpr float C = SCALE * 1.4426950408889634f;
;   float pmax = p0[0];
; #pragma unroll
;   for (int r = 1; r < 16; ++r) pmax = fmaxf(pmax, p0[r]);
; #pragma unroll
;   for (int r = 0; r < 16; ++r) pmax = fmaxf(pmax, p1[r]);
;   { auto rr = __builtin_amdgcn_permlane32_swap(__float_as_uint(pmax), __float_as_uint(pmax), false, false);
;     pmax = fmaxf(__uint_as_float(rr[0]), __uint_as_float(rr[1])); }
;   if (__builtin_expect(__all(pmax - m_reg <= THR / SCALE), 1)) { mn = m_reg; alpha = 1.f; }
;   else { mn = fmaxf(m_reg, pmax); alpha = __builtin_amdgcn_exp2f((m_reg - mn) * C); m_reg = mn; }
;   float mnC = -mn * C;
; #pragma unroll
;   for (int r = 0; r < 16; ++r) p0[r] = fmaf(p0[r], C, mnC);
; #pragma unroll
;   for (int r = 0; r < 16; ++r) p1[r] = fmaf(p1[r], C, mnC);
; #pragma unroll
;   for (int r = 0; r < 16; ++r) p0[r] = __builtin_amdgcn_exp2f(p0[r]);
; }
; __device__ __forceinline__ void attn_diff_dma(const bf16_t* __restrict__ Qb, const bf16_t* __restrict__ Kh, const bf16_t* __restrict__ Vh, bf16_t* __restrict__ Ob,
;                                               int seq, char* lds, float lam, const float* __restrict__ gsub, const int tid) {
;     ...
;     pv_d0_t(o, vb0 + vprev * SHM_VV, pa0, pa1, pa2, pa3); partialSM<0>(pB0, pB1, m_reg, mnB, alB);
;     TILE_BAR();
;     RESC(alB);
;     { const int t = vprev; vprev = vcur; vcur = vnxt; vnxt = t; }
;     SBAR(); qkt_diff<0>(pA0, pA1, ka, qr);
	v_mfma_f32_32x32x16_bf16 v[16:31], v[148:151], v[112:115], v[16:31]
	ds_read_b64_tr_b16 v[148:149], v132 offset:0x600
	ds_read_b64_tr_b16 v[150:151], v132 offset:0xe00
	v_mfma_f32_32x32x16_bf16 v[16:31], v[152:155], v[120:123], v[16:31]
	ds_read_b64_tr_b16 v[152:153], v132 offset:0x1600
	ds_read_b64_tr_b16 v[154:155], v132 offset:0x1e00
	v_mfma_f32_32x32x16_bf16 v[16:31], v[170:173], v[124:127], v[16:31]
	ds_read_b64_tr_b16 v[170:171], v132 offset:0x2600
	ds_read_b64_tr_b16 v[172:173], v132 offset:0x2e00
	v_mfma_f32_32x32x16_bf16 v[16:31], v[188:191], v[144:147], v[16:31]
	ds_read_b64_tr_b16 v[188:189], v132 offset:0x3600
	ds_read_b64_tr_b16 v[190:191], v132 offset:0x3e00
	s_waitcnt lgkmcnt(0)
	v_mfma_f32_32x32x16_bf16 v[0:15], v[148:151], v[112:115], v[0:15]
	v_max_f32_e32 v112, v80, v81
	v_max3_f32 v112, v112, v82, v83
	v_max3_f32 v112, v112, v84, v85
	v_max3_f32 v112, v112, v86, v87
	v_max3_f32 v112, v112, v88, v89
	v_max3_f32 v112, v112, v90, v91
	v_max3_f32 v112, v112, v92, v93
	v_mfma_f32_32x32x16_bf16 v[0:15], v[152:155], v[120:123], v[0:15]
	v_max3_f32 v112, v112, v94, v95
	v_max3_f32 v112, v112, v64, v65
	v_max3_f32 v112, v112, v66, v67
	v_max3_f32 v112, v112, v68, v69
	v_max3_f32 v112, v112, v70, v71
	v_max3_f32 v112, v112, v72, v73
	v_max3_f32 v112, v112, v74, v75
	v_max3_f32 v112, v112, v76, v77
	v_mfma_f32_32x32x16_bf16 v[0:15], v[170:173], v[124:127], v[0:15]
	v_max3_f32 v112, v112, v78, v79
	v_mov_b32_e32 v113, v112
	s_nop 1
	v_permlane32_swap_b32_e32 v112, v113
	v_max_f32_e32 v112, v112, v113
	v_sub_f32_e32 v113, v112, v143
	v_cmp_ge_f32_e32 vcc, s70, v113
	v_max_f32_e32 v112, v143, v112
	v_mfma_f32_32x32x16_bf16 v[0:15], v[188:191], v[144:147], v[0:15]
	v_sub_f32_e32 v113, v143, v112
	v_mul_f32_e32 v113, 0x3e38aa3b, v113
	v_exp_f32_e32 v113, v113
	s_cmp_eq_u64 vcc, exec
	s_cselect_b64 s[4:5], -1, 0
	s_waitcnt vmcnt(0) lgkmcnt(0)
	v_cndmask_b32_e64 v116, v113, 1.0, s[4:5]
	v_cmp_gt_f32_e32 vcc, 1.0, v116
	s_barrier
	s_cbranch_vccz .LBB0_131
	v_pk_mul_f32 v[46:47], v[46:47], v[116:117] op_sel_hi:[1,0]
	v_pk_mul_f32 v[44:45], v[44:45], v[116:117] op_sel_hi:[1,0]
	v_pk_mul_f32 v[42:43], v[42:43], v[116:117] op_sel_hi:[1,0]
	v_pk_mul_f32 v[40:41], v[40:41], v[116:117] op_sel_hi:[1,0]
	v_pk_mul_f32 v[38:39], v[38:39], v[116:117] op_sel_hi:[1,0]
	v_pk_mul_f32 v[36:37], v[36:37], v[116:117] op_sel_hi:[1,0]
	v_pk_mul_f32 v[34:35], v[34:35], v[116:117] op_sel_hi:[1,0]
	v_pk_mul_f32 v[32:33], v[32:33], v[116:117] op_sel_hi:[1,0]
	v_pk_mul_f32 v[62:63], v[62:63], v[116:117] op_sel_hi:[1,0]
	v_pk_mul_f32 v[60:61], v[60:61], v[116:117] op_sel_hi:[1,0]
	v_pk_mul_f32 v[58:59], v[58:59], v[116:117] op_sel_hi:[1,0]
	v_pk_mul_f32 v[56:57], v[56:57], v[116:117] op_sel_hi:[1,0]
	v_pk_mul_f32 v[54:55], v[54:55], v[116:117] op_sel_hi:[1,0]
	v_pk_mul_f32 v[52:53], v[52:53], v[116:117] op_sel_hi:[1,0]
	v_pk_mul_f32 v[50:51], v[50:51], v[116:117] op_sel_hi:[1,0]
	v_pk_mul_f32 v[48:49], v[48:49], v[116:117] op_sel_hi:[1,0]
	v_pk_mul_f32 v[30:31], v[30:31], v[116:117] op_sel_hi:[1,0]
	v_pk_mul_f32 v[28:29], v[28:29], v[116:117] op_sel_hi:[1,0]
	v_pk_mul_f32 v[26:27], v[26:27], v[116:117] op_sel_hi:[1,0]
	v_pk_mul_f32 v[24:25], v[24:25], v[116:117] op_sel_hi:[1,0]
	v_pk_mul_f32 v[22:23], v[22:23], v[116:117] op_sel_hi:[1,0]
	v_pk_mul_f32 v[20:21], v[20:21], v[116:117] op_sel_hi:[1,0]
	v_pk_mul_f32 v[18:19], v[18:19], v[116:117] op_sel_hi:[1,0]
	v_pk_mul_f32 v[16:17], v[16:17], v[116:117] op_sel_hi:[1,0]
	v_pk_mul_f32 v[14:15], v[14:15], v[116:117] op_sel_hi:[1,0]
	v_pk_mul_f32 v[12:13], v[12:13], v[116:117] op_sel_hi:[1,0]
	v_pk_mul_f32 v[10:11], v[10:11], v[116:117] op_sel_hi:[1,0]
	v_pk_mul_f32 v[8:9], v[8:9], v[116:117] op_sel_hi:[1,0]
	v_pk_mul_f32 v[6:7], v[6:7], v[116:117] op_sel_hi:[1,0]
	v_pk_mul_f32 v[4:5], v[4:5], v[116:117] op_sel_hi:[1,0]
	v_pk_mul_f32 v[2:3], v[2:3], v[116:117] op_sel_hi:[1,0]
	v_pk_mul_f32 v[0:1], v[0:1], v[116:117] op_sel_hi:[1,0]
.LBB0_131:
	v_cndmask_b32_e64 v119, v112, v143, s[4:5]
	v_mul_f32_e32 v124, 0xbe38aa3b, v119
	v_fmamk_f32 v80, v80, 0x3e38aa3b, v124
	v_fmamk_f32 v81, v81, 0x3e38aa3b, v124
	v_fmamk_f32 v82, v82, 0x3e38aa3b, v124
	v_fmamk_f32 v83, v83, 0x3e38aa3b, v124
	v_fmamk_f32 v84, v84, 0x3e38aa3b, v124
	v_fmamk_f32 v85, v85, 0x3e38aa3b, v124
	v_fmamk_f32 v86, v86, 0x3e38aa3b, v124
	v_fmamk_f32 v87, v87, 0x3e38aa3b, v124
	v_fmamk_f32 v88, v88, 0x3e38aa3b, v124
	v_fmamk_f32 v89, v89, 0x3e38aa3b, v124
	v_fmamk_f32 v90, v90, 0x3e38aa3b, v124
	v_fmamk_f32 v91, v91, 0x3e38aa3b, v124
	v_fmamk_f32 v92, v92, 0x3e38aa3b, v124
	v_fmamk_f32 v93, v93, 0x3e38aa3b, v124
	v_fmamk_f32 v94, v94, 0x3e38aa3b, v124
	v_fmamk_f32 v95, v95, 0x3e38aa3b, v124
	v_fmamk_f32 v125, v64, 0x3e38aa3b, v124
	v_fmamk_f32 v126, v65, 0x3e38aa3b, v124
	v_fmamk_f32 v127, v66, 0x3e38aa3b, v124
	v_fmamk_f32 v128, v67, 0x3e38aa3b, v124
	v_fmamk_f32 v129, v68, 0x3e38aa3b, v124
	v_fmamk_f32 v143, v69, 0x3e38aa3b, v124
	v_fmamk_f32 v144, v70, 0x3e38aa3b, v124
	v_fmamk_f32 v145, v71, 0x3e38aa3b, v124
	v_fmamk_f32 v146, v72, 0x3e38aa3b, v124
	v_fmamk_f32 v147, v73, 0x3e38aa3b, v124
	v_fmamk_f32 v148, v74, 0x3e38aa3b, v124
	v_fmamk_f32 v149, v75, 0x3e38aa3b, v124
	v_fmamk_f32 v150, v76, 0x3e38aa3b, v124
	v_exp_f32_e32 v151, v80
	v_exp_f32_e32 v152, v81
	v_exp_f32_e32 v153, v82
	v_exp_f32_e32 v154, v83
	v_exp_f32_e32 v155, v84
	v_exp_f32_e32 v156, v85
	v_exp_f32_e32 v158, v86
	v_exp_f32_e32 v159, v87
	v_exp_f32_e32 v162, v88
	v_exp_f32_e32 v167, v89
	v_exp_f32_e32 v169, v90
	v_exp_f32_e32 v170, v91
	v_exp_f32_e32 v171, v92
	v_exp_f32_e32 v172, v93
	v_exp_f32_e32 v173, v94
	v_exp_f32_e32 v188, v95
	v_fmamk_f32 v189, v77, 0x3e38aa3b, v124
	v_fmamk_f32 v190, v78, 0x3e38aa3b, v124
	v_fmac_f32_e32 v124, 0x3e38aa3b, v79
	ds_read_b128 v[64:67], v138
	ds_read_b128 v[68:71], v138 offset:8192
	ds_read_b128 v[112:115], v141
	ds_read_b128 v[120:123], v141 offset:8192
	v_exp_f32_e32 v191, v125
	v_exp_f32_e32 v126, v126
	s_waitcnt lgkmcnt(0)
; #define SBAR() __builtin_amdgcn_sched_barrier(0)
; __device__ __forceinline__ void finishSM(f32x16& p0, f32x16& p1, float alpha, float& l_reg, bf16x8& pa0, bf16x8& pa1, bf16x8& pa2, bf16x8& pa3) {
; #pragma unroll
;   for (int r = 0; r < 16; ++r) p1[r] = __builtin_amdgcn_exp2f(p1[r]);
;   float ps = 0;
; #pragma unroll
;   for (int r = 0; r < 16; ++r) ps += p0[r];
; #pragma unroll
;   for (int r = 0; r < 16; ++r) ps += p1[r];
;   { auto rr = __builtin_amdgcn_permlane32_swap(__float_as_uint(ps), __float_as_uint(ps), false, false);
;     ps = __uint_as_float(rr[0]) + __uint_as_float(rr[1]); }
;   l_reg = l_reg * alpha + ps;
;     ...
;   PK4(p0, 0, pa0); PK4(p0, 8, pa1); PK4(p1, 0, pa2); PK4(p1, 8, pa3);
;     ...
; }
; __device__ __forceinline__ void attn_diff_dma(const bf16_t* __restrict__ Qb, const bf16_t* __restrict__ Kh, const bf16_t* __restrict__ Vh, bf16_t* __restrict__ Ob,
;                                               int seq, char* lds, float lam, const float* __restrict__ gsub, const int tid) {
;     ...
;     SBAR(); qkt_diff<0>(pA0, pA1, ka, qr);
;     finishSM(pB0, pB1, alB, l_reg, pa0, pa1, pa2, pa3); SBAR();
;     DMA_TILE((j + 2) * KVBLK, 1, vnxt); SBAR();
;     pv_d0_t(o, vb0 + vprev * SHM_VV, pa0, pa1, pa2, pa3); partialSM<0>(pA0, pA1, m_reg, mnA, alA);
	v_mfma_f32_32x32x16_bf16 v[80:95], v[64:67], v[108:111], 0
	v_exp_f32_e32 v127, v127
	v_exp_f32_e32 v128, v128
	v_exp_f32_e32 v129, v129
	v_exp_f32_e32 v143, v143
	v_exp_f32_e32 v144, v144
	v_exp_f32_e32 v145, v145
	v_exp_f32_e32 v146, v146
	v_mfma_f32_32x32x16_bf16 v[64:79], v[68:71], v[108:111], 0
	v_exp_f32_e32 v147, v147
	v_exp_f32_e32 v148, v148
	v_exp_f32_e32 v149, v149
	v_exp_f32_e32 v150, v150
	v_exp_f32_e32 v189, v189
	v_exp_f32_e32 v190, v190
	v_exp_f32_e32 v192, v124
	v_mfma_f32_32x32x16_bf16 v[80:95], v[112:115], v[104:107], v[80:95]
	v_mfma_f32_32x32x16_bf16 v[64:79], v[120:123], v[104:107], v[64:79]
	ds_read_b128 v[112:115], v140
	ds_read_b128 v[120:123], v140 offset:8192
	s_waitcnt lgkmcnt(0)
	v_mfma_f32_32x32x16_bf16 v[80:95], v[112:115], v[100:103], v[80:95]
	v_mfma_f32_32x32x16_bf16 v[64:79], v[120:123], v[100:103], v[64:79]
	ds_read_b128 v[112:115], v139
	ds_read_b128 v[120:123], v139 offset:8192
	s_waitcnt lgkmcnt(0)
	v_mfma_f32_32x32x16_bf16 v[80:95], v[112:115], v[96:99], v[80:95]
	v_add_f32_e32 v112, v152, v151
	v_add_f32_e32 v112, v153, v112
	v_add_f32_e32 v112, v154, v112
	v_add_f32_e32 v112, v155, v112
	v_add_f32_e32 v112, v156, v112
	v_add_f32_e32 v112, v158, v112
	v_add_f32_e32 v112, v159, v112
	v_add_f32_e32 v112, v162, v112
	v_add_f32_e32 v112, v167, v112
	v_add_f32_e32 v112, v169, v112
	v_add_f32_e32 v112, v170, v112
	v_add_f32_e32 v112, v171, v112
	v_add_f32_e32 v112, v172, v112
	v_add_f32_e32 v112, v173, v112
	v_add_f32_e32 v112, v188, v112
	v_add_f32_e32 v112, v191, v112
	v_add_f32_e32 v112, v126, v112
	v_add_f32_e32 v112, v127, v112
	v_add_f32_e32 v112, v128, v112
	v_add_f32_e32 v112, v129, v112
	v_add_f32_e32 v112, v143, v112
	v_add_f32_e32 v112, v144, v112
	v_add_f32_e32 v112, v145, v112
	v_add_f32_e32 v112, v146, v112
	v_add_f32_e32 v112, v147, v112
	v_mfma_f32_32x32x16_bf16 v[64:79], v[120:123], v[96:99], v[64:79]
	v_add_f32_e32 v112, v148, v112
	v_add_f32_e32 v112, v149, v112
	v_add_f32_e32 v112, v150, v112
	v_add_f32_e32 v112, v189, v112
	v_add_f32_e32 v112, v190, v112
	v_add_f32_e32 v120, v192, v112
	v_mov_b32_e32 v121, v120
	v_cvt_pk_bf16_f32 v112, v151, v152
	v_cvt_pk_bf16_f32 v113, v153, v154
	v_cvt_pk_bf16_f32 v114, v155, v156
	v_cvt_pk_bf16_f32 v115, v158, v159
	s_nop 1
	v_permlane32_swap_b32_e32 v120, v121
	v_cvt_pk_bf16_f32 v122, v162, v167
	v_cvt_pk_bf16_f32 v123, v169, v170
	v_cvt_pk_bf16_f32 v124, v171, v172
	v_cvt_pk_bf16_f32 v125, v173, v188
	v_cvt_pk_bf16_f32 v126, v191, v126
	v_cvt_pk_bf16_f32 v127, v127, v128
	v_cvt_pk_bf16_f32 v128, v129, v143
	v_cvt_pk_bf16_f32 v129, v144, v145
	v_cvt_pk_bf16_f32 v144, v146, v147
	v_cvt_pk_bf16_f32 v145, v148, v149
	v_cvt_pk_bf16_f32 v146, v150, v189
	v_cvt_pk_bf16_f32 v147, v190, v192
	s_nop 0
	s_add_u32 s4, s14, 0x20000
	s_addc_u32 s5, s15, 0
	s_add_u32 s56, s14, 0x2020000
	s_mov_b32 m0, s16
	s_addc_u32 s57, s15, 0
	s_add_i32 s55, s42, s55
	s_nop 0
	global_load_lds_dwordx4 v134, s[4:5]
	s_mov_b32 m0, s17
	s_nop 0
	global_load_lds_dwordx4 v135, s[4:5]
	s_mov_b32 m0, s55
	s_nop 0
	global_load_lds_dwordx4 v136, s[56:57]
	s_add_i32 m0, s55, 0x2000
	s_nop 0
	global_load_lds_dwordx4 v137, s[56:57]
	v_lshl_add_u32 v143, s54, 14, v133
	ds_read_b64_tr_b16 v[148:149], v143 offset:0
	ds_read_b64_tr_b16 v[150:151], v143 offset:0x800
	ds_read_b64_tr_b16 v[152:153], v143 offset:0x1000
	ds_read_b64_tr_b16 v[154:155], v143 offset:0x1800
	ds_read_b64_tr_b16 v[170:171], v143 offset:0x2000
	ds_read_b64_tr_b16 v[172:173], v143 offset:0x2800
	ds_read_b64_tr_b16 v[188:189], v143 offset:0x3000
	ds_read_b64_tr_b16 v[190:191], v143 offset:0x3800
	s_waitcnt lgkmcnt(0)
	s_nop 0
	v_mfma_f32_32x32x16_bf16 v[32:47], v[148:151], v[112:115], v[32:47]
	ds_read_b64_tr_b16 v[148:149], v143 offset:0x200
	ds_read_b64_tr_b16 v[150:151], v143 offset:0xa00
	v_mfma_f32_32x32x16_bf16 v[32:47], v[152:155], v[122:125], v[32:47]
	ds_read_b64_tr_b16 v[152:153], v143 offset:0x1200
	ds_read_b64_tr_b16 v[154:155], v143 offset:0x1a00
	v_mfma_f32_32x32x16_bf16 v[32:47], v[170:173], v[126:129], v[32:47]
	ds_read_b64_tr_b16 v[170:171], v143 offset:0x2200
	ds_read_b64_tr_b16 v[172:173], v143 offset:0x2a00
	v_mfma_f32_32x32x16_bf16 v[32:47], v[188:191], v[144:147], v[32:47]
	ds_read_b64_tr_b16 v[188:189], v143 offset:0x3200
	ds_read_b64_tr_b16 v[190:191], v143 offset:0x3a00
	s_waitcnt lgkmcnt(0)
	v_mfma_f32_32x32x16_bf16 v[48:63], v[148:151], v[112:115], v[48:63]
	ds_read_b64_tr_b16 v[148:149], v143 offset:0x400
	ds_read_b64_tr_b16 v[150:151], v143 offset:0xc00
	v_mfma_f32_32x32x16_bf16 v[48:63], v[152:155], v[122:125], v[48:63]
	ds_read_b64_tr_b16 v[152:153], v143 offset:0x1400
	ds_read_b64_tr_b16 v[154:155], v143 offset:0x1c00
	v_mfma_f32_32x32x16_bf16 v[48:63], v[170:173], v[126:129], v[48:63]
	ds_read_b64_tr_b16 v[170:171], v143 offset:0x2400
	ds_read_b64_tr_b16 v[172:173], v143 offset:0x2c00
	v_mfma_f32_32x32x16_bf16 v[48:63], v[188:191], v[144:147], v[48:63]
	ds_read_b64_tr_b16 v[188:189], v143 offset:0x3400
	ds_read_b64_tr_b16 v[190:191], v143 offset:0x3c00
	s_waitcnt lgkmcnt(0)
	v_mfma_f32_32x32x16_bf16 v[16:31], v[148:151], v[112:115], v[16:31]
	ds_read_b64_tr_b16 v[148:149], v143 offset:0x600
	ds_read_b64_tr_b16 v[150:151], v143 offset:0xe00
	v_mfma_f32_32x32x16_bf16 v[16:31], v[152:155], v[122:125], v[16:31]
	ds_read_b64_tr_b16 v[152:153], v143 offset:0x1600
	ds_read_b64_tr_b16 v[154:155], v143 offset:0x1e00
	v_mfma_f32_32x32x16_bf16 v[16:31], v[170:173], v[126:129], v[16:31]
	ds_read_b64_tr_b16 v[170:171], v143 offset:0x2600
	ds_read_b64_tr_b16 v[172:173], v143 offset:0x2e00
	v_mfma_f32_32x32x16_bf16 v[16:31], v[188:191], v[144:147], v[16:31]
	ds_read_b64_tr_b16 v[188:189], v143 offset:0x3600
	ds_read_b64_tr_b16 v[190:191], v143 offset:0x3e00
	s_waitcnt lgkmcnt(0)
	v_mfma_f32_32x32x16_bf16 v[0:15], v[148:151], v[112:115], v[0:15]
	v_max_f32_e32 v112, v80, v81
	v_max3_f32 v112, v112, v82, v83
	v_max3_f32 v112, v112, v84, v85
	v_max3_f32 v112, v112, v86, v87
	v_max3_f32 v112, v112, v88, v89
	v_max3_f32 v112, v112, v90, v91
	v_max3_f32 v112, v112, v92, v93
	v_mfma_f32_32x32x16_bf16 v[0:15], v[152:155], v[122:125], v[0:15]
	v_max3_f32 v112, v112, v94, v95
	v_max3_f32 v112, v112, v64, v65
	v_max3_f32 v112, v112, v66, v67
	v_max3_f32 v112, v112, v68, v69
	v_max3_f32 v112, v112, v70, v71
	v_max3_f32 v112, v112, v72, v73
	v_max3_f32 v112, v112, v74, v75
	v_max3_f32 v112, v112, v76, v77
	v_mfma_f32_32x32x16_bf16 v[0:15], v[170:173], v[126:129], v[0:15]
	v_max3_f32 v112, v112, v78, v79
	v_mov_b32_e32 v113, v112
	s_nop 1
	v_permlane32_swap_b32_e32 v112, v113
	v_max_f32_e32 v112, v112, v113
	v_sub_f32_e32 v113, v112, v119
	v_cmp_ge_f32_e32 vcc, s70, v113
	v_max_f32_e32 v113, v119, v119
	v_max_f32_e32 v113, v113, v112
	v_mfma_f32_32x32x16_bf16 v[0:15], v[188:191], v[144:147], v[0:15]
	v_sub_f32_e32 v112, v119, v113
	v_mul_f32_e32 v112, 0x3e38aa3b, v112
	v_exp_f32_e32 v112, v112
	s_cmp_eq_u64 vcc, exec
	s_cselect_b64 s[4:5], -1, 0
	s_waitcnt vmcnt(0) lgkmcnt(0)
	v_cndmask_b32_e64 v112, v112, 1.0, s[4:5]
	v_cmp_gt_f32_e32 vcc, 1.0, v112
	s_barrier
; #define RESC(a) do { if (__any((a) < 1.f)) { if (hi == 0) al_l[r32] = (a); asm volatile("s_waitcnt lgkmcnt(0)" ::: "memory"); \
;     for (int d = 0; d < 4; ++d) for (int r = 0; r < 16; ++r) o[d][r] *= al_l[crow_(r, hi)]; } } while (0)
; #define TILE_BAR() do { asm volatile("s_waitcnt vmcnt(0) lgkmcnt(0)" ::: "memory"); __builtin_amdgcn_s_barrier(); } while (0)
; #define RESC(a) do { if (__any((a) < 1.f)) { for (int d = 0; d < 4; ++d) for (int r = 0; r < 16; ++r) o[d][r] *= (a); } } while (0)
; #define TILE_BAR() do { asm volatile("s_waitcnt vmcnt(0) lgkmcnt(0)" ::: "memory"); __builtin_amdgcn_s_barrier(); } while (0)
; #define RESC(a) do { if (__any((a) < 1.f)) { for (int d = 0; d < 4; ++d) for (int r = 0; r < 16; ++r) o[d][r] *= (a); } } while (0)
; __device__ __forceinline__ void attn_diff_dma(const bf16_t* __restrict__ Qb, const bf16_t* __restrict__ Kh, const bf16_t* __restrict__ Vh, bf16_t* __restrict__ Ob,
;                                               int seq, char* lds, float lam, const float* __restrict__ gsub, const int tid) {
;     ...
;     pv_d0_t(o, vb0 + vprev * SHM_VV, pa0, pa1, pa2, pa3); partialSM<0>(pA0, pA1, m_reg, mnA, alA);
;     TILE_BAR();
;     RESC(alA);
	s_cbranch_vccz .LBB0_133
	v_pk_mul_f32 v[46:47], v[46:47], v[112:113] op_sel_hi:[1,0]
	v_pk_mul_f32 v[44:45], v[44:45], v[112:113] op_sel_hi:[1,0]
	v_pk_mul_f32 v[42:43], v[42:43], v[112:113] op_sel_hi:[1,0]
	v_pk_mul_f32 v[40:41], v[40:41], v[112:113] op_sel_hi:[1,0]
	v_pk_mul_f32 v[38:39], v[38:39], v[112:113] op_sel_hi:[1,0]
	v_pk_mul_f32 v[36:37], v[36:37], v[112:113] op_sel_hi:[1,0]
	v_pk_mul_f32 v[34:35], v[34:35], v[112:113] op_sel_hi:[1,0]
	v_pk_mul_f32 v[32:33], v[32:33], v[112:113] op_sel_hi:[1,0]
	v_pk_mul_f32 v[62:63], v[62:63], v[112:113] op_sel_hi:[1,0]
	v_pk_mul_f32 v[60:61], v[60:61], v[112:113] op_sel_hi:[1,0]
	v_pk_mul_f32 v[58:59], v[58:59], v[112:113] op_sel_hi:[1,0]
	v_pk_mul_f32 v[56:57], v[56:57], v[112:113] op_sel_hi:[1,0]
	v_pk_mul_f32 v[54:55], v[54:55], v[112:113] op_sel_hi:[1,0]
	v_pk_mul_f32 v[52:53], v[52:53], v[112:113] op_sel_hi:[1,0]
	v_pk_mul_f32 v[50:51], v[50:51], v[112:113] op_sel_hi:[1,0]
	v_pk_mul_f32 v[48:49], v[48:49], v[112:113] op_sel_hi:[1,0]
	v_pk_mul_f32 v[30:31], v[30:31], v[112:113] op_sel_hi:[1,0]
	v_pk_mul_f32 v[28:29], v[28:29], v[112:113] op_sel_hi:[1,0]
	v_pk_mul_f32 v[26:27], v[26:27], v[112:113] op_sel_hi:[1,0]
	v_pk_mul_f32 v[24:25], v[24:25], v[112:113] op_sel_hi:[1,0]
	v_pk_mul_f32 v[22:23], v[22:23], v[112:113] op_sel_hi:[1,0]
	v_pk_mul_f32 v[20:21], v[20:21], v[112:113] op_sel_hi:[1,0]
	v_pk_mul_f32 v[18:19], v[18:19], v[112:113] op_sel_hi:[1,0]
	v_pk_mul_f32 v[16:17], v[16:17], v[112:113] op_sel_hi:[1,0]
	v_pk_mul_f32 v[14:15], v[14:15], v[112:113] op_sel_hi:[1,0]
	v_pk_mul_f32 v[12:13], v[12:13], v[112:113] op_sel_hi:[1,0]
	v_pk_mul_f32 v[10:11], v[10:11], v[112:113] op_sel_hi:[1,0]
	v_pk_mul_f32 v[8:9], v[8:9], v[112:113] op_sel_hi:[1,0]
	v_pk_mul_f32 v[6:7], v[6:7], v[112:113] op_sel_hi:[1,0]
	v_pk_mul_f32 v[4:5], v[4:5], v[112:113] op_sel_hi:[1,0]
	v_pk_mul_f32 v[2:3], v[2:3], v[112:113] op_sel_hi:[1,0]
	v_pk_mul_f32 v[0:1], v[0:1], v[112:113] op_sel_hi:[1,0]

; #define SBAR() __builtin_amdgcn_sched_barrier(0)
; #define RESC(a) do { if (__any((a) < 1.f)) { if (hi == 0) al_l[r32] = (a); asm volatile("s_waitcnt lgkmcnt(0)" ::: "memory"); \
;     for (int d = 0; d < 4; ++d) for (int r = 0; r < 16; ++r) o[d][r] *= al_l[crow_(r, hi)]; } } while (0)
; #define RESC(a) do { if (__any((a) < 1.f)) { for (int d = 0; d < 4; ++d) for (int r = 0; r < 16; ++r) o[d][r] *= (a); } } while (0)
; #define RESC(a) do { if (__any((a) < 1.f)) { for (int d = 0; d < 4; ++d) for (int r = 0; r < 16; ++r) o[d][r] *= (a); } } while (0)
; template <int BUFOFF>
; __device__ __forceinline__ void qkt_diff(f32x16& p0, f32x16& p1, const int* ka, const bf16x8* qr) {
;   typedef __attribute__((address_space(3))) const bf16x8* lp;
;   p0 = f32x16{}; p1 = f32x16{};
; #pragma unroll
;   for (int d0 = 0; d0 < 4; ++d0) {
;     const int a = ka[d0] + BUFOFF;
;     const bf16x8 b0 = *(lp)(a), b1 = *(lp)(a + 8192);
;     p0 = __builtin_amdgcn_mfma_f32_32x32x16_bf16(b0, qr[d0], p0, 0, 0, 0);
;     p1 = __builtin_amdgcn_mfma_f32_32x32x16_bf16(b1, qr[d0], p1, 0, 0, 0);
;   }
; }
; __device__ __forceinline__ void attn_diff_dma(const bf16_t* __restrict__ Qb, const bf16_t* __restrict__ Kh, const bf16_t* __restrict__ Vh, bf16_t* __restrict__ Ob,
;                                               int seq, char* lds, float lam, const float* __restrict__ gsub, const int tid) {
;     ...
;   SBAR(); qkt_diff<(int)SHM_K128>(pB0, pB1, ka, qr);
;   finishSM(pA0, pA1, alA, l_reg, pa0, pa1, pa2, pa3); SBAR();
;   pv_d0_t(o, vb0 + vprev * SHM_VV, pa0, pa1, pa2, pa3); partialSM<0>(pB0, pB1, m_reg, mnB, alB);
;   RESC(alB);
.LBB0_135:
	ds_read_b128 v[64:67], v138 offset:16384
	ds_read_b128 v[68:71], v138 offset:24576
	v_exp_f32_e32 v120, v120
	v_exp_f32_e32 v121, v121
	v_exp_f32_e32 v118, v118
	s_waitcnt lgkmcnt(0)
	v_mfma_f32_32x32x16_bf16 v[80:95], v[64:67], v[108:111], 0
	v_exp_f32_e32 v119, v119
	v_exp_f32_e32 v116, v116
	v_exp_f32_e32 v117, v117
	v_exp_f32_e32 v122, v122
	v_exp_f32_e32 v123, v123
	v_mfma_f32_32x32x16_bf16 v[64:79], v[68:71], v[108:111], 0
	ds_read_b128 v[108:111], v141 offset:16384
	ds_read_b128 v[134:137], v141 offset:24576
	s_waitcnt lgkmcnt(0)
	v_mfma_f32_32x32x16_bf16 v[80:95], v[108:111], v[104:107], v[80:95]
	v_mfma_f32_32x32x16_bf16 v[64:79], v[134:137], v[104:107], v[64:79]
	ds_read_b128 v[104:107], v140 offset:16384
	ds_read_b128 v[108:111], v140 offset:24576
	s_waitcnt lgkmcnt(0)
	v_mfma_f32_32x32x16_bf16 v[80:95], v[104:107], v[100:103], v[80:95]
	v_mfma_f32_32x32x16_bf16 v[64:79], v[108:111], v[100:103], v[64:79]
	ds_read_b128 v[100:103], v139 offset:16384
	ds_read_b128 v[104:107], v139 offset:24576
	v_exp_f32_e32 v109, v126
	v_exp_f32_e32 v110, v127
	v_exp_f32_e32 v111, v124
	v_exp_f32_e32 v124, v125
	v_exp_f32_e32 v125, v114
	v_exp_f32_e32 v126, v115
	s_waitcnt lgkmcnt(0)
	v_mfma_f32_32x32x16_bf16 v[80:95], v[100:103], v[96:99], v[80:95]
	v_cvt_pk_bf16_f32 v100, v113, v155
	v_cvt_pk_bf16_f32 v101, v152, v156
	v_cvt_pk_bf16_f32 v102, v153, v158
	v_cvt_pk_bf16_f32 v103, v154, v159
	s_nop 0
	v_mfma_f32_32x32x16_bf16 v[64:79], v[104:107], v[96:99], v[64:79]
	v_add_f32_e32 v97, 0, v113
	v_add_f32_e32 v97, v155, v97
	v_add_f32_e32 v97, v152, v97
	v_add_f32_e32 v97, v156, v97
	v_add_f32_e32 v97, v153, v97
	v_add_f32_e32 v97, v158, v97
	v_add_f32_e32 v97, v154, v97
	v_add_f32_e32 v97, v159, v97
	v_add_f32_e32 v97, v144, v97
	v_add_f32_e32 v97, v148, v97
	v_add_f32_e32 v97, v145, v97
	v_add_f32_e32 v97, v149, v97
	v_exp_f32_e32 v96, v128
	v_add_f32_e32 v97, v146, v97
	v_exp_f32_e32 v99, v129
	v_add_f32_e32 v97, v150, v97
	v_add_f32_e32 v97, v147, v97
	v_add_f32_e32 v97, v151, v97
	v_add_f32_e32 v97, v96, v97
	v_add_f32_e32 v97, v99, v97
	v_add_f32_e32 v97, v109, v97
	v_add_f32_e32 v97, v110, v97
	v_add_f32_e32 v97, v111, v97
	v_add_f32_e32 v97, v124, v97
	v_add_f32_e32 v97, v120, v97
	v_add_f32_e32 v97, v121, v97
	v_add_f32_e32 v97, v118, v97
	v_add_f32_e32 v97, v119, v97
	v_add_f32_e32 v97, v116, v97
	v_add_f32_e32 v97, v117, v97
	v_add_f32_e32 v97, v125, v97
	v_add_f32_e32 v97, v126, v97
	v_add_f32_e32 v97, v122, v97
	v_add_f32_e32 v97, v123, v97
	v_mov_b32_e32 v98, v97
	s_nop 1
	v_permlane32_swap_b32_e32 v97, v98
	v_cvt_pk_bf16_f32 v104, v144, v148
	v_cvt_pk_bf16_f32 v105, v145, v149
	v_cvt_pk_bf16_f32 v106, v146, v150
	v_cvt_pk_bf16_f32 v107, v147, v151
	v_cvt_pk_bf16_f32 v108, v96, v99
	v_cvt_pk_bf16_f32 v109, v109, v110
	v_cvt_pk_bf16_f32 v110, v111, v124
	v_cvt_pk_bf16_f32 v111, v120, v121
	v_cvt_pk_bf16_f32 v114, v118, v119
	v_cvt_pk_bf16_f32 v115, v116, v117
	v_cvt_pk_bf16_f32 v116, v125, v126
	v_cvt_pk_bf16_f32 v117, v122, v123
	v_add_u32_e32 v96, s52, v133
	ds_read_b64_tr_b16 v[118:119], v96 offset:0
	ds_read_b64_tr_b16 v[120:121], v96 offset:0x800
	ds_read_b64_tr_b16 v[122:123], v96 offset:0x1000
	ds_read_b64_tr_b16 v[124:125], v96 offset:0x1800
	ds_read_b64_tr_b16 v[126:127], v96 offset:0x2000
	ds_read_b64_tr_b16 v[128:129], v96 offset:0x2800
	ds_read_b64_tr_b16 v[134:135], v96 offset:0x3000
	ds_read_b64_tr_b16 v[136:137], v96 offset:0x3800
	s_waitcnt lgkmcnt(0)
	s_nop 0
	v_mfma_f32_32x32x16_bf16 v[32:47], v[118:121], v[100:103], v[32:47]
	ds_read_b64_tr_b16 v[118:119], v96 offset:0x200
	ds_read_b64_tr_b16 v[120:121], v96 offset:0xa00
	v_mfma_f32_32x32x16_bf16 v[32:47], v[122:125], v[104:107], v[32:47]
	ds_read_b64_tr_b16 v[122:123], v96 offset:0x1200
	ds_read_b64_tr_b16 v[124:125], v96 offset:0x1a00
	v_mfma_f32_32x32x16_bf16 v[32:47], v[126:129], v[108:111], v[32:47]
	ds_read_b64_tr_b16 v[126:127], v96 offset:0x2200
	ds_read_b64_tr_b16 v[128:129], v96 offset:0x2a00
	v_mfma_f32_32x32x16_bf16 v[32:47], v[134:137], v[114:117], v[32:47]
	ds_read_b64_tr_b16 v[134:135], v96 offset:0x3200
	ds_read_b64_tr_b16 v[136:137], v96 offset:0x3a00
	s_waitcnt lgkmcnt(0)
	v_mfma_f32_32x32x16_bf16 v[48:63], v[118:121], v[100:103], v[48:63]
	ds_read_b64_tr_b16 v[118:119], v96 offset:0x400
	ds_read_b64_tr_b16 v[120:121], v96 offset:0xc00
	v_mfma_f32_32x32x16_bf16 v[48:63], v[122:125], v[104:107], v[48:63]
	ds_read_b64_tr_b16 v[122:123], v96 offset:0x1400
	ds_read_b64_tr_b16 v[124:125], v96 offset:0x1c00
	v_mfma_f32_32x32x16_bf16 v[48:63], v[126:129], v[108:111], v[48:63]
	ds_read_b64_tr_b16 v[126:127], v96 offset:0x2400
	ds_read_b64_tr_b16 v[128:129], v96 offset:0x2c00
	v_mfma_f32_32x32x16_bf16 v[48:63], v[134:137], v[114:117], v[48:63]
	ds_read_b64_tr_b16 v[134:135], v96 offset:0x3400
	ds_read_b64_tr_b16 v[136:137], v96 offset:0x3c00
	s_waitcnt lgkmcnt(0)
	v_mfma_f32_32x32x16_bf16 v[16:31], v[118:121], v[100:103], v[16:31]
	ds_read_b64_tr_b16 v[118:119], v96 offset:0x600
	ds_read_b64_tr_b16 v[120:121], v96 offset:0xe00
	v_mfma_f32_32x32x16_bf16 v[16:31], v[122:125], v[104:107], v[16:31]
	ds_read_b64_tr_b16 v[122:123], v96 offset:0x1600
	ds_read_b64_tr_b16 v[124:125], v96 offset:0x1e00
	v_mfma_f32_32x32x16_bf16 v[16:31], v[126:129], v[108:111], v[16:31]
	ds_read_b64_tr_b16 v[126:127], v96 offset:0x2600
	ds_read_b64_tr_b16 v[128:129], v96 offset:0x2e00
	v_mfma_f32_32x32x16_bf16 v[16:31], v[134:137], v[114:117], v[16:31]
	ds_read_b64_tr_b16 v[134:135], v96 offset:0x3600
	ds_read_b64_tr_b16 v[136:137], v96 offset:0x3e00
	s_waitcnt lgkmcnt(0)
	v_mfma_f32_32x32x16_bf16 v[0:15], v[118:121], v[100:103], v[0:15]
	v_max_f32_e32 v96, v81, v81
	v_max_f32_e32 v99, v80, v80
	v_max_f32_e32 v96, v99, v96
	v_max3_f32 v96, v96, v82, v83
	v_max3_f32 v96, v96, v84, v85
	v_max3_f32 v96, v96, v86, v87
	v_max3_f32 v96, v96, v88, v89
	v_max3_f32 v96, v96, v90, v91
	v_max3_f32 v96, v96, v92, v93
	v_mfma_f32_32x32x16_bf16 v[0:15], v[122:125], v[104:107], v[0:15]
	v_max3_f32 v96, v96, v94, v95
	v_max3_f32 v96, v96, v64, v65
	v_max3_f32 v96, v96, v66, v67
	v_max3_f32 v96, v96, v68, v69
	v_max3_f32 v96, v96, v70, v71
	v_max3_f32 v96, v96, v72, v73
	v_max3_f32 v96, v96, v74, v75
	v_max3_f32 v96, v96, v76, v77
	v_mfma_f32_32x32x16_bf16 v[0:15], v[126:129], v[108:111], v[0:15]
	v_max3_f32 v96, v96, v78, v79
	v_mov_b32_e32 v99, v96
	s_nop 1
	v_permlane32_swap_b32_e32 v96, v99
	v_max_f32_e32 v99, v99, v99
	v_max_f32_e32 v96, v96, v96
	v_max_f32_e32 v96, v96, v99
	v_sub_f32_e32 v99, v96, v143
	v_cmp_ge_f32_e32 vcc, s70, v99
	v_max_f32_e32 v99, v143, v143
	v_max_f32_e32 v99, v99, v96
	v_mfma_f32_32x32x16_bf16 v[0:15], v[134:137], v[114:117], v[0:15]
	v_sub_f32_e32 v96, v143, v99
	v_mul_f32_e32 v96, 0x3e38aa3b, v96
	v_exp_f32_e32 v96, v96
	s_cmp_eq_u64 vcc, exec
	s_cselect_b64 s[4:5], -1, 0
	v_cndmask_b32_e64 v96, v96, 1.0, s[4:5]
	v_cmp_gt_f32_e32 vcc, 1.0, v96
	s_cbranch_vccz .LBB0_137
; #define SBAR() __builtin_amdgcn_sched_barrier(0)
; #define RESC(a) do { if (__any((a) < 1.f)) { if (hi == 0) al_l[r32] = (a); asm volatile("s_waitcnt lgkmcnt(0)" ::: "memory"); \
;     for (int d = 0; d < 4; ++d) for (int r = 0; r < 16; ++r) o[d][r] *= al_l[crow_(r, hi)]; } } while (0)
; #define RESC(a) do { if (__any((a) < 1.f)) { for (int d = 0; d < 4; ++d) for (int r = 0; r < 16; ++r) o[d][r] *= (a); } } while (0)
; #define RESC(a) do { if (__any((a) < 1.f)) { for (int d = 0; d < 4; ++d) for (int r = 0; r < 16; ++r) o[d][r] *= (a); } } while (0)
; __device__ __forceinline__ void finishSM(f32x16& p0, f32x16& p1, float alpha, float& l_reg, bf16x8& pa0, bf16x8& pa1, bf16x8& pa2, bf16x8& pa3) {
; #pragma unroll
;   for (int r = 0; r < 16; ++r) p1[r] = __builtin_amdgcn_exp2f(p1[r]);
;   float ps = 0;
; #pragma unroll
;   for (int r = 0; r < 16; ++r) ps += p0[r];
; #pragma unroll
;   for (int r = 0; r < 16; ++r) ps += p1[r];
;   { auto rr = __builtin_amdgcn_permlane32_swap(__float_as_uint(ps), __float_as_uint(ps), false, false);
;     ps = __uint_as_float(rr[0]) + __uint_as_float(rr[1]); }
;   l_reg = l_reg * alpha + ps;
;     ...
;   PK4(p0, 0, pa0); PK4(p0, 8, pa1); PK4(p1, 0, pa2); PK4(p1, 8, pa3);
;     ...
; }
; __device__ __forceinline__ void attn_diff_dma(const bf16_t* __restrict__ Qb, const bf16_t* __restrict__ Kh, const bf16_t* __restrict__ Vh, bf16_t* __restrict__ Ob,
;                                               int seq, char* lds, float lam, const float* __restrict__ gsub, const int tid) {
;     ...
;   RESC(alB);
;   finishSM(pB0, pB1, alB, l_reg, pa0, pa1, pa2, pa3); SBAR();
;   pv_d0_t(o, vb0 + vcur * SHM_VV, pa0, pa1, pa2, pa3);
	v_pk_mul_f32 v[46:47], v[46:47], v[96:97] op_sel_hi:[1,0]
	v_pk_mul_f32 v[44:45], v[44:45], v[96:97] op_sel_hi:[1,0]
	v_pk_mul_f32 v[42:43], v[42:43], v[96:97] op_sel_hi:[1,0]
	v_pk_mul_f32 v[40:41], v[40:41], v[96:97] op_sel_hi:[1,0]
	v_pk_mul_f32 v[38:39], v[38:39], v[96:97] op_sel_hi:[1,0]
	v_pk_mul_f32 v[36:37], v[36:37], v[96:97] op_sel_hi:[1,0]
	v_pk_mul_f32 v[34:35], v[34:35], v[96:97] op_sel_hi:[1,0]
	v_pk_mul_f32 v[32:33], v[32:33], v[96:97] op_sel_hi:[1,0]
	v_pk_mul_f32 v[62:63], v[62:63], v[96:97] op_sel_hi:[1,0]
	v_pk_mul_f32 v[60:61], v[60:61], v[96:97] op_sel_hi:[1,0]
	v_pk_mul_f32 v[58:59], v[58:59], v[96:97] op_sel_hi:[1,0]
	v_pk_mul_f32 v[56:57], v[56:57], v[96:97] op_sel_hi:[1,0]
	v_pk_mul_f32 v[54:55], v[54:55], v[96:97] op_sel_hi:[1,0]
	v_pk_mul_f32 v[52:53], v[52:53], v[96:97] op_sel_hi:[1,0]
	v_pk_mul_f32 v[50:51], v[50:51], v[96:97] op_sel_hi:[1,0]
	v_pk_mul_f32 v[48:49], v[48:49], v[96:97] op_sel_hi:[1,0]
	v_pk_mul_f32 v[30:31], v[30:31], v[96:97] op_sel_hi:[1,0]
	v_pk_mul_f32 v[28:29], v[28:29], v[96:97] op_sel_hi:[1,0]
	v_pk_mul_f32 v[26:27], v[26:27], v[96:97] op_sel_hi:[1,0]
	v_pk_mul_f32 v[24:25], v[24:25], v[96:97] op_sel_hi:[1,0]
	v_pk_mul_f32 v[22:23], v[22:23], v[96:97] op_sel_hi:[1,0]
	v_pk_mul_f32 v[20:21], v[20:21], v[96:97] op_sel_hi:[1,0]
	v_pk_mul_f32 v[18:19], v[18:19], v[96:97] op_sel_hi:[1,0]
	v_pk_mul_f32 v[16:17], v[16:17], v[96:97] op_sel_hi:[1,0]
	v_pk_mul_f32 v[14:15], v[14:15], v[96:97] op_sel_hi:[1,0]
	v_pk_mul_f32 v[12:13], v[12:13], v[96:97] op_sel_hi:[1,0]
	v_pk_mul_f32 v[10:11], v[10:11], v[96:97] op_sel_hi:[1,0]
	v_pk_mul_f32 v[8:9], v[8:9], v[96:97] op_sel_hi:[1,0]
	v_pk_mul_f32 v[6:7], v[6:7], v[96:97] op_sel_hi:[1,0]
	v_pk_mul_f32 v[4:5], v[4:5], v[96:97] op_sel_hi:[1,0]
	v_pk_mul_f32 v[2:3], v[2:3], v[96:97] op_sel_hi:[1,0]
	v_pk_mul_f32 v[0:1], v[0:1], v[96:97] op_sel_hi:[1,0]
.LBB0_137:
	v_add_f32_e32 v97, v97, v98
	v_cndmask_b32_e64 v98, v99, v143, s[4:5]
	v_mul_f32_e32 v98, 0xbe38aa3b, v98
	v_fmamk_f32 v80, v80, 0x3e38aa3b, v98
	v_fmamk_f32 v81, v81, 0x3e38aa3b, v98
	v_fmamk_f32 v82, v82, 0x3e38aa3b, v98
	v_fmamk_f32 v83, v83, 0x3e38aa3b, v98
	v_fmamk_f32 v84, v84, 0x3e38aa3b, v98
	v_fmamk_f32 v85, v85, 0x3e38aa3b, v98
	v_fmamk_f32 v86, v86, 0x3e38aa3b, v98
	v_fmamk_f32 v87, v87, 0x3e38aa3b, v98
	v_fmamk_f32 v88, v88, 0x3e38aa3b, v98
	v_fmamk_f32 v89, v89, 0x3e38aa3b, v98
	v_fmamk_f32 v90, v90, 0x3e38aa3b, v98
	v_fmamk_f32 v91, v91, 0x3e38aa3b, v98
	v_fmamk_f32 v92, v92, 0x3e38aa3b, v98
	v_fmamk_f32 v93, v93, 0x3e38aa3b, v98
	v_fmamk_f32 v94, v94, 0x3e38aa3b, v98
	v_fmamk_f32 v95, v95, 0x3e38aa3b, v98
	v_fmamk_f32 v64, v64, 0x3e38aa3b, v98
	v_fmamk_f32 v65, v65, 0x3e38aa3b, v98
	v_fmamk_f32 v66, v66, 0x3e38aa3b, v98
	v_fmamk_f32 v67, v67, 0x3e38aa3b, v98
	v_fmamk_f32 v68, v68, 0x3e38aa3b, v98
	v_fmamk_f32 v69, v69, 0x3e38aa3b, v98
	v_fmamk_f32 v70, v70, 0x3e38aa3b, v98
	v_fmamk_f32 v71, v71, 0x3e38aa3b, v98
	v_fmamk_f32 v72, v72, 0x3e38aa3b, v98
	v_fmamk_f32 v73, v73, 0x3e38aa3b, v98
	v_fmamk_f32 v74, v74, 0x3e38aa3b, v98
	v_fmamk_f32 v75, v75, 0x3e38aa3b, v98
	v_fmamk_f32 v76, v76, 0x3e38aa3b, v98
	v_fmamk_f32 v77, v77, 0x3e38aa3b, v98
	v_fmamk_f32 v78, v78, 0x3e38aa3b, v98
	v_fmac_f32_e32 v98, 0x3e38aa3b, v79
	v_exp_f32_e32 v79, v80
	v_exp_f32_e32 v80, v81
	v_exp_f32_e32 v81, v82
	v_exp_f32_e32 v82, v83
	v_exp_f32_e32 v83, v84
	v_exp_f32_e32 v84, v85
	v_exp_f32_e32 v85, v86
	v_exp_f32_e32 v86, v87
	v_exp_f32_e32 v87, v88
	v_exp_f32_e32 v88, v89
	v_exp_f32_e32 v89, v90
	v_exp_f32_e32 v90, v91
	v_exp_f32_e32 v91, v92
	v_exp_f32_e32 v92, v93
	v_exp_f32_e32 v93, v94
	v_exp_f32_e32 v94, v95
	v_exp_f32_e32 v95, v64
	v_add_f32_e32 v64, 0, v79
	v_add_f32_e32 v64, v80, v64
	v_add_f32_e32 v64, v81, v64
	v_add_f32_e32 v64, v82, v64
	v_add_f32_e32 v64, v83, v64
	v_add_f32_e32 v64, v84, v64
	v_add_f32_e32 v64, v85, v64
	v_add_f32_e32 v64, v86, v64
	v_add_f32_e32 v64, v87, v64
	v_add_f32_e32 v64, v88, v64
	v_add_f32_e32 v64, v89, v64
	v_add_f32_e32 v64, v90, v64
	v_add_f32_e32 v64, v91, v64
	v_exp_f32_e32 v99, v65
	v_add_f32_e32 v64, v92, v64
	v_exp_f32_e32 v100, v66
	v_add_f32_e32 v64, v93, v64
	v_exp_f32_e32 v101, v67
	v_add_f32_e32 v64, v94, v64
	v_exp_f32_e32 v102, v68
	v_add_f32_e32 v64, v95, v64
	v_exp_f32_e32 v103, v69
	v_add_f32_e32 v64, v99, v64
	v_exp_f32_e32 v104, v70
	v_add_f32_e32 v64, v100, v64
	v_exp_f32_e32 v105, v71
	v_add_f32_e32 v64, v101, v64
	v_exp_f32_e32 v106, v72
	v_add_f32_e32 v64, v102, v64
	v_exp_f32_e32 v107, v73
	v_add_f32_e32 v64, v103, v64
	v_exp_f32_e32 v108, v74
	v_add_f32_e32 v64, v104, v64
	v_exp_f32_e32 v109, v75
	v_add_f32_e32 v64, v105, v64
	v_exp_f32_e32 v110, v76
	v_add_f32_e32 v64, v106, v64
	v_exp_f32_e32 v111, v77
	v_add_f32_e32 v64, v107, v64
	v_fmac_f32_e32 v97, v131, v112
	v_exp_f32_e32 v112, v78
	v_add_f32_e32 v64, v108, v64
	v_exp_f32_e32 v98, v98
	v_add_f32_e32 v64, v109, v64
	v_add_f32_e32 v64, v110, v64
	v_add_f32_e32 v64, v111, v64
	v_add_f32_e32 v64, v112, v64
	v_add_f32_e32 v64, v98, v64
	v_mov_b32_e32 v65, v64
	s_nop 1
	v_permlane32_swap_b32_e32 v64, v65
	v_add_f32_e32 v113, v64, v65
	v_cvt_pk_bf16_f32 v64, v79, v80
	v_cvt_pk_bf16_f32 v65, v81, v82
	v_cvt_pk_bf16_f32 v66, v83, v84
	v_cvt_pk_bf16_f32 v67, v85, v86
	v_cvt_pk_bf16_f32 v68, v87, v88
	v_cvt_pk_bf16_f32 v69, v89, v90
	v_cvt_pk_bf16_f32 v70, v91, v92
	v_cvt_pk_bf16_f32 v71, v93, v94
	s_nop 0
	v_cvt_pk_bf16_f32 v72, v95, v99
	v_cvt_pk_bf16_f32 v73, v100, v101
	v_cvt_pk_bf16_f32 v74, v102, v103
	v_cvt_pk_bf16_f32 v75, v104, v105
	v_cvt_pk_bf16_f32 v76, v106, v107
	v_cvt_pk_bf16_f32 v77, v108, v109
	v_cvt_pk_bf16_f32 v78, v110, v111
	v_cvt_pk_bf16_f32 v79, v112, v98
	v_fmac_f32_e32 v113, v97, v96
	ds_read_b64_tr_b16 v[80:81], v132 offset:0
	ds_read_b64_tr_b16 v[82:83], v132 offset:0x800
	ds_read_b64_tr_b16 v[84:85], v132 offset:0x1000
	ds_read_b64_tr_b16 v[86:87], v132 offset:0x1800
	ds_read_b64_tr_b16 v[88:89], v132 offset:0x2000
	ds_read_b64_tr_b16 v[90:91], v132 offset:0x2800
	ds_read_b64_tr_b16 v[92:93], v132 offset:0x3000
	ds_read_b64_tr_b16 v[94:95], v132 offset:0x3800
	s_waitcnt lgkmcnt(0)
; __device__ __forceinline__ int crow_(int r, int hi) { return (r & 3) + 8 * (r >> 2) + 4 * hi; }
; __device__ __forceinline__ void attn_diff_dma(const bf16_t* __restrict__ Qb, const bf16_t* __restrict__ Kh, const bf16_t* __restrict__ Vh, bf16_t* __restrict__ Ob,
;                                               int seq, char* lds, float lam, const float* __restrict__ gsub, const int tid) {
;     ...
;   pv_d0_t(o, vb0 + vcur * SHM_VV, pa0, pa1, pa2, pa3);
;   int tide = tid; asm volatile("" : "+v"(tide));
;   const int wide = tide >> 6, r32e = tide & 31, hie = (tide >> 5) & 1, wrowe = wide & 3, compe = wide >> 2;
;   const float rl = __builtin_amdgcn_rcpf(l_reg);
;   __syncthreads();
;   float* X = (float*)lds + wrowe * QBLK + r32e;
;   if (compe == 1) {
; #pragma unroll
;     for (int d0 = 0; d0 < 4; ++d0)
; #pragma unroll
;       for (int r = 0; r < 16; ++r) X[(d0 * 32 + crow_(r, hie)) * 128] = o[d0][r] * rl;
	s_nop 0
	v_mfma_f32_32x32x16_bf16 v[32:47], v[80:83], v[64:67], v[32:47]
	ds_read_b64_tr_b16 v[80:81], v132 offset:0x200
	ds_read_b64_tr_b16 v[82:83], v132 offset:0xa00
	v_mfma_f32_32x32x16_bf16 v[32:47], v[84:87], v[68:71], v[32:47]
	ds_read_b64_tr_b16 v[84:85], v132 offset:0x1200
	ds_read_b64_tr_b16 v[86:87], v132 offset:0x1a00
	v_mfma_f32_32x32x16_bf16 v[32:47], v[88:91], v[72:75], v[32:47]
	ds_read_b64_tr_b16 v[88:89], v132 offset:0x2200
	ds_read_b64_tr_b16 v[90:91], v132 offset:0x2a00
	v_mfma_f32_32x32x16_bf16 v[32:47], v[92:95], v[76:79], v[32:47]
	ds_read_b64_tr_b16 v[92:93], v132 offset:0x3200
	ds_read_b64_tr_b16 v[94:95], v132 offset:0x3a00
	s_waitcnt lgkmcnt(0)
	v_mfma_f32_32x32x16_bf16 v[48:63], v[80:83], v[64:67], v[48:63]
	ds_read_b64_tr_b16 v[80:81], v132 offset:0x400
	ds_read_b64_tr_b16 v[82:83], v132 offset:0xc00
	v_mfma_f32_32x32x16_bf16 v[48:63], v[84:87], v[68:71], v[48:63]
	ds_read_b64_tr_b16 v[84:85], v132 offset:0x1400
	ds_read_b64_tr_b16 v[86:87], v132 offset:0x1c00
	v_mfma_f32_32x32x16_bf16 v[48:63], v[88:91], v[72:75], v[48:63]
	ds_read_b64_tr_b16 v[88:89], v132 offset:0x2400
	ds_read_b64_tr_b16 v[90:91], v132 offset:0x2c00
	v_mfma_f32_32x32x16_bf16 v[48:63], v[92:95], v[76:79], v[48:63]
	ds_read_b64_tr_b16 v[92:93], v132 offset:0x3400
	ds_read_b64_tr_b16 v[94:95], v132 offset:0x3c00
	s_waitcnt lgkmcnt(0)
	v_mfma_f32_32x32x16_bf16 v[16:31], v[80:83], v[64:67], v[16:31]
	ds_read_b64_tr_b16 v[80:81], v132 offset:0x600
	ds_read_b64_tr_b16 v[82:83], v132 offset:0xe00
	v_mfma_f32_32x32x16_bf16 v[16:31], v[84:87], v[68:71], v[16:31]
	ds_read_b64_tr_b16 v[84:85], v132 offset:0x1600
	ds_read_b64_tr_b16 v[86:87], v132 offset:0x1e00
	v_mfma_f32_32x32x16_bf16 v[16:31], v[88:91], v[72:75], v[16:31]
	ds_read_b64_tr_b16 v[88:89], v132 offset:0x2600
	ds_read_b64_tr_b16 v[90:91], v132 offset:0x2e00
	v_mfma_f32_32x32x16_bf16 v[16:31], v[92:95], v[76:79], v[16:31]
	ds_read_b64_tr_b16 v[92:93], v132 offset:0x3600
	ds_read_b64_tr_b16 v[94:95], v132 offset:0x3e00
	s_waitcnt lgkmcnt(0)
	v_mfma_f32_32x32x16_bf16 v[0:15], v[80:83], v[64:67], v[0:15]
	v_rcp_f32_e32 v156, v113
	v_lshrrev_b32_e32 v66, 1, v130
	v_and_b32_e32 v64, 31, v130
	v_and_b32_e32 v66, 0x60, v66
	v_lshlrev_b32_e32 v67, 2, v66
	v_bfe_u32 v65, v130, 5, 1
	v_mfma_f32_32x32x16_bf16 v[0:15], v[84:87], v[68:71], v[0:15]
	v_lshlrev_b32_e32 v68, 2, v64
	v_add3_u32 v67, 0, v67, v68
	v_and_b32_e32 v68, 0xffffff00, v130
	s_movk_i32 s4, 0x100
	v_cmp_eq_u32_e32 vcc, s4, v68
	v_lshl_add_u32 v71, v65, 11, v67
	s_waitcnt vmcnt(0)
	v_mfma_f32_32x32x16_bf16 v[0:15], v[88:91], v[72:75], v[0:15]
	s_barrier
	v_mfma_f32_32x32x16_bf16 v[0:15], v[92:95], v[76:79], v[0:15]
	s_and_saveexec_b64 s[4:5], vcc
	s_cbranch_execz .LBB0_139
	v_mul_f32_e32 v67, v156, v32
	v_mul_f32_e32 v68, v156, v33
	ds_write2st64_b32 v71, v67, v68 offset1:2
	v_mul_f32_e32 v67, v156, v34
	v_mul_f32_e32 v68, v156, v35
	ds_write2st64_b32 v71, v67, v68 offset0:4 offset1:6
	v_mul_f32_e32 v67, v156, v36
	v_mul_f32_e32 v68, v156, v37
	ds_write2st64_b32 v71, v67, v68 offset0:16 offset1:18
	v_mul_f32_e32 v67, v156, v38
	v_mul_f32_e32 v68, v156, v39
	ds_write2st64_b32 v71, v67, v68 offset0:20 offset1:22
	v_mul_f32_e32 v67, v156, v40
	v_mul_f32_e32 v68, v156, v41
	ds_write2st64_b32 v71, v67, v68 offset0:32 offset1:34
	v_mul_f32_e32 v67, v156, v42
	v_mul_f32_e32 v68, v156, v43
	ds_write2st64_b32 v71, v67, v68 offset0:36 offset1:38
	v_mul_f32_e32 v67, v156, v44
	v_mul_f32_e32 v68, v156, v45
	ds_write2st64_b32 v71, v67, v68 offset0:48 offset1:50
	v_mul_f32_e32 v67, v156, v46
	v_mul_f32_e32 v68, v156, v47
	ds_write2st64_b32 v71, v67, v68 offset0:52 offset1:54
	v_mul_f32_e32 v67, v156, v48
	v_mul_f32_e32 v68, v156, v49
	ds_write2st64_b32 v71, v67, v68 offset0:64 offset1:66
	v_mul_f32_e32 v67, v156, v50
	v_mul_f32_e32 v68, v156, v51
	ds_write2st64_b32 v71, v67, v68 offset0:68 offset1:70
	v_mul_f32_e32 v67, v156, v52
	v_mul_f32_e32 v68, v156, v53
	ds_write2st64_b32 v71, v67, v68 offset0:80 offset1:82
	v_mul_f32_e32 v67, v156, v54
	v_mul_f32_e32 v68, v156, v55
	ds_write2st64_b32 v71, v67, v68 offset0:84 offset1:86
	v_mul_f32_e32 v67, v156, v56
	v_mul_f32_e32 v68, v156, v57
	ds_write2st64_b32 v71, v67, v68 offset0:96 offset1:98
	v_mul_f32_e32 v67, v156, v58
	v_mul_f32_e32 v68, v156, v59
	ds_write2st64_b32 v71, v67, v68 offset0:100 offset1:102
	v_mul_f32_e32 v67, v156, v60
	v_mul_f32_e32 v68, v156, v61
	ds_write2st64_b32 v71, v67, v68 offset0:112 offset1:114
	v_mul_f32_e32 v67, v156, v62
	v_mul_f32_e32 v68, v156, v63
	ds_write2st64_b32 v71, v67, v68 offset0:116 offset1:118
	v_mul_f32_e32 v67, v156, v16
	v_mul_f32_e32 v68, v156, v17
	ds_write2st64_b32 v71, v67, v68 offset0:128 offset1:130
	v_mul_f32_e32 v67, v156, v18
	v_mul_f32_e32 v68, v156, v19
	ds_write2st64_b32 v71, v67, v68 offset0:132 offset1:134
	v_mul_f32_e32 v67, v156, v20
	v_mul_f32_e32 v68, v156, v21
	ds_write2st64_b32 v71, v67, v68 offset0:144 offset1:146
	v_mul_f32_e32 v67, v156, v22
	v_mul_f32_e32 v68, v156, v23
	ds_write2st64_b32 v71, v67, v68 offset0:148 offset1:150
	v_mul_f32_e32 v67, v156, v24
	v_mul_f32_e32 v68, v156, v25
	ds_write2st64_b32 v71, v67, v68 offset0:160 offset1:162
	v_mul_f32_e32 v67, v156, v26
	v_mul_f32_e32 v68, v156, v27
	ds_write2st64_b32 v71, v67, v68 offset0:164 offset1:166
	v_mul_f32_e32 v67, v156, v28
	v_mul_f32_e32 v68, v156, v29
	ds_write2st64_b32 v71, v67, v68 offset0:176 offset1:178
	v_mul_f32_e32 v67, v156, v30
	v_mul_f32_e32 v68, v156, v31
	ds_write2st64_b32 v71, v67, v68 offset0:180 offset1:182
	v_mul_f32_e32 v67, v156, v0
	v_mul_f32_e32 v68, v156, v1
	ds_write2st64_b32 v71, v67, v68 offset0:192 offset1:194
	v_mul_f32_e32 v67, v156, v2
	v_mul_f32_e32 v68, v156, v3
	ds_write2st64_b32 v71, v67, v68 offset0:196 offset1:198
	v_mul_f32_e32 v67, v156, v4
	v_mul_f32_e32 v68, v156, v5
	ds_write2st64_b32 v71, v67, v68 offset0:208 offset1:210
	v_mul_f32_e32 v67, v156, v6
	v_mul_f32_e32 v68, v156, v7
	ds_write2st64_b32 v71, v67, v68 offset0:212 offset1:214
	v_mul_f32_e32 v67, v156, v8
	v_mul_f32_e32 v68, v156, v9
	ds_write2st64_b32 v71, v67, v68 offset0:224 offset1:226
	v_mul_f32_e32 v67, v156, v10
	v_mul_f32_e32 v68, v156, v11
	ds_write2st64_b32 v71, v67, v68 offset0:228 offset1:230
	v_mul_f32_e32 v67, v156, v12
	v_mul_f32_e32 v68, v156, v13
	ds_write2st64_b32 v71, v67, v68 offset0:240 offset1:242
	v_mul_f32_e32 v67, v156, v14
	v_mul_f32_e32 v68, v156, v15
	ds_write2st64_b32 v71, v67, v68 offset0:244 offset1:246

; __global__ __launch_bounds__(512, 2) void mega(Params p) {
	.amdhsa_kernel _Z4mega6Params
		.amdhsa_group_segment_fixed_size 0
		.amdhsa_private_segment_fixed_size 0
		.amdhsa_kernarg_size 432
		.amdhsa_user_sgpr_count 2
		.amdhsa_user_sgpr_dispatch_ptr 0
		.amdhsa_user_sgpr_queue_ptr 0
		.amdhsa_user_sgpr_kernarg_segment_ptr 1
		.amdhsa_user_sgpr_dispatch_id 0
		.amdhsa_user_sgpr_kernarg_preload_length 0
		.amdhsa_user_sgpr_kernarg_preload_offset 0
		.amdhsa_user_sgpr_private_segment_size 0
		.amdhsa_uses_dynamic_stack 0
		.amdhsa_enable_private_segment 0
		.amdhsa_system_sgpr_workgroup_id_x 1
		.amdhsa_system_sgpr_workgroup_id_y 0
		.amdhsa_system_sgpr_workgroup_id_z 0
		.amdhsa_system_sgpr_workgroup_info 0
		.amdhsa_system_vgpr_workitem_id 2
		.amdhsa_next_free_vgpr 251
		.amdhsa_next_free_sgpr 100
		.amdhsa_accum_offset 252
		.amdhsa_reserve_vcc 1
		.amdhsa_float_round_mode_32 0
		.amdhsa_float_round_mode_16_64 0
		.amdhsa_float_denorm_mode_32 3
		.amdhsa_float_denorm_mode_16_64 3
		.amdhsa_dx10_clamp 1
		.amdhsa_ieee_mode 1
		.amdhsa_fp16_overflow 0
		.amdhsa_tg_split 0
		.amdhsa_exception_fp_ieee_invalid_op 0
		.amdhsa_exception_fp_denorm_src 0
		.amdhsa_exception_fp_ieee_div_zero 0
		.amdhsa_exception_fp_ieee_overflow 0
		.amdhsa_exception_fp_ieee_underflow 0
		.amdhsa_exception_fp_ieee_inexact 0
		.amdhsa_exception_int_div_zero 0
	.end_amdhsa_kernel

; __global__ __launch_bounds__(512, 2) void mega(Params p) {
amdhsa.kernels:
  - .agpr_count:     0
    .args:
      - .offset:         0
        .size:           176
        .value_kind:     by_value
      - .offset:         176
        .size:           4
        .value_kind:     hidden_block_count_x
      - .offset:         180
        .size:           4
        .value_kind:     hidden_block_count_y
      - .offset:         184
        .size:           4
        .value_kind:     hidden_block_count_z
      - .offset:         188
        .size:           2
        .value_kind:     hidden_group_size_x
      - .offset:         190
        .size:           2
        .value_kind:     hidden_group_size_y
      - .offset:         192
        .size:           2
        .value_kind:     hidden_group_size_z
      - .offset:         194
        .size:           2
        .value_kind:     hidden_remainder_x
      - .offset:         196
        .size:           2
        .value_kind:     hidden_remainder_y
      - .offset:         198
        .size:           2
        .value_kind:     hidden_remainder_z
      - .offset:         216
        .size:           8
        .value_kind:     hidden_global_offset_x
      - .offset:         224
        .size:           8
        .value_kind:     hidden_global_offset_y
      - .offset:         232
        .size:           8
        .value_kind:     hidden_global_offset_z
      - .offset:         240
        .size:           2
        .value_kind:     hidden_grid_dims
      - .offset:         264
        .size:           8
        .value_kind:     hidden_multigrid_sync_arg
      - .offset:         296
        .size:           4
        .value_kind:     hidden_dynamic_lds_size
    .group_segment_fixed_size: 0
    .kernarg_segment_align: 8
    .kernarg_segment_size: 432
    .language:       OpenCL C
    .language_version:
      - 2
      - 0
    .max_flat_workgroup_size: 512
    .name:           _Z4mega6Params
    .private_segment_fixed_size: 0
    .sgpr_count:     106
    .sgpr_spill_count: 182
    .symbol:         _Z4mega6Params.kd
    .uniform_work_group_size: 1
    .uses_dynamic_stack: false
    .vgpr_count:     251
    .vgpr_spill_count: 0
    .wavefront_size: 64
